# RK_G2 W2/A2 epilogues: per-column rk_w0/rk_a0 values preloaded once per tile instead of a load+vmcnt(0) round trip per element
# speedup vs baseline: 1.0539x; 1.0033x over previous
; #define PW(T, off) ((T*)(lndp(p.ws) + (off)))
; DEVI float bf2f(bf16 h) { return __uint_as_float(((unsigned)h) << 16); }
; DEVI float sigmf(float x) { return __builtin_amdgcn_rcpf(1.f + __expf(-x)); }
; DEVI float softplusf(float x) { return x > 20.f ? x : __logf(1.f + __expf(x)); }
; DEVI float tanhfast(float x) { return 1.f - 2.f / (__expf(2.f * x) + 1.f); }
; DEVI int accrow(int r, int lane) { return (r & 3) + 8 * (r >> 2) + 4 * (lane >> 5); }
; template <int EPI>
; DEVI void gemm_epi(const Params& p, const GJob& jb, f32x16 (&acc)[2][2], int rbase, int cbase, int lane) {
;     ...
;   for (int i = 0; i < 2; ++i) {
; #pragma unroll
;     for (int r = 0; r < 16; ++r) {
;       const int row = rbase + i * 32 + accrow(r, lane);
;       if (row < M) {
; #pragma unroll
;         for (int j = 0; j < 2; ++j) {
;           const int col = cbase + j * 32 + (lane & 31);
;           const float v = acc[i][j][r];
;           if (EPI == EPI_SSD_IN) {
;             if (col < 2048) ((bf16*)(ar + S_ZB))[(size_t)row * 2048 + col] = f2bf(v);
;             else if (col < 6144) ((bf16*)(ar + S_XBC))[(size_t)row * 4096 + col - 2048] = f2bf(v);
;             else if (col < 6176) ((float*)(ar + S_DTRAW))[(size_t)row * 32 + col - 6144] = v;
;           } else if (EPI == EPI_RESID) {
;             PW(bf16, W_Z)[(size_t)row * 1024 + col] = f2bf(ALPHA * bf2f(PW(bf16, W_Xb)[(size_t)row * 1024 + col]) + v);
;           } else if (EPI == EPI_GU) {
;             ((bf16*)(ar + F_GU))[(size_t)row * 5632 + col] = f2bf(v);
;           } else if (EPI == EPI_BF16) {
;             ((bf16*)jb.of)[(size_t)row * 1024 + col] = f2bf(v);
;           } else if (EPI == EPI_F32) {
;             jb.of[(size_t)row * 1024 + col] = v;
;           } else if (EPI == EPI_RK_W1) {
;             if (col < 64) ((bf16*)(ar + R_HW))[(size_t)row * 64 + col] = f2bf(tanhfast(v));
;           } else if (EPI == EPI_RK_A1) {
;             if (col < 64) ((bf16*)(ar + R_HA))[(size_t)row * 64 + col] = f2bf(v);
;           } else if (EPI == EPI_RK_G1) {
;             if (col < 192) ((bf16*)(ar + R_HG))[(size_t)row * 192 + col] = f2bf(col < 160 ? sigmf(v) : 0.f);
;           } else if (EPI == EPI_RK_W2) {
;             const float z = i_rk_w0[col] + v;
;             const float wl = -softplusf(-z) - 0.5f;
;             ((float*)(ar + R_W))[(size_t)row * 1024 + col] = __expf(-__expf(wl));
.LBB0_510:
	s_andn2_b64 vcc, exec, s[4:5]
	s_cbranch_vccnz .LBB0_356
	v_lshrrev_b32_e32 v70, 3, v70
	v_or_b32_e32 v64, v69, v96
	s_mov_b64 s[2:3], -1
	s_cmp_lg_u32 s25, 9
	v_and_b32_e32 v69, 4, v70
	v_ashrrev_i32_e32 v65, 31, v64
	s_cbranch_scc0 .LBB0_577
	s_mov_b32 s2, 23
	s_ashr_i32 s3, s2, 31
	s_lshl_b64 s[2:3], s[2:3], 3
	s_add_u32 s2, s0, s2
	s_addc_u32 s3, s1, s3
	s_load_dwordx2 s[8:9], s[2:3], 0x0
	s_mov_b32 s2, 26
	s_waitcnt lgkmcnt(0)
	s_ashr_i32 s3, s2, 31
	s_lshl_b64 s[2:3], s[2:3], 3
	s_add_u32 s2, s0, s2
	s_addc_u32 s3, s1, s3
	s_load_dwordx2 s[2:3], s[2:3], 0x0
	s_mov_b64 s[4:5], s[74:75]
	v_or_b32_e32 v66, v68, v69
	s_waitcnt lgkmcnt(0)
	s_add_u32 s6, s4, 0x11d7c000
	s_addc_u32 s7, s5, 0
	v_cmp_gt_i32_e32 vcc, s90, v66
	v_lshlrev_b64 v[172:173], 2, v[64:65]
	v_lshl_add_u64 v[172:173], v[172:173], 0, s[8:9]
	global_load_dword v170, v[172:173], off
	global_load_dword v171, v[172:173], off offset:128
	s_waitcnt vmcnt(0)
	s_and_saveexec_b64 s[2:3], vcc
	s_cbranch_execz .LBB0_514
	s_waitcnt vmcnt(4)
	v_lshlrev_b64 v[72:73], 2, v[64:65]
	v_lshl_add_u64 v[74:75], s[8:9], 0, v[72:73]
	v_mov_b32_e32 v67, v170
	s_mov_b32 s5, 0x3f317217
	s_mov_b32 s18, 0x7f800000
	s_mov_b32 s4, 0xc1a00000
	v_add_f32_e32 v67, v32, v67
	v_mul_f32_e32 v71, 0xbfb8aa3b, v67
	v_exp_f32_e32 v71, v71
	s_nop 0
	v_add_f32_e32 v71, 1.0, v71
	v_cmp_gt_f32_e32 vcc, s69, v71
	s_nop 1
	v_cndmask_b32_e64 v76, 0, 32, vcc
	v_ldexp_f32 v71, v71, v76
	v_log_f32_e32 v71, v71
	v_cndmask_b32_e32 v76, 0, v216, vcc
	v_mul_f32_e32 v77, 0x3f317217, v71
	v_fma_f32 v77, v71, s5, -v77
	v_fmac_f32_e32 v77, 0x3377d1cf, v71
	v_fmac_f32_e32 v77, 0x3f317217, v71
	v_cmp_lt_f32_e64 vcc, |v71|, s18
	s_nop 1
	v_cndmask_b32_e32 v71, v71, v77, vcc
	v_sub_f32_e32 v71, v71, v76
	v_cmp_gt_f32_e32 vcc, s4, v67
	s_nop 1
	v_cndmask_b32_e64 v67, v71, -v67, vcc
	v_sub_f32_e32 v67, -0.5, v67
	v_mul_f32_e32 v67, 0x3fb8aa3b, v67
	v_exp_f32_e32 v71, v67
	v_ashrrev_i32_e32 v67, 31, v66
	v_lshlrev_b64 v[66:67], 12, v[66:67]
	v_lshl_add_u64 v[66:67], s[6:7], 0, v[66:67]
	v_mul_f32_e32 v71, 0xbfb8aa3b, v71
	v_exp_f32_e32 v71, v71
	v_lshl_add_u64 v[66:67], v[66:67], 0, v[72:73]
	global_store_dword v[66:67], v71, off
	v_mov_b32_e32 v71, v171
	v_add_f32_e32 v71, v48, v71
	v_mul_f32_e32 v72, 0xbfb8aa3b, v71
	v_exp_f32_e32 v72, v72
	s_nop 0
	v_add_f32_e32 v72, 1.0, v72
	v_cmp_gt_f32_e32 vcc, s69, v72
	s_nop 1
	v_cndmask_b32_e64 v73, 0, 32, vcc
	v_ldexp_f32 v72, v72, v73
	v_log_f32_e32 v72, v72
	v_cndmask_b32_e32 v73, 0, v216, vcc
	v_mul_f32_e32 v74, 0x3f317217, v72
	v_fma_f32 v74, v72, s5, -v74
	v_fmac_f32_e32 v74, 0x3377d1cf, v72
	v_fmac_f32_e32 v74, 0x3f317217, v72
	v_cmp_lt_f32_e64 vcc, |v72|, s18
	s_nop 1
	v_cndmask_b32_e32 v72, v72, v74, vcc
	v_sub_f32_e32 v72, v72, v73
	v_cmp_gt_f32_e32 vcc, s4, v71
	s_nop 1
	v_cndmask_b32_e64 v71, v72, -v71, vcc
	v_sub_f32_e32 v71, -0.5, v71
	v_mul_f32_e32 v71, 0x3fb8aa3b, v71
	v_exp_f32_e32 v71, v71
	s_nop 0
	v_mul_f32_e32 v71, 0xbfb8aa3b, v71
	v_exp_f32_e32 v71, v71
	global_store_dword v[66:67], v71, off offset:128
.LBB0_514:
	s_or_b64 exec, exec, s[2:3]
	v_or_b32_e32 v71, 1, v69
	v_or_b32_e32 v66, v71, v68
	v_cmp_gt_i32_e32 vcc, s90, v66
	s_and_saveexec_b64 s[2:3], vcc
	s_cbranch_execz .LBB0_516
	s_waitcnt vmcnt(4)
	v_lshlrev_b64 v[72:73], 2, v[64:65]
	v_lshl_add_u64 v[74:75], s[8:9], 0, v[72:73]
	v_mov_b32_e32 v67, v170
	s_mov_b32 s5, 0x3f317217
	s_mov_b32 s18, 0x7f800000
	s_mov_b32 s4, 0xc1a00000
	v_add_f32_e32 v67, v33, v67
	v_mul_f32_e32 v76, 0xbfb8aa3b, v67
	v_exp_f32_e32 v76, v76
	s_nop 0
	v_add_f32_e32 v76, 1.0, v76
	v_cmp_gt_f32_e32 vcc, s69, v76
	s_nop 1
	v_cndmask_b32_e64 v77, 0, 32, vcc
	v_ldexp_f32 v76, v76, v77
	v_log_f32_e32 v76, v76
	v_cndmask_b32_e32 v77, 0, v216, vcc
	v_mul_f32_e32 v78, 0x3f317217, v76
	v_fma_f32 v78, v76, s5, -v78
	v_fmac_f32_e32 v78, 0x3377d1cf, v76
	v_fmac_f32_e32 v78, 0x3f317217, v76
	v_cmp_lt_f32_e64 vcc, |v76|, s18
	s_nop 1
	v_cndmask_b32_e32 v76, v76, v78, vcc
	v_sub_f32_e32 v76, v76, v77
	v_cmp_gt_f32_e32 vcc, s4, v67
	s_nop 1
	v_cndmask_b32_e64 v67, v76, -v67, vcc
	v_sub_f32_e32 v67, -0.5, v67
	v_mul_f32_e32 v67, 0x3fb8aa3b, v67
	v_exp_f32_e32 v76, v67
	v_ashrrev_i32_e32 v67, 31, v66
	v_lshlrev_b64 v[66:67], 12, v[66:67]
	v_lshl_add_u64 v[66:67], s[6:7], 0, v[66:67]
	v_mul_f32_e32 v76, 0xbfb8aa3b, v76
	v_exp_f32_e32 v76, v76
	v_lshl_add_u64 v[66:67], v[66:67], 0, v[72:73]
	global_store_dword v[66:67], v76, off
	v_mov_b32_e32 v72, v171
	v_add_f32_e32 v72, v49, v72
	v_mul_f32_e32 v73, 0xbfb8aa3b, v72
	v_exp_f32_e32 v73, v73
	s_nop 0
	v_add_f32_e32 v73, 1.0, v73
	v_cmp_gt_f32_e32 vcc, s69, v73
	s_nop 1
	v_cndmask_b32_e64 v74, 0, 32, vcc
	v_ldexp_f32 v73, v73, v74
	v_log_f32_e32 v73, v73
	v_cndmask_b32_e32 v74, 0, v216, vcc
	v_mul_f32_e32 v75, 0x3f317217, v73
	v_fma_f32 v75, v73, s5, -v75
	v_fmac_f32_e32 v75, 0x3377d1cf, v73
	v_fmac_f32_e32 v75, 0x3f317217, v73
	v_cmp_lt_f32_e64 vcc, |v73|, s18
	s_nop 1
	v_cndmask_b32_e32 v73, v73, v75, vcc
	v_sub_f32_e32 v73, v73, v74
	v_cmp_gt_f32_e32 vcc, s4, v72
	s_nop 1
	v_cndmask_b32_e64 v72, v73, -v72, vcc
	v_sub_f32_e32 v72, -0.5, v72
	v_mul_f32_e32 v72, 0x3fb8aa3b, v72
	v_exp_f32_e32 v72, v72
	s_nop 0
	v_mul_f32_e32 v72, 0xbfb8aa3b, v72
	v_exp_f32_e32 v72, v72
	global_store_dword v[66:67], v72, off offset:128
; #define PW(T, off) ((T*)(lndp(p.ws) + (off)))
; DEVI float bf2f(bf16 h) { return __uint_as_float(((unsigned)h) << 16); }
; DEVI float sigmf(float x) { return __builtin_amdgcn_rcpf(1.f + __expf(-x)); }
; DEVI float softplusf(float x) { return x > 20.f ? x : __logf(1.f + __expf(x)); }
; DEVI float tanhfast(float x) { return 1.f - 2.f / (__expf(2.f * x) + 1.f); }
; DEVI int accrow(int r, int lane) { return (r & 3) + 8 * (r >> 2) + 4 * (lane >> 5); }
; template <int EPI>
; DEVI void gemm_epi(const Params& p, const GJob& jb, f32x16 (&acc)[2][2], int rbase, int cbase, int lane) {
;     ...
;   for (int i = 0; i < 2; ++i) {
; #pragma unroll
;     for (int r = 0; r < 16; ++r) {
;       const int row = rbase + i * 32 + accrow(r, lane);
;       if (row < M) {
; #pragma unroll
;         for (int j = 0; j < 2; ++j) {
;           const int col = cbase + j * 32 + (lane & 31);
;           const float v = acc[i][j][r];
;           if (EPI == EPI_SSD_IN) {
;             if (col < 2048) ((bf16*)(ar + S_ZB))[(size_t)row * 2048 + col] = f2bf(v);
;             else if (col < 6144) ((bf16*)(ar + S_XBC))[(size_t)row * 4096 + col - 2048] = f2bf(v);
;             else if (col < 6176) ((float*)(ar + S_DTRAW))[(size_t)row * 32 + col - 6144] = v;
;           } else if (EPI == EPI_RESID) {
;             PW(bf16, W_Z)[(size_t)row * 1024 + col] = f2bf(ALPHA * bf2f(PW(bf16, W_Xb)[(size_t)row * 1024 + col]) + v);
;           } else if (EPI == EPI_GU) {
;             ((bf16*)(ar + F_GU))[(size_t)row * 5632 + col] = f2bf(v);
;           } else if (EPI == EPI_BF16) {
;             ((bf16*)jb.of)[(size_t)row * 1024 + col] = f2bf(v);
;           } else if (EPI == EPI_F32) {
;             jb.of[(size_t)row * 1024 + col] = v;
;           } else if (EPI == EPI_RK_W1) {
;             if (col < 64) ((bf16*)(ar + R_HW))[(size_t)row * 64 + col] = f2bf(tanhfast(v));
;           } else if (EPI == EPI_RK_A1) {
;             if (col < 64) ((bf16*)(ar + R_HA))[(size_t)row * 64 + col] = f2bf(v);
;           } else if (EPI == EPI_RK_G1) {
;             if (col < 192) ((bf16*)(ar + R_HG))[(size_t)row * 192 + col] = f2bf(col < 160 ? sigmf(v) : 0.f);
;           } else if (EPI == EPI_RK_W2) {
;             const float z = i_rk_w0[col] + v;
;             const float wl = -softplusf(-z) - 0.5f;
;             ((float*)(ar + R_W))[(size_t)row * 1024 + col] = __expf(-__expf(wl));
.LBB0_516:
	s_or_b64 exec, exec, s[2:3]
	s_waitcnt vmcnt(4)
	v_or_b32_e32 v72, 2, v69
	v_or_b32_e32 v66, v72, v68
	v_cmp_gt_i32_e32 vcc, s90, v66
	s_and_saveexec_b64 s[2:3], vcc
	s_cbranch_execz .LBB0_518
	v_lshlrev_b64 v[74:75], 2, v[64:65]
	v_lshl_add_u64 v[76:77], s[8:9], 0, v[74:75]
	v_mov_b32_e32 v67, v170
	s_mov_b32 s5, 0x3f317217
	s_mov_b32 s18, 0x7f800000
	s_mov_b32 s4, 0xc1a00000
	v_add_f32_e32 v67, v34, v67
	v_mul_f32_e32 v73, 0xbfb8aa3b, v67
	v_exp_f32_e32 v73, v73
	s_nop 0
	v_add_f32_e32 v73, 1.0, v73
	v_cmp_gt_f32_e32 vcc, s69, v73
	s_nop 1
	v_cndmask_b32_e64 v78, 0, 32, vcc
	v_ldexp_f32 v73, v73, v78
	v_log_f32_e32 v73, v73
	v_cndmask_b32_e32 v78, 0, v216, vcc
	v_mul_f32_e32 v79, 0x3f317217, v73
	v_fma_f32 v79, v73, s5, -v79
	v_fmac_f32_e32 v79, 0x3377d1cf, v73
	v_fmac_f32_e32 v79, 0x3f317217, v73
	v_cmp_lt_f32_e64 vcc, |v73|, s18
	s_nop 1
	v_cndmask_b32_e32 v73, v73, v79, vcc
	v_sub_f32_e32 v73, v73, v78
	v_cmp_gt_f32_e32 vcc, s4, v67
	s_nop 1
	v_cndmask_b32_e64 v67, v73, -v67, vcc
	v_sub_f32_e32 v67, -0.5, v67
	v_mul_f32_e32 v67, 0x3fb8aa3b, v67
	v_exp_f32_e32 v73, v67
	v_ashrrev_i32_e32 v67, 31, v66
	v_lshlrev_b64 v[66:67], 12, v[66:67]
	v_lshl_add_u64 v[66:67], s[6:7], 0, v[66:67]
	v_mul_f32_e32 v73, 0xbfb8aa3b, v73
	v_exp_f32_e32 v73, v73
	v_lshl_add_u64 v[66:67], v[66:67], 0, v[74:75]
	global_store_dword v[66:67], v73, off
	v_mov_b32_e32 v73, v171
	v_add_f32_e32 v73, v50, v73
	v_mul_f32_e32 v74, 0xbfb8aa3b, v73
	v_exp_f32_e32 v74, v74
	s_nop 0
	v_add_f32_e32 v74, 1.0, v74
	v_cmp_gt_f32_e32 vcc, s69, v74
	s_nop 1
	v_cndmask_b32_e64 v75, 0, 32, vcc
	v_ldexp_f32 v74, v74, v75
	v_log_f32_e32 v74, v74
	v_cndmask_b32_e32 v75, 0, v216, vcc
	v_mul_f32_e32 v76, 0x3f317217, v74
	v_fma_f32 v76, v74, s5, -v76
	v_fmac_f32_e32 v76, 0x3377d1cf, v74
	v_fmac_f32_e32 v76, 0x3f317217, v74
	v_cmp_lt_f32_e64 vcc, |v74|, s18
	s_nop 1
	v_cndmask_b32_e32 v74, v74, v76, vcc
	v_sub_f32_e32 v74, v74, v75
	v_cmp_gt_f32_e32 vcc, s4, v73
	s_nop 1
	v_cndmask_b32_e64 v73, v74, -v73, vcc
	v_sub_f32_e32 v73, -0.5, v73
	v_mul_f32_e32 v73, 0x3fb8aa3b, v73
	v_exp_f32_e32 v73, v73
	s_nop 0
	v_mul_f32_e32 v73, 0xbfb8aa3b, v73
	v_exp_f32_e32 v73, v73
	global_store_dword v[66:67], v73, off offset:128
.LBB0_518:
	s_or_b64 exec, exec, s[2:3]
	v_or_b32_e32 v73, 3, v70
	v_or_b32_e32 v66, v68, v73
	v_cmp_gt_i32_e32 vcc, s90, v66
	s_and_saveexec_b64 s[2:3], vcc
	s_cbranch_execz .LBB0_520
	v_lshlrev_b64 v[74:75], 2, v[64:65]
	v_lshl_add_u64 v[76:77], s[8:9], 0, v[74:75]
	v_mov_b32_e32 v67, v170
	s_mov_b32 s5, 0x3f317217
	s_mov_b32 s18, 0x7f800000
	s_mov_b32 s4, 0xc1a00000
	v_add_f32_e32 v67, v35, v67
	v_mul_f32_e32 v78, 0xbfb8aa3b, v67
	v_exp_f32_e32 v78, v78
	s_nop 0
	v_add_f32_e32 v78, 1.0, v78
	v_cmp_gt_f32_e32 vcc, s69, v78
	s_nop 1
	v_cndmask_b32_e64 v79, 0, 32, vcc
	v_ldexp_f32 v78, v78, v79
	v_log_f32_e32 v78, v78
	v_cndmask_b32_e32 v79, 0, v216, vcc
	v_mul_f32_e32 v80, 0x3f317217, v78
	v_fma_f32 v80, v78, s5, -v80
	v_fmac_f32_e32 v80, 0x3377d1cf, v78
	v_fmac_f32_e32 v80, 0x3f317217, v78
	v_cmp_lt_f32_e64 vcc, |v78|, s18
	s_nop 1
	v_cndmask_b32_e32 v78, v78, v80, vcc
	v_sub_f32_e32 v78, v78, v79
	v_cmp_gt_f32_e32 vcc, s4, v67
	s_nop 1
	v_cndmask_b32_e64 v67, v78, -v67, vcc
	v_sub_f32_e32 v67, -0.5, v67
	v_mul_f32_e32 v67, 0x3fb8aa3b, v67
	v_exp_f32_e32 v78, v67
	v_ashrrev_i32_e32 v67, 31, v66
	v_lshlrev_b64 v[66:67], 12, v[66:67]
	v_lshl_add_u64 v[66:67], s[6:7], 0, v[66:67]
	v_mul_f32_e32 v78, 0xbfb8aa3b, v78
	v_exp_f32_e32 v78, v78
	v_lshl_add_u64 v[66:67], v[66:67], 0, v[74:75]
	global_store_dword v[66:67], v78, off
	v_mov_b32_e32 v74, v171
	v_add_f32_e32 v74, v51, v74
	v_mul_f32_e32 v75, 0xbfb8aa3b, v74
	v_exp_f32_e32 v75, v75
	s_nop 0
	v_add_f32_e32 v75, 1.0, v75
	v_cmp_gt_f32_e32 vcc, s69, v75
	s_nop 1
	v_cndmask_b32_e64 v76, 0, 32, vcc
	v_ldexp_f32 v75, v75, v76
	v_log_f32_e32 v75, v75
	v_cndmask_b32_e32 v76, 0, v216, vcc
	v_mul_f32_e32 v77, 0x3f317217, v75
	v_fma_f32 v77, v75, s5, -v77
	v_fmac_f32_e32 v77, 0x3377d1cf, v75
	v_fmac_f32_e32 v77, 0x3f317217, v75
	v_cmp_lt_f32_e64 vcc, |v75|, s18
	s_nop 1
	v_cndmask_b32_e32 v75, v75, v77, vcc
	v_sub_f32_e32 v75, v75, v76
	v_cmp_gt_f32_e32 vcc, s4, v74
	s_nop 1
	v_cndmask_b32_e64 v74, v75, -v74, vcc
	v_sub_f32_e32 v74, -0.5, v74
	v_mul_f32_e32 v74, 0x3fb8aa3b, v74
	v_exp_f32_e32 v74, v74
	s_nop 0
	v_mul_f32_e32 v74, 0xbfb8aa3b, v74
	v_exp_f32_e32 v74, v74
	global_store_dword v[66:67], v74, off offset:128
.LBB0_520:
	s_or_b64 exec, exec, s[2:3]
	v_or_b32_e32 v74, 8, v69
	v_or_b32_e32 v66, v74, v68
	v_cmp_gt_i32_e32 vcc, s90, v66
	s_and_saveexec_b64 s[2:3], vcc
	s_cbranch_execz .LBB0_522
	v_lshlrev_b64 v[76:77], 2, v[64:65]
	v_lshl_add_u64 v[78:79], s[8:9], 0, v[76:77]
	v_mov_b32_e32 v67, v170
	s_mov_b32 s5, 0x3f317217
	s_mov_b32 s18, 0x7f800000
	s_mov_b32 s4, 0xc1a00000
	v_add_f32_e32 v67, v36, v67
	v_mul_f32_e32 v75, 0xbfb8aa3b, v67
	v_exp_f32_e32 v75, v75
	s_nop 0
	v_add_f32_e32 v75, 1.0, v75
	v_cmp_gt_f32_e32 vcc, s69, v75
	s_nop 1
	v_cndmask_b32_e64 v80, 0, 32, vcc
	v_ldexp_f32 v75, v75, v80
	v_log_f32_e32 v75, v75
	v_cndmask_b32_e32 v80, 0, v216, vcc
	v_mul_f32_e32 v81, 0x3f317217, v75
	v_fma_f32 v81, v75, s5, -v81
	v_fmac_f32_e32 v81, 0x3377d1cf, v75
	v_fmac_f32_e32 v81, 0x3f317217, v75
	v_cmp_lt_f32_e64 vcc, |v75|, s18
	s_nop 1
	v_cndmask_b32_e32 v75, v75, v81, vcc
	v_sub_f32_e32 v75, v75, v80
	v_cmp_gt_f32_e32 vcc, s4, v67
	s_nop 1
	v_cndmask_b32_e64 v67, v75, -v67, vcc
	v_sub_f32_e32 v67, -0.5, v67
	v_mul_f32_e32 v67, 0x3fb8aa3b, v67
	v_exp_f32_e32 v75, v67
	v_ashrrev_i32_e32 v67, 31, v66
	v_lshlrev_b64 v[66:67], 12, v[66:67]
	v_lshl_add_u64 v[66:67], s[6:7], 0, v[66:67]
	v_mul_f32_e32 v75, 0xbfb8aa3b, v75
	v_exp_f32_e32 v75, v75
	v_lshl_add_u64 v[66:67], v[66:67], 0, v[76:77]
	global_store_dword v[66:67], v75, off
	v_mov_b32_e32 v75, v171
	v_add_f32_e32 v75, v52, v75
	v_mul_f32_e32 v76, 0xbfb8aa3b, v75
	v_exp_f32_e32 v76, v76
	s_nop 0
	v_add_f32_e32 v76, 1.0, v76
	v_cmp_gt_f32_e32 vcc, s69, v76
	s_nop 1
	v_cndmask_b32_e64 v77, 0, 32, vcc
	v_ldexp_f32 v76, v76, v77
	v_log_f32_e32 v76, v76
	v_cndmask_b32_e32 v77, 0, v216, vcc
	v_mul_f32_e32 v78, 0x3f317217, v76
	v_fma_f32 v78, v76, s5, -v78
	v_fmac_f32_e32 v78, 0x3377d1cf, v76
	v_fmac_f32_e32 v78, 0x3f317217, v76
	v_cmp_lt_f32_e64 vcc, |v76|, s18
	s_nop 1
	v_cndmask_b32_e32 v76, v76, v78, vcc
	v_sub_f32_e32 v76, v76, v77
	v_cmp_gt_f32_e32 vcc, s4, v75
	s_nop 1
	v_cndmask_b32_e64 v75, v76, -v75, vcc
	v_sub_f32_e32 v75, -0.5, v75
	v_mul_f32_e32 v75, 0x3fb8aa3b, v75
	v_exp_f32_e32 v75, v75
	s_nop 0
	v_mul_f32_e32 v75, 0xbfb8aa3b, v75
	v_exp_f32_e32 v75, v75
	global_store_dword v[66:67], v75, off offset:128
; #define PW(T, off) ((T*)(lndp(p.ws) + (off)))
; DEVI float bf2f(bf16 h) { return __uint_as_float(((unsigned)h) << 16); }
; DEVI float sigmf(float x) { return __builtin_amdgcn_rcpf(1.f + __expf(-x)); }
; DEVI float softplusf(float x) { return x > 20.f ? x : __logf(1.f + __expf(x)); }
; DEVI float tanhfast(float x) { return 1.f - 2.f / (__expf(2.f * x) + 1.f); }
; DEVI int accrow(int r, int lane) { return (r & 3) + 8 * (r >> 2) + 4 * (lane >> 5); }
; template <int EPI>
; DEVI void gemm_epi(const Params& p, const GJob& jb, f32x16 (&acc)[2][2], int rbase, int cbase, int lane) {
;     ...
;   for (int i = 0; i < 2; ++i) {
; #pragma unroll
;     for (int r = 0; r < 16; ++r) {
;       const int row = rbase + i * 32 + accrow(r, lane);
;       if (row < M) {
; #pragma unroll
;         for (int j = 0; j < 2; ++j) {
;           const int col = cbase + j * 32 + (lane & 31);
;           const float v = acc[i][j][r];
;           if (EPI == EPI_SSD_IN) {
;             if (col < 2048) ((bf16*)(ar + S_ZB))[(size_t)row * 2048 + col] = f2bf(v);
;             else if (col < 6144) ((bf16*)(ar + S_XBC))[(size_t)row * 4096 + col - 2048] = f2bf(v);
;             else if (col < 6176) ((float*)(ar + S_DTRAW))[(size_t)row * 32 + col - 6144] = v;
;           } else if (EPI == EPI_RESID) {
;             PW(bf16, W_Z)[(size_t)row * 1024 + col] = f2bf(ALPHA * bf2f(PW(bf16, W_Xb)[(size_t)row * 1024 + col]) + v);
;           } else if (EPI == EPI_GU) {
;             ((bf16*)(ar + F_GU))[(size_t)row * 5632 + col] = f2bf(v);
;           } else if (EPI == EPI_BF16) {
;             ((bf16*)jb.of)[(size_t)row * 1024 + col] = f2bf(v);
;           } else if (EPI == EPI_F32) {
;             jb.of[(size_t)row * 1024 + col] = v;
;           } else if (EPI == EPI_RK_W1) {
;             if (col < 64) ((bf16*)(ar + R_HW))[(size_t)row * 64 + col] = f2bf(tanhfast(v));
;           } else if (EPI == EPI_RK_A1) {
;             if (col < 64) ((bf16*)(ar + R_HA))[(size_t)row * 64 + col] = f2bf(v);
;           } else if (EPI == EPI_RK_G1) {
;             if (col < 192) ((bf16*)(ar + R_HG))[(size_t)row * 192 + col] = f2bf(col < 160 ? sigmf(v) : 0.f);
;           } else if (EPI == EPI_RK_W2) {
;             const float z = i_rk_w0[col] + v;
;             const float wl = -softplusf(-z) - 0.5f;
;             ((float*)(ar + R_W))[(size_t)row * 1024 + col] = __expf(-__expf(wl));
.LBB0_522:
	s_or_b64 exec, exec, s[2:3]
	v_or_b32_e32 v75, 9, v69
	v_or_b32_e32 v66, v75, v68
	v_cmp_gt_i32_e32 vcc, s90, v66
	s_and_saveexec_b64 s[2:3], vcc
	s_cbranch_execz .LBB0_524
	v_lshlrev_b64 v[76:77], 2, v[64:65]
	v_lshl_add_u64 v[78:79], s[8:9], 0, v[76:77]
	v_mov_b32_e32 v67, v170
	s_mov_b32 s5, 0x3f317217
	s_mov_b32 s18, 0x7f800000
	s_mov_b32 s4, 0xc1a00000
	v_add_f32_e32 v67, v37, v67
	v_mul_f32_e32 v80, 0xbfb8aa3b, v67
	v_exp_f32_e32 v80, v80
	s_nop 0
	v_add_f32_e32 v80, 1.0, v80
	v_cmp_gt_f32_e32 vcc, s69, v80
	s_nop 1
	v_cndmask_b32_e64 v81, 0, 32, vcc
	v_ldexp_f32 v80, v80, v81
	v_log_f32_e32 v80, v80
	v_cndmask_b32_e32 v81, 0, v216, vcc
	v_mul_f32_e32 v82, 0x3f317217, v80
	v_fma_f32 v82, v80, s5, -v82
	v_fmac_f32_e32 v82, 0x3377d1cf, v80
	v_fmac_f32_e32 v82, 0x3f317217, v80
	v_cmp_lt_f32_e64 vcc, |v80|, s18
	s_nop 1
	v_cndmask_b32_e32 v80, v80, v82, vcc
	v_sub_f32_e32 v80, v80, v81
	v_cmp_gt_f32_e32 vcc, s4, v67
	s_nop 1
	v_cndmask_b32_e64 v67, v80, -v67, vcc
	v_sub_f32_e32 v67, -0.5, v67
	v_mul_f32_e32 v67, 0x3fb8aa3b, v67
	v_exp_f32_e32 v80, v67
	v_ashrrev_i32_e32 v67, 31, v66
	v_lshlrev_b64 v[66:67], 12, v[66:67]
	v_lshl_add_u64 v[66:67], s[6:7], 0, v[66:67]
	v_mul_f32_e32 v80, 0xbfb8aa3b, v80
	v_exp_f32_e32 v80, v80
	v_lshl_add_u64 v[66:67], v[66:67], 0, v[76:77]
	global_store_dword v[66:67], v80, off
	v_mov_b32_e32 v76, v171
	v_add_f32_e32 v76, v53, v76
	v_mul_f32_e32 v77, 0xbfb8aa3b, v76
	v_exp_f32_e32 v77, v77
	s_nop 0
	v_add_f32_e32 v77, 1.0, v77
	v_cmp_gt_f32_e32 vcc, s69, v77
	s_nop 1
	v_cndmask_b32_e64 v78, 0, 32, vcc
	v_ldexp_f32 v77, v77, v78
	v_log_f32_e32 v77, v77
	v_cndmask_b32_e32 v78, 0, v216, vcc
	v_mul_f32_e32 v79, 0x3f317217, v77
	v_fma_f32 v79, v77, s5, -v79
	v_fmac_f32_e32 v79, 0x3377d1cf, v77
	v_fmac_f32_e32 v79, 0x3f317217, v77
	v_cmp_lt_f32_e64 vcc, |v77|, s18
	s_nop 1
	v_cndmask_b32_e32 v77, v77, v79, vcc
	v_sub_f32_e32 v77, v77, v78
	v_cmp_gt_f32_e32 vcc, s4, v76
	s_nop 1
	v_cndmask_b32_e64 v76, v77, -v76, vcc
	v_sub_f32_e32 v76, -0.5, v76
	v_mul_f32_e32 v76, 0x3fb8aa3b, v76
	v_exp_f32_e32 v76, v76
	s_nop 0
	v_mul_f32_e32 v76, 0xbfb8aa3b, v76
	v_exp_f32_e32 v76, v76
	global_store_dword v[66:67], v76, off offset:128
.LBB0_524:
	s_or_b64 exec, exec, s[2:3]
	v_or_b32_e32 v76, 10, v69
	v_or_b32_e32 v66, v76, v68
	v_cmp_gt_i32_e32 vcc, s90, v66
	s_and_saveexec_b64 s[2:3], vcc
	s_cbranch_execz .LBB0_526
	v_lshlrev_b64 v[78:79], 2, v[64:65]
	s_waitcnt vmcnt(3)
	v_lshl_add_u64 v[80:81], s[8:9], 0, v[78:79]
	v_mov_b32_e32 v67, v170
	s_mov_b32 s5, 0x3f317217
	s_mov_b32 s18, 0x7f800000
	s_mov_b32 s4, 0xc1a00000
	v_add_f32_e32 v67, v38, v67
	v_mul_f32_e32 v77, 0xbfb8aa3b, v67
	v_exp_f32_e32 v77, v77
	s_nop 0
	v_add_f32_e32 v77, 1.0, v77
	v_cmp_gt_f32_e32 vcc, s69, v77
	s_nop 1
	v_cndmask_b32_e64 v82, 0, 32, vcc
	v_ldexp_f32 v77, v77, v82
	v_log_f32_e32 v77, v77
	v_cndmask_b32_e32 v82, 0, v216, vcc
	v_mul_f32_e32 v83, 0x3f317217, v77
	v_fma_f32 v83, v77, s5, -v83
	v_fmac_f32_e32 v83, 0x3377d1cf, v77
	v_fmac_f32_e32 v83, 0x3f317217, v77
	v_cmp_lt_f32_e64 vcc, |v77|, s18
	s_nop 1
	v_cndmask_b32_e32 v77, v77, v83, vcc
	v_sub_f32_e32 v77, v77, v82
	v_cmp_gt_f32_e32 vcc, s4, v67
	s_nop 1
	v_cndmask_b32_e64 v67, v77, -v67, vcc
	v_sub_f32_e32 v67, -0.5, v67
	v_mul_f32_e32 v67, 0x3fb8aa3b, v67
	v_exp_f32_e32 v77, v67
	v_ashrrev_i32_e32 v67, 31, v66
	v_lshlrev_b64 v[66:67], 12, v[66:67]
	v_lshl_add_u64 v[66:67], s[6:7], 0, v[66:67]
	v_mul_f32_e32 v77, 0xbfb8aa3b, v77
	v_exp_f32_e32 v77, v77
	v_lshl_add_u64 v[66:67], v[66:67], 0, v[78:79]
	global_store_dword v[66:67], v77, off
	v_mov_b32_e32 v77, v171
	v_add_f32_e32 v77, v54, v77
	v_mul_f32_e32 v78, 0xbfb8aa3b, v77
	v_exp_f32_e32 v78, v78
	s_nop 0
	v_add_f32_e32 v78, 1.0, v78
	v_cmp_gt_f32_e32 vcc, s69, v78
	s_nop 1
	v_cndmask_b32_e64 v79, 0, 32, vcc
	v_ldexp_f32 v78, v78, v79
	v_log_f32_e32 v78, v78
	v_cndmask_b32_e32 v79, 0, v216, vcc
	v_mul_f32_e32 v80, 0x3f317217, v78
	v_fma_f32 v80, v78, s5, -v80
	v_fmac_f32_e32 v80, 0x3377d1cf, v78
	v_fmac_f32_e32 v80, 0x3f317217, v78
	v_cmp_lt_f32_e64 vcc, |v78|, s18
	s_nop 1
	v_cndmask_b32_e32 v78, v78, v80, vcc
	v_sub_f32_e32 v78, v78, v79
	v_cmp_gt_f32_e32 vcc, s4, v77
	s_nop 1
	v_cndmask_b32_e64 v77, v78, -v77, vcc
	v_sub_f32_e32 v77, -0.5, v77
	v_mul_f32_e32 v77, 0x3fb8aa3b, v77
	v_exp_f32_e32 v77, v77
	s_nop 0
	v_mul_f32_e32 v77, 0xbfb8aa3b, v77
	v_exp_f32_e32 v77, v77
	global_store_dword v[66:67], v77, off offset:128
.LBB0_526:
	s_or_b64 exec, exec, s[2:3]
	v_or_b32_e32 v77, 11, v70
	v_or_b32_e32 v66, v68, v77
	v_cmp_gt_i32_e32 vcc, s90, v66
	s_and_saveexec_b64 s[2:3], vcc
	s_cbranch_execz .LBB0_528
	v_lshlrev_b64 v[78:79], 2, v[64:65]
	s_waitcnt vmcnt(3)
	v_lshl_add_u64 v[80:81], s[8:9], 0, v[78:79]
	v_mov_b32_e32 v67, v170
	s_mov_b32 s5, 0x3f317217
	s_mov_b32 s18, 0x7f800000
	s_mov_b32 s4, 0xc1a00000
	v_add_f32_e32 v67, v39, v67
	v_mul_f32_e32 v82, 0xbfb8aa3b, v67
	v_exp_f32_e32 v82, v82
	s_nop 0
	v_add_f32_e32 v82, 1.0, v82
	v_cmp_gt_f32_e32 vcc, s69, v82
	s_nop 1
	v_cndmask_b32_e64 v83, 0, 32, vcc
	v_ldexp_f32 v82, v82, v83
	v_log_f32_e32 v82, v82
	v_cndmask_b32_e32 v83, 0, v216, vcc
	v_mul_f32_e32 v84, 0x3f317217, v82
	v_fma_f32 v84, v82, s5, -v84
	v_fmac_f32_e32 v84, 0x3377d1cf, v82
	v_fmac_f32_e32 v84, 0x3f317217, v82
	v_cmp_lt_f32_e64 vcc, |v82|, s18
	s_nop 1
	v_cndmask_b32_e32 v82, v82, v84, vcc
	v_sub_f32_e32 v82, v82, v83
	v_cmp_gt_f32_e32 vcc, s4, v67
	s_nop 1
	v_cndmask_b32_e64 v67, v82, -v67, vcc
	v_sub_f32_e32 v67, -0.5, v67
	v_mul_f32_e32 v67, 0x3fb8aa3b, v67
	v_exp_f32_e32 v82, v67
	v_ashrrev_i32_e32 v67, 31, v66
	v_lshlrev_b64 v[66:67], 12, v[66:67]
	v_lshl_add_u64 v[66:67], s[6:7], 0, v[66:67]
	v_mul_f32_e32 v82, 0xbfb8aa3b, v82
	v_exp_f32_e32 v82, v82
	v_lshl_add_u64 v[66:67], v[66:67], 0, v[78:79]
	global_store_dword v[66:67], v82, off
	v_mov_b32_e32 v78, v171
	v_add_f32_e32 v78, v55, v78
	v_mul_f32_e32 v79, 0xbfb8aa3b, v78
	v_exp_f32_e32 v79, v79
	s_nop 0
	v_add_f32_e32 v79, 1.0, v79
	v_cmp_gt_f32_e32 vcc, s69, v79
	s_nop 1
	v_cndmask_b32_e64 v80, 0, 32, vcc
	v_ldexp_f32 v79, v79, v80
	v_log_f32_e32 v79, v79
	v_cndmask_b32_e32 v80, 0, v216, vcc
	v_mul_f32_e32 v81, 0x3f317217, v79
	v_fma_f32 v81, v79, s5, -v81
	v_fmac_f32_e32 v81, 0x3377d1cf, v79
	v_fmac_f32_e32 v81, 0x3f317217, v79
	v_cmp_lt_f32_e64 vcc, |v79|, s18
	s_nop 1
	v_cndmask_b32_e32 v79, v79, v81, vcc
	v_sub_f32_e32 v79, v79, v80
	v_cmp_gt_f32_e32 vcc, s4, v78
	s_nop 1
	v_cndmask_b32_e64 v78, v79, -v78, vcc
	v_sub_f32_e32 v78, -0.5, v78
	v_mul_f32_e32 v78, 0x3fb8aa3b, v78
	v_exp_f32_e32 v78, v78
	s_nop 0
	v_mul_f32_e32 v78, 0xbfb8aa3b, v78
	v_exp_f32_e32 v78, v78
	global_store_dword v[66:67], v78, off offset:128
; #define PW(T, off) ((T*)(lndp(p.ws) + (off)))
; DEVI float bf2f(bf16 h) { return __uint_as_float(((unsigned)h) << 16); }
; DEVI float sigmf(float x) { return __builtin_amdgcn_rcpf(1.f + __expf(-x)); }
; DEVI float softplusf(float x) { return x > 20.f ? x : __logf(1.f + __expf(x)); }
; DEVI float tanhfast(float x) { return 1.f - 2.f / (__expf(2.f * x) + 1.f); }
; DEVI int accrow(int r, int lane) { return (r & 3) + 8 * (r >> 2) + 4 * (lane >> 5); }
; template <int EPI>
; DEVI void gemm_epi(const Params& p, const GJob& jb, f32x16 (&acc)[2][2], int rbase, int cbase, int lane) {
;     ...
;   for (int i = 0; i < 2; ++i) {
; #pragma unroll
;     for (int r = 0; r < 16; ++r) {
;       const int row = rbase + i * 32 + accrow(r, lane);
;       if (row < M) {
; #pragma unroll
;         for (int j = 0; j < 2; ++j) {
;           const int col = cbase + j * 32 + (lane & 31);
;           const float v = acc[i][j][r];
;           if (EPI == EPI_SSD_IN) {
;             if (col < 2048) ((bf16*)(ar + S_ZB))[(size_t)row * 2048 + col] = f2bf(v);
;             else if (col < 6144) ((bf16*)(ar + S_XBC))[(size_t)row * 4096 + col - 2048] = f2bf(v);
;             else if (col < 6176) ((float*)(ar + S_DTRAW))[(size_t)row * 32 + col - 6144] = v;
;           } else if (EPI == EPI_RESID) {
;             PW(bf16, W_Z)[(size_t)row * 1024 + col] = f2bf(ALPHA * bf2f(PW(bf16, W_Xb)[(size_t)row * 1024 + col]) + v);
;           } else if (EPI == EPI_GU) {
;             ((bf16*)(ar + F_GU))[(size_t)row * 5632 + col] = f2bf(v);
;           } else if (EPI == EPI_BF16) {
;             ((bf16*)jb.of)[(size_t)row * 1024 + col] = f2bf(v);
;           } else if (EPI == EPI_F32) {
;             jb.of[(size_t)row * 1024 + col] = v;
;           } else if (EPI == EPI_RK_W1) {
;             if (col < 64) ((bf16*)(ar + R_HW))[(size_t)row * 64 + col] = f2bf(tanhfast(v));
;           } else if (EPI == EPI_RK_A1) {
;             if (col < 64) ((bf16*)(ar + R_HA))[(size_t)row * 64 + col] = f2bf(v);
;           } else if (EPI == EPI_RK_G1) {
;             if (col < 192) ((bf16*)(ar + R_HG))[(size_t)row * 192 + col] = f2bf(col < 160 ? sigmf(v) : 0.f);
;           } else if (EPI == EPI_RK_W2) {
;             const float z = i_rk_w0[col] + v;
;             const float wl = -softplusf(-z) - 0.5f;
;             ((float*)(ar + R_W))[(size_t)row * 1024 + col] = __expf(-__expf(wl));
.LBB0_528:
	s_or_b64 exec, exec, s[2:3]
	v_or_b32_e32 v78, 16, v69
	v_or_b32_e32 v66, v78, v68
	v_cmp_gt_i32_e32 vcc, s90, v66
	s_and_saveexec_b64 s[2:3], vcc
	s_cbranch_execz .LBB0_530
	s_waitcnt vmcnt(3)
	v_lshlrev_b64 v[80:81], 2, v[64:65]
	v_lshl_add_u64 v[82:83], s[8:9], 0, v[80:81]
	v_mov_b32_e32 v67, v170
	s_mov_b32 s5, 0x3f317217
	s_mov_b32 s18, 0x7f800000
	s_mov_b32 s4, 0xc1a00000
	v_add_f32_e32 v67, v40, v67
	v_mul_f32_e32 v79, 0xbfb8aa3b, v67
	v_exp_f32_e32 v79, v79
	s_nop 0
	v_add_f32_e32 v79, 1.0, v79
	v_cmp_gt_f32_e32 vcc, s69, v79
	s_nop 1
	v_cndmask_b32_e64 v84, 0, 32, vcc
	v_ldexp_f32 v79, v79, v84
	v_log_f32_e32 v79, v79
	v_cndmask_b32_e32 v84, 0, v216, vcc
	v_mul_f32_e32 v85, 0x3f317217, v79
	v_fma_f32 v85, v79, s5, -v85
	v_fmac_f32_e32 v85, 0x3377d1cf, v79
	v_fmac_f32_e32 v85, 0x3f317217, v79
	v_cmp_lt_f32_e64 vcc, |v79|, s18
	s_nop 1
	v_cndmask_b32_e32 v79, v79, v85, vcc
	v_sub_f32_e32 v79, v79, v84
	v_cmp_gt_f32_e32 vcc, s4, v67
	s_nop 1
	v_cndmask_b32_e64 v67, v79, -v67, vcc
	v_sub_f32_e32 v67, -0.5, v67
	v_mul_f32_e32 v67, 0x3fb8aa3b, v67
	v_exp_f32_e32 v79, v67
	v_ashrrev_i32_e32 v67, 31, v66
	v_lshlrev_b64 v[66:67], 12, v[66:67]
	v_lshl_add_u64 v[66:67], s[6:7], 0, v[66:67]
	v_mul_f32_e32 v79, 0xbfb8aa3b, v79
	v_exp_f32_e32 v79, v79
	v_lshl_add_u64 v[66:67], v[66:67], 0, v[80:81]
	global_store_dword v[66:67], v79, off
	v_mov_b32_e32 v79, v171
	v_add_f32_e32 v79, v56, v79
	v_mul_f32_e32 v80, 0xbfb8aa3b, v79
	v_exp_f32_e32 v80, v80
	s_nop 0
	v_add_f32_e32 v80, 1.0, v80
	v_cmp_gt_f32_e32 vcc, s69, v80
	s_nop 1
	v_cndmask_b32_e64 v81, 0, 32, vcc
	v_ldexp_f32 v80, v80, v81
	v_log_f32_e32 v80, v80
	v_cndmask_b32_e32 v81, 0, v216, vcc
	v_mul_f32_e32 v82, 0x3f317217, v80
	v_fma_f32 v82, v80, s5, -v82
	v_fmac_f32_e32 v82, 0x3377d1cf, v80
	v_fmac_f32_e32 v82, 0x3f317217, v80
	v_cmp_lt_f32_e64 vcc, |v80|, s18
	s_nop 1
	v_cndmask_b32_e32 v80, v80, v82, vcc
	v_sub_f32_e32 v80, v80, v81
	v_cmp_gt_f32_e32 vcc, s4, v79
	s_nop 1
	v_cndmask_b32_e64 v79, v80, -v79, vcc
	v_sub_f32_e32 v79, -0.5, v79
	v_mul_f32_e32 v79, 0x3fb8aa3b, v79
	v_exp_f32_e32 v79, v79
	s_nop 0
	v_mul_f32_e32 v79, 0xbfb8aa3b, v79
	v_exp_f32_e32 v79, v79
	global_store_dword v[66:67], v79, off offset:128
.LBB0_530:
	s_or_b64 exec, exec, s[2:3]
	v_or_b32_e32 v79, 17, v69
	v_or_b32_e32 v66, v79, v68
	v_cmp_gt_i32_e32 vcc, s90, v66
	s_and_saveexec_b64 s[2:3], vcc
	s_cbranch_execz .LBB0_532
	s_waitcnt vmcnt(3)
	v_lshlrev_b64 v[80:81], 2, v[64:65]
	v_lshl_add_u64 v[82:83], s[8:9], 0, v[80:81]
	v_mov_b32_e32 v67, v170
	s_mov_b32 s5, 0x3f317217
	s_mov_b32 s18, 0x7f800000
	s_mov_b32 s4, 0xc1a00000
	v_add_f32_e32 v67, v41, v67
	v_mul_f32_e32 v84, 0xbfb8aa3b, v67
	v_exp_f32_e32 v84, v84
	s_nop 0
	v_add_f32_e32 v84, 1.0, v84
	v_cmp_gt_f32_e32 vcc, s69, v84
	s_nop 1
	v_cndmask_b32_e64 v85, 0, 32, vcc
	v_ldexp_f32 v84, v84, v85
	v_log_f32_e32 v84, v84
	v_cndmask_b32_e32 v85, 0, v216, vcc
	v_mul_f32_e32 v86, 0x3f317217, v84
	v_fma_f32 v86, v84, s5, -v86
	v_fmac_f32_e32 v86, 0x3377d1cf, v84
	v_fmac_f32_e32 v86, 0x3f317217, v84
	v_cmp_lt_f32_e64 vcc, |v84|, s18
	s_nop 1
	v_cndmask_b32_e32 v84, v84, v86, vcc
	v_sub_f32_e32 v84, v84, v85
	v_cmp_gt_f32_e32 vcc, s4, v67
	s_nop 1
	v_cndmask_b32_e64 v67, v84, -v67, vcc
	v_sub_f32_e32 v67, -0.5, v67
	v_mul_f32_e32 v67, 0x3fb8aa3b, v67
	v_exp_f32_e32 v84, v67
	v_ashrrev_i32_e32 v67, 31, v66
	v_lshlrev_b64 v[66:67], 12, v[66:67]
	v_lshl_add_u64 v[66:67], s[6:7], 0, v[66:67]
	v_mul_f32_e32 v84, 0xbfb8aa3b, v84
	v_exp_f32_e32 v84, v84
	v_lshl_add_u64 v[66:67], v[66:67], 0, v[80:81]
	global_store_dword v[66:67], v84, off
	v_mov_b32_e32 v80, v171
	v_add_f32_e32 v80, v57, v80
	v_mul_f32_e32 v81, 0xbfb8aa3b, v80
	v_exp_f32_e32 v81, v81
	s_nop 0
	v_add_f32_e32 v81, 1.0, v81
	v_cmp_gt_f32_e32 vcc, s69, v81
	s_nop 1
	v_cndmask_b32_e64 v82, 0, 32, vcc
	v_ldexp_f32 v81, v81, v82
	v_log_f32_e32 v81, v81
	v_cndmask_b32_e32 v82, 0, v216, vcc
	v_mul_f32_e32 v83, 0x3f317217, v81
	v_fma_f32 v83, v81, s5, -v83
	v_fmac_f32_e32 v83, 0x3377d1cf, v81
	v_fmac_f32_e32 v83, 0x3f317217, v81
	v_cmp_lt_f32_e64 vcc, |v81|, s18
	s_nop 1
	v_cndmask_b32_e32 v81, v81, v83, vcc
	v_sub_f32_e32 v81, v81, v82
	v_cmp_gt_f32_e32 vcc, s4, v80
	s_nop 1
	v_cndmask_b32_e64 v80, v81, -v80, vcc
	v_sub_f32_e32 v80, -0.5, v80
	v_mul_f32_e32 v80, 0x3fb8aa3b, v80
	v_exp_f32_e32 v80, v80
	s_nop 0
	v_mul_f32_e32 v80, 0xbfb8aa3b, v80
	v_exp_f32_e32 v80, v80
	global_store_dword v[66:67], v80, off offset:128
.LBB0_532:
	s_or_b64 exec, exec, s[2:3]
	s_waitcnt vmcnt(3)
	v_or_b32_e32 v80, 18, v69
	v_or_b32_e32 v66, v80, v68
	v_cmp_gt_i32_e32 vcc, s90, v66
	s_and_saveexec_b64 s[2:3], vcc
	s_cbranch_execz .LBB0_534
	v_lshlrev_b64 v[82:83], 2, v[64:65]
	s_waitcnt vmcnt(2)
	v_lshl_add_u64 v[84:85], s[8:9], 0, v[82:83]
	v_mov_b32_e32 v67, v170
	s_mov_b32 s5, 0x3f317217
	s_mov_b32 s18, 0x7f800000
	s_mov_b32 s4, 0xc1a00000
	v_add_f32_e32 v67, v42, v67
	v_mul_f32_e32 v81, 0xbfb8aa3b, v67
	v_exp_f32_e32 v81, v81
	s_nop 0
	v_add_f32_e32 v81, 1.0, v81
	v_cmp_gt_f32_e32 vcc, s69, v81
	s_nop 1
	v_cndmask_b32_e64 v86, 0, 32, vcc
	v_ldexp_f32 v81, v81, v86
	v_log_f32_e32 v81, v81
	v_cndmask_b32_e32 v86, 0, v216, vcc
	v_mul_f32_e32 v87, 0x3f317217, v81
	v_fma_f32 v87, v81, s5, -v87
	v_fmac_f32_e32 v87, 0x3377d1cf, v81
	v_fmac_f32_e32 v87, 0x3f317217, v81
	v_cmp_lt_f32_e64 vcc, |v81|, s18
	s_nop 1
	v_cndmask_b32_e32 v81, v81, v87, vcc
	v_sub_f32_e32 v81, v81, v86
	v_cmp_gt_f32_e32 vcc, s4, v67
	s_nop 1
	v_cndmask_b32_e64 v67, v81, -v67, vcc
	v_sub_f32_e32 v67, -0.5, v67
	v_mul_f32_e32 v67, 0x3fb8aa3b, v67
	v_exp_f32_e32 v81, v67
	v_ashrrev_i32_e32 v67, 31, v66
	v_lshlrev_b64 v[66:67], 12, v[66:67]
	v_lshl_add_u64 v[66:67], s[6:7], 0, v[66:67]
	v_mul_f32_e32 v81, 0xbfb8aa3b, v81
	v_exp_f32_e32 v81, v81
	v_lshl_add_u64 v[66:67], v[66:67], 0, v[82:83]
	global_store_dword v[66:67], v81, off
	v_mov_b32_e32 v81, v171
	v_add_f32_e32 v81, v58, v81
	v_mul_f32_e32 v82, 0xbfb8aa3b, v81
	v_exp_f32_e32 v82, v82
	s_nop 0
	v_add_f32_e32 v82, 1.0, v82
	v_cmp_gt_f32_e32 vcc, s69, v82
	s_nop 1
	v_cndmask_b32_e64 v83, 0, 32, vcc
	v_ldexp_f32 v82, v82, v83
	v_log_f32_e32 v82, v82
	v_cndmask_b32_e32 v83, 0, v216, vcc
	v_mul_f32_e32 v84, 0x3f317217, v82
	v_fma_f32 v84, v82, s5, -v84
	v_fmac_f32_e32 v84, 0x3377d1cf, v82
	v_fmac_f32_e32 v84, 0x3f317217, v82
	v_cmp_lt_f32_e64 vcc, |v82|, s18
	s_nop 1
	v_cndmask_b32_e32 v82, v82, v84, vcc
	v_sub_f32_e32 v82, v82, v83
	v_cmp_gt_f32_e32 vcc, s4, v81
	s_nop 1
	v_cndmask_b32_e64 v81, v82, -v81, vcc
	v_sub_f32_e32 v81, -0.5, v81
	v_mul_f32_e32 v81, 0x3fb8aa3b, v81
	v_exp_f32_e32 v81, v81
	s_nop 0
	v_mul_f32_e32 v81, 0xbfb8aa3b, v81
	v_exp_f32_e32 v81, v81
	global_store_dword v[66:67], v81, off offset:128
; #define PW(T, off) ((T*)(lndp(p.ws) + (off)))
; DEVI float bf2f(bf16 h) { return __uint_as_float(((unsigned)h) << 16); }
; DEVI float sigmf(float x) { return __builtin_amdgcn_rcpf(1.f + __expf(-x)); }
; DEVI float softplusf(float x) { return x > 20.f ? x : __logf(1.f + __expf(x)); }
; DEVI float tanhfast(float x) { return 1.f - 2.f / (__expf(2.f * x) + 1.f); }
; DEVI int accrow(int r, int lane) { return (r & 3) + 8 * (r >> 2) + 4 * (lane >> 5); }
; template <int EPI>
; DEVI void gemm_epi(const Params& p, const GJob& jb, f32x16 (&acc)[2][2], int rbase, int cbase, int lane) {
;     ...
;   for (int i = 0; i < 2; ++i) {
; #pragma unroll
;     for (int r = 0; r < 16; ++r) {
;       const int row = rbase + i * 32 + accrow(r, lane);
;       if (row < M) {
; #pragma unroll
;         for (int j = 0; j < 2; ++j) {
;           const int col = cbase + j * 32 + (lane & 31);
;           const float v = acc[i][j][r];
;           if (EPI == EPI_SSD_IN) {
;             if (col < 2048) ((bf16*)(ar + S_ZB))[(size_t)row * 2048 + col] = f2bf(v);
;             else if (col < 6144) ((bf16*)(ar + S_XBC))[(size_t)row * 4096 + col - 2048] = f2bf(v);
;             else if (col < 6176) ((float*)(ar + S_DTRAW))[(size_t)row * 32 + col - 6144] = v;
;           } else if (EPI == EPI_RESID) {
;             PW(bf16, W_Z)[(size_t)row * 1024 + col] = f2bf(ALPHA * bf2f(PW(bf16, W_Xb)[(size_t)row * 1024 + col]) + v);
;           } else if (EPI == EPI_GU) {
;             ((bf16*)(ar + F_GU))[(size_t)row * 5632 + col] = f2bf(v);
;           } else if (EPI == EPI_BF16) {
;             ((bf16*)jb.of)[(size_t)row * 1024 + col] = f2bf(v);
;           } else if (EPI == EPI_F32) {
;             jb.of[(size_t)row * 1024 + col] = v;
;           } else if (EPI == EPI_RK_W1) {
;             if (col < 64) ((bf16*)(ar + R_HW))[(size_t)row * 64 + col] = f2bf(tanhfast(v));
;           } else if (EPI == EPI_RK_A1) {
;             if (col < 64) ((bf16*)(ar + R_HA))[(size_t)row * 64 + col] = f2bf(v);
;           } else if (EPI == EPI_RK_G1) {
;             if (col < 192) ((bf16*)(ar + R_HG))[(size_t)row * 192 + col] = f2bf(col < 160 ? sigmf(v) : 0.f);
;           } else if (EPI == EPI_RK_W2) {
;             const float z = i_rk_w0[col] + v;
;             const float wl = -softplusf(-z) - 0.5f;
;             ((float*)(ar + R_W))[(size_t)row * 1024 + col] = __expf(-__expf(wl));
.LBB0_534:
	s_or_b64 exec, exec, s[2:3]
	v_or_b32_e32 v81, 19, v70
	v_or_b32_e32 v66, v68, v81
	v_cmp_gt_i32_e32 vcc, s90, v66
	s_and_saveexec_b64 s[2:3], vcc
	s_cbranch_execz .LBB0_536
	v_lshlrev_b64 v[82:83], 2, v[64:65]
	s_waitcnt vmcnt(2)
	v_lshl_add_u64 v[84:85], s[8:9], 0, v[82:83]
	v_mov_b32_e32 v67, v170
	s_mov_b32 s5, 0x3f317217
	s_mov_b32 s18, 0x7f800000
	s_mov_b32 s4, 0xc1a00000
	v_add_f32_e32 v67, v43, v67
	v_mul_f32_e32 v86, 0xbfb8aa3b, v67
	v_exp_f32_e32 v86, v86
	s_nop 0
	v_add_f32_e32 v86, 1.0, v86
	v_cmp_gt_f32_e32 vcc, s69, v86
	s_nop 1
	v_cndmask_b32_e64 v87, 0, 32, vcc
	v_ldexp_f32 v86, v86, v87
	v_log_f32_e32 v86, v86
	v_cndmask_b32_e32 v87, 0, v216, vcc
	v_mul_f32_e32 v88, 0x3f317217, v86
	v_fma_f32 v88, v86, s5, -v88
	v_fmac_f32_e32 v88, 0x3377d1cf, v86
	v_fmac_f32_e32 v88, 0x3f317217, v86
	v_cmp_lt_f32_e64 vcc, |v86|, s18
	s_nop 1
	v_cndmask_b32_e32 v86, v86, v88, vcc
	v_sub_f32_e32 v86, v86, v87
	v_cmp_gt_f32_e32 vcc, s4, v67
	s_nop 1
	v_cndmask_b32_e64 v67, v86, -v67, vcc
	v_sub_f32_e32 v67, -0.5, v67
	v_mul_f32_e32 v67, 0x3fb8aa3b, v67
	v_exp_f32_e32 v86, v67
	v_ashrrev_i32_e32 v67, 31, v66
	v_lshlrev_b64 v[66:67], 12, v[66:67]
	v_lshl_add_u64 v[66:67], s[6:7], 0, v[66:67]
	v_mul_f32_e32 v86, 0xbfb8aa3b, v86
	v_exp_f32_e32 v86, v86
	v_lshl_add_u64 v[66:67], v[66:67], 0, v[82:83]
	global_store_dword v[66:67], v86, off
	v_mov_b32_e32 v82, v171
	v_add_f32_e32 v82, v59, v82
	v_mul_f32_e32 v83, 0xbfb8aa3b, v82
	v_exp_f32_e32 v83, v83
	s_nop 0
	v_add_f32_e32 v83, 1.0, v83
	v_cmp_gt_f32_e32 vcc, s69, v83
	s_nop 1
	v_cndmask_b32_e64 v84, 0, 32, vcc
	v_ldexp_f32 v83, v83, v84
	v_log_f32_e32 v83, v83
	v_cndmask_b32_e32 v84, 0, v216, vcc
	v_mul_f32_e32 v85, 0x3f317217, v83
	v_fma_f32 v85, v83, s5, -v85
	v_fmac_f32_e32 v85, 0x3377d1cf, v83
	v_fmac_f32_e32 v85, 0x3f317217, v83
	v_cmp_lt_f32_e64 vcc, |v83|, s18
	s_nop 1
	v_cndmask_b32_e32 v83, v83, v85, vcc
	v_sub_f32_e32 v83, v83, v84
	v_cmp_gt_f32_e32 vcc, s4, v82
	s_nop 1
	v_cndmask_b32_e64 v82, v83, -v82, vcc
	v_sub_f32_e32 v82, -0.5, v82
	v_mul_f32_e32 v82, 0x3fb8aa3b, v82
	v_exp_f32_e32 v82, v82
	s_nop 0
	v_mul_f32_e32 v82, 0xbfb8aa3b, v82
	v_exp_f32_e32 v82, v82
	global_store_dword v[66:67], v82, off offset:128
.LBB0_536:
	s_or_b64 exec, exec, s[2:3]
	v_or_b32_e32 v82, 24, v69
	v_or_b32_e32 v66, v82, v68
	v_cmp_gt_i32_e32 vcc, s90, v66
	s_and_saveexec_b64 s[2:3], vcc
	s_cbranch_execz .LBB0_538
	s_waitcnt vmcnt(2)
	v_lshlrev_b64 v[84:85], 2, v[64:65]
	v_lshl_add_u64 v[86:87], s[8:9], 0, v[84:85]
	v_mov_b32_e32 v67, v170
	s_mov_b32 s5, 0x3f317217
	s_mov_b32 s18, 0x7f800000
	s_mov_b32 s4, 0xc1a00000
	v_add_f32_e32 v67, v44, v67
	v_mul_f32_e32 v83, 0xbfb8aa3b, v67
	v_exp_f32_e32 v83, v83
	s_nop 0
	v_add_f32_e32 v83, 1.0, v83
	v_cmp_gt_f32_e32 vcc, s69, v83
	s_nop 1
	v_cndmask_b32_e64 v88, 0, 32, vcc
	v_ldexp_f32 v83, v83, v88
	v_log_f32_e32 v83, v83
	v_cndmask_b32_e32 v88, 0, v216, vcc
	v_mul_f32_e32 v89, 0x3f317217, v83
	v_fma_f32 v89, v83, s5, -v89
	v_fmac_f32_e32 v89, 0x3377d1cf, v83
	v_fmac_f32_e32 v89, 0x3f317217, v83
	v_cmp_lt_f32_e64 vcc, |v83|, s18
	s_nop 1
	v_cndmask_b32_e32 v83, v83, v89, vcc
	v_sub_f32_e32 v83, v83, v88
	v_cmp_gt_f32_e32 vcc, s4, v67
	s_nop 1
	v_cndmask_b32_e64 v67, v83, -v67, vcc
	v_sub_f32_e32 v67, -0.5, v67
	v_mul_f32_e32 v67, 0x3fb8aa3b, v67
	v_exp_f32_e32 v83, v67
	v_ashrrev_i32_e32 v67, 31, v66
	v_lshlrev_b64 v[66:67], 12, v[66:67]
	v_lshl_add_u64 v[66:67], s[6:7], 0, v[66:67]
	v_mul_f32_e32 v83, 0xbfb8aa3b, v83
	v_exp_f32_e32 v83, v83
	v_lshl_add_u64 v[66:67], v[66:67], 0, v[84:85]
	global_store_dword v[66:67], v83, off
	v_mov_b32_e32 v83, v171
	v_add_f32_e32 v83, v60, v83
	v_mul_f32_e32 v84, 0xbfb8aa3b, v83
	v_exp_f32_e32 v84, v84
	s_nop 0
	v_add_f32_e32 v84, 1.0, v84
	v_cmp_gt_f32_e32 vcc, s69, v84
	s_nop 1
	v_cndmask_b32_e64 v85, 0, 32, vcc
	v_ldexp_f32 v84, v84, v85
	v_log_f32_e32 v84, v84
	v_cndmask_b32_e32 v85, 0, v216, vcc
	v_mul_f32_e32 v86, 0x3f317217, v84
	v_fma_f32 v86, v84, s5, -v86
	v_fmac_f32_e32 v86, 0x3377d1cf, v84
	v_fmac_f32_e32 v86, 0x3f317217, v84
	v_cmp_lt_f32_e64 vcc, |v84|, s18
	s_nop 1
	v_cndmask_b32_e32 v84, v84, v86, vcc
	v_sub_f32_e32 v84, v84, v85
	v_cmp_gt_f32_e32 vcc, s4, v83
	s_nop 1
	v_cndmask_b32_e64 v83, v84, -v83, vcc
	v_sub_f32_e32 v83, -0.5, v83
	v_mul_f32_e32 v83, 0x3fb8aa3b, v83
	v_exp_f32_e32 v83, v83
	s_nop 0
	v_mul_f32_e32 v83, 0xbfb8aa3b, v83
	v_exp_f32_e32 v83, v83
	global_store_dword v[66:67], v83, off offset:128
.LBB0_538:
	s_or_b64 exec, exec, s[2:3]
	v_or_b32_e32 v83, 25, v69
	v_or_b32_e32 v66, v83, v68
	v_cmp_gt_i32_e32 vcc, s90, v66
	s_and_saveexec_b64 s[2:3], vcc
	s_cbranch_execz .LBB0_540
	s_waitcnt vmcnt(2)
	v_lshlrev_b64 v[84:85], 2, v[64:65]
	v_lshl_add_u64 v[86:87], s[8:9], 0, v[84:85]
	v_mov_b32_e32 v67, v170
	s_mov_b32 s5, 0x3f317217
	s_mov_b32 s18, 0x7f800000
	s_mov_b32 s4, 0xc1a00000
	v_add_f32_e32 v67, v45, v67
	v_mul_f32_e32 v88, 0xbfb8aa3b, v67
	v_exp_f32_e32 v88, v88
	s_nop 0
	v_add_f32_e32 v88, 1.0, v88
	v_cmp_gt_f32_e32 vcc, s69, v88
	s_nop 1
	v_cndmask_b32_e64 v89, 0, 32, vcc
	v_ldexp_f32 v88, v88, v89
	v_log_f32_e32 v88, v88
	v_cndmask_b32_e32 v89, 0, v216, vcc
	v_mul_f32_e32 v90, 0x3f317217, v88
	v_fma_f32 v90, v88, s5, -v90
	v_fmac_f32_e32 v90, 0x3377d1cf, v88
	v_fmac_f32_e32 v90, 0x3f317217, v88
	v_cmp_lt_f32_e64 vcc, |v88|, s18
	s_nop 1
	v_cndmask_b32_e32 v88, v88, v90, vcc
	v_sub_f32_e32 v88, v88, v89
	v_cmp_gt_f32_e32 vcc, s4, v67
	s_nop 1
	v_cndmask_b32_e64 v67, v88, -v67, vcc
	v_sub_f32_e32 v67, -0.5, v67
	v_mul_f32_e32 v67, 0x3fb8aa3b, v67
	v_exp_f32_e32 v88, v67
	v_ashrrev_i32_e32 v67, 31, v66
	v_lshlrev_b64 v[66:67], 12, v[66:67]
	v_lshl_add_u64 v[66:67], s[6:7], 0, v[66:67]
	v_mul_f32_e32 v88, 0xbfb8aa3b, v88
	v_exp_f32_e32 v88, v88
	v_lshl_add_u64 v[66:67], v[66:67], 0, v[84:85]
	global_store_dword v[66:67], v88, off
	v_mov_b32_e32 v84, v171
	v_add_f32_e32 v84, v61, v84
	v_mul_f32_e32 v85, 0xbfb8aa3b, v84
	v_exp_f32_e32 v85, v85
	s_nop 0
	v_add_f32_e32 v85, 1.0, v85
	v_cmp_gt_f32_e32 vcc, s69, v85
	s_nop 1
	v_cndmask_b32_e64 v86, 0, 32, vcc
	v_ldexp_f32 v85, v85, v86
	v_log_f32_e32 v85, v85
	v_cndmask_b32_e32 v86, 0, v216, vcc
	v_mul_f32_e32 v87, 0x3f317217, v85
	v_fma_f32 v87, v85, s5, -v87
	v_fmac_f32_e32 v87, 0x3377d1cf, v85
	v_fmac_f32_e32 v87, 0x3f317217, v85
	v_cmp_lt_f32_e64 vcc, |v85|, s18
	s_nop 1
	v_cndmask_b32_e32 v85, v85, v87, vcc
	v_sub_f32_e32 v85, v85, v86
	v_cmp_gt_f32_e32 vcc, s4, v84
	s_nop 1
	v_cndmask_b32_e64 v84, v85, -v84, vcc
	v_sub_f32_e32 v84, -0.5, v84
	v_mul_f32_e32 v84, 0x3fb8aa3b, v84
	v_exp_f32_e32 v84, v84
	s_nop 0
	v_mul_f32_e32 v84, 0xbfb8aa3b, v84
	v_exp_f32_e32 v84, v84
	global_store_dword v[66:67], v84, off offset:128
; #define PW(T, off) ((T*)(lndp(p.ws) + (off)))
; DEVI float bf2f(bf16 h) { return __uint_as_float(((unsigned)h) << 16); }
; DEVI float sigmf(float x) { return __builtin_amdgcn_rcpf(1.f + __expf(-x)); }
; DEVI float softplusf(float x) { return x > 20.f ? x : __logf(1.f + __expf(x)); }
; DEVI float tanhfast(float x) { return 1.f - 2.f / (__expf(2.f * x) + 1.f); }
; DEVI int accrow(int r, int lane) { return (r & 3) + 8 * (r >> 2) + 4 * (lane >> 5); }
; template <int EPI>
; DEVI void gemm_epi(const Params& p, const GJob& jb, f32x16 (&acc)[2][2], int rbase, int cbase, int lane) {
;     ...
;   for (int i = 0; i < 2; ++i) {
; #pragma unroll
;     for (int r = 0; r < 16; ++r) {
;       const int row = rbase + i * 32 + accrow(r, lane);
;       if (row < M) {
; #pragma unroll
;         for (int j = 0; j < 2; ++j) {
;           const int col = cbase + j * 32 + (lane & 31);
;           const float v = acc[i][j][r];
;           if (EPI == EPI_SSD_IN) {
;             if (col < 2048) ((bf16*)(ar + S_ZB))[(size_t)row * 2048 + col] = f2bf(v);
;             else if (col < 6144) ((bf16*)(ar + S_XBC))[(size_t)row * 4096 + col - 2048] = f2bf(v);
;             else if (col < 6176) ((float*)(ar + S_DTRAW))[(size_t)row * 32 + col - 6144] = v;
;           } else if (EPI == EPI_RESID) {
;             PW(bf16, W_Z)[(size_t)row * 1024 + col] = f2bf(ALPHA * bf2f(PW(bf16, W_Xb)[(size_t)row * 1024 + col]) + v);
;           } else if (EPI == EPI_GU) {
;             ((bf16*)(ar + F_GU))[(size_t)row * 5632 + col] = f2bf(v);
;           } else if (EPI == EPI_BF16) {
;             ((bf16*)jb.of)[(size_t)row * 1024 + col] = f2bf(v);
;           } else if (EPI == EPI_F32) {
;             jb.of[(size_t)row * 1024 + col] = v;
;           } else if (EPI == EPI_RK_W1) {
;             if (col < 64) ((bf16*)(ar + R_HW))[(size_t)row * 64 + col] = f2bf(tanhfast(v));
;           } else if (EPI == EPI_RK_A1) {
;             if (col < 64) ((bf16*)(ar + R_HA))[(size_t)row * 64 + col] = f2bf(v);
;           } else if (EPI == EPI_RK_G1) {
;             if (col < 192) ((bf16*)(ar + R_HG))[(size_t)row * 192 + col] = f2bf(col < 160 ? sigmf(v) : 0.f);
;           } else if (EPI == EPI_RK_W2) {
;             const float z = i_rk_w0[col] + v;
;             const float wl = -softplusf(-z) - 0.5f;
;             ((float*)(ar + R_W))[(size_t)row * 1024 + col] = __expf(-__expf(wl));
.LBB0_540:
	s_or_b64 exec, exec, s[2:3]
	s_waitcnt vmcnt(2)
	v_or_b32_e32 v84, 26, v69
	v_or_b32_e32 v66, v84, v68
	v_cmp_gt_i32_e32 vcc, s90, v66
	s_and_saveexec_b64 s[2:3], vcc
	s_cbranch_execz .LBB0_542
	v_lshlrev_b64 v[86:87], 2, v[64:65]
	s_waitcnt vmcnt(1)
	v_lshl_add_u64 v[88:89], s[8:9], 0, v[86:87]
	v_mov_b32_e32 v67, v170
	s_mov_b32 s5, 0x3f317217
	s_mov_b32 s18, 0x7f800000
	s_mov_b32 s4, 0xc1a00000
	v_add_f32_e32 v67, v46, v67
	v_mul_f32_e32 v85, 0xbfb8aa3b, v67
	v_exp_f32_e32 v85, v85
	s_nop 0
	v_add_f32_e32 v85, 1.0, v85
	v_cmp_gt_f32_e32 vcc, s69, v85
	s_nop 1
	v_cndmask_b32_e64 v90, 0, 32, vcc
	v_ldexp_f32 v85, v85, v90
	v_log_f32_e32 v85, v85
	v_cndmask_b32_e32 v90, 0, v216, vcc
	v_mul_f32_e32 v91, 0x3f317217, v85
	v_fma_f32 v91, v85, s5, -v91
	v_fmac_f32_e32 v91, 0x3377d1cf, v85
	v_fmac_f32_e32 v91, 0x3f317217, v85
	v_cmp_lt_f32_e64 vcc, |v85|, s18
	s_nop 1
	v_cndmask_b32_e32 v85, v85, v91, vcc
	v_sub_f32_e32 v85, v85, v90
	v_cmp_gt_f32_e32 vcc, s4, v67
	s_nop 1
	v_cndmask_b32_e64 v67, v85, -v67, vcc
	v_sub_f32_e32 v67, -0.5, v67
	v_mul_f32_e32 v67, 0x3fb8aa3b, v67
	v_exp_f32_e32 v85, v67
	v_ashrrev_i32_e32 v67, 31, v66
	v_lshlrev_b64 v[66:67], 12, v[66:67]
	v_lshl_add_u64 v[66:67], s[6:7], 0, v[66:67]
	v_mul_f32_e32 v85, 0xbfb8aa3b, v85
	v_exp_f32_e32 v85, v85
	v_lshl_add_u64 v[66:67], v[66:67], 0, v[86:87]
	global_store_dword v[66:67], v85, off
	v_mov_b32_e32 v85, v171
	v_add_f32_e32 v85, v62, v85
	v_mul_f32_e32 v86, 0xbfb8aa3b, v85
	v_exp_f32_e32 v86, v86
	s_nop 0
	v_add_f32_e32 v86, 1.0, v86
	v_cmp_gt_f32_e32 vcc, s69, v86
	s_nop 1
	v_cndmask_b32_e64 v87, 0, 32, vcc
	v_ldexp_f32 v86, v86, v87
	v_log_f32_e32 v86, v86
	v_cndmask_b32_e32 v87, 0, v216, vcc
	v_mul_f32_e32 v88, 0x3f317217, v86
	v_fma_f32 v88, v86, s5, -v88
	v_fmac_f32_e32 v88, 0x3377d1cf, v86
	v_fmac_f32_e32 v88, 0x3f317217, v86
	v_cmp_lt_f32_e64 vcc, |v86|, s18
	s_nop 1
	v_cndmask_b32_e32 v86, v86, v88, vcc
	v_sub_f32_e32 v86, v86, v87
	v_cmp_gt_f32_e32 vcc, s4, v85
	s_nop 1
	v_cndmask_b32_e64 v85, v86, -v85, vcc
	v_sub_f32_e32 v85, -0.5, v85
	v_mul_f32_e32 v85, 0x3fb8aa3b, v85
	v_exp_f32_e32 v85, v85
	s_nop 0
	v_mul_f32_e32 v85, 0xbfb8aa3b, v85
	v_exp_f32_e32 v85, v85
	global_store_dword v[66:67], v85, off offset:128
.LBB0_542:
	s_or_b64 exec, exec, s[2:3]
	v_or_b32_e32 v85, 27, v70
	v_or_b32_e32 v66, v68, v85
	v_cmp_gt_i32_e32 vcc, s90, v66
	s_and_saveexec_b64 s[2:3], vcc
	s_cbranch_execz .LBB0_544
	v_lshlrev_b64 v[86:87], 2, v[64:65]
	s_waitcnt vmcnt(1)
	v_lshl_add_u64 v[88:89], s[8:9], 0, v[86:87]
	v_mov_b32_e32 v67, v170
	s_mov_b32 s5, 0x3f317217
	s_mov_b32 s18, 0x7f800000
	s_mov_b32 s4, 0xc1a00000
	v_add_f32_e32 v67, v47, v67
	v_mul_f32_e32 v90, 0xbfb8aa3b, v67
	v_exp_f32_e32 v90, v90
	s_nop 0
	v_add_f32_e32 v90, 1.0, v90
	v_cmp_gt_f32_e32 vcc, s69, v90
	s_nop 1
	v_cndmask_b32_e64 v91, 0, 32, vcc
	v_ldexp_f32 v90, v90, v91
	v_log_f32_e32 v90, v90
	v_cndmask_b32_e32 v91, 0, v216, vcc
	v_mul_f32_e32 v92, 0x3f317217, v90
	v_fma_f32 v92, v90, s5, -v92
	v_fmac_f32_e32 v92, 0x3377d1cf, v90
	v_fmac_f32_e32 v92, 0x3f317217, v90
	v_cmp_lt_f32_e64 vcc, |v90|, s18
	s_nop 1
	v_cndmask_b32_e32 v90, v90, v92, vcc
	v_sub_f32_e32 v90, v90, v91
	v_cmp_gt_f32_e32 vcc, s4, v67
	s_nop 1
	v_cndmask_b32_e64 v67, v90, -v67, vcc
	v_sub_f32_e32 v67, -0.5, v67
	v_mul_f32_e32 v67, 0x3fb8aa3b, v67
	v_exp_f32_e32 v90, v67
	v_ashrrev_i32_e32 v67, 31, v66
	v_lshlrev_b64 v[66:67], 12, v[66:67]
	v_lshl_add_u64 v[66:67], s[6:7], 0, v[66:67]
	v_mul_f32_e32 v90, 0xbfb8aa3b, v90
	v_exp_f32_e32 v90, v90
	v_lshl_add_u64 v[66:67], v[66:67], 0, v[86:87]
	global_store_dword v[66:67], v90, off
	v_mov_b32_e32 v86, v171
	v_add_f32_e32 v86, v63, v86
	v_mul_f32_e32 v87, 0xbfb8aa3b, v86
	v_exp_f32_e32 v87, v87
	s_nop 0
	v_add_f32_e32 v87, 1.0, v87
	v_cmp_gt_f32_e32 vcc, s69, v87
	s_nop 1
	v_cndmask_b32_e64 v88, 0, 32, vcc
	v_ldexp_f32 v87, v87, v88
	v_log_f32_e32 v87, v87
	v_cndmask_b32_e32 v88, 0, v216, vcc
	v_mul_f32_e32 v89, 0x3f317217, v87
	v_fma_f32 v89, v87, s5, -v89
	v_fmac_f32_e32 v89, 0x3377d1cf, v87
	v_fmac_f32_e32 v89, 0x3f317217, v87
	v_cmp_lt_f32_e64 vcc, |v87|, s18
	s_nop 1
	v_cndmask_b32_e32 v87, v87, v89, vcc
	v_sub_f32_e32 v87, v87, v88
	v_cmp_gt_f32_e32 vcc, s4, v86
	s_nop 1
	v_cndmask_b32_e64 v86, v87, -v86, vcc
	v_sub_f32_e32 v86, -0.5, v86
	v_mul_f32_e32 v86, 0x3fb8aa3b, v86
	v_exp_f32_e32 v86, v86
	s_nop 0
	v_mul_f32_e32 v86, 0xbfb8aa3b, v86
	v_exp_f32_e32 v86, v86
	global_store_dword v[66:67], v86, off offset:128
.LBB0_544:
	s_or_b64 exec, exec, s[2:3]
	v_or_b32_e32 v86, 32, v68
	v_or_b32_e32 v66, v86, v69
	v_cmp_gt_i32_e32 vcc, s90, v66
	s_and_saveexec_b64 s[2:3], vcc
	s_cbranch_execz .LBB0_546
	s_waitcnt vmcnt(1)
	v_lshlrev_b64 v[88:89], 2, v[64:65]
	v_lshl_add_u64 v[90:91], s[8:9], 0, v[88:89]
	v_mov_b32_e32 v67, v170
	s_mov_b32 s5, 0x3f317217
	s_mov_b32 s18, 0x7f800000
	s_mov_b32 s4, 0xc1a00000
	v_add_f32_e32 v67, v16, v67
	v_mul_f32_e32 v87, 0xbfb8aa3b, v67
	v_exp_f32_e32 v87, v87
	s_nop 0
	v_add_f32_e32 v87, 1.0, v87
	v_cmp_gt_f32_e32 vcc, s69, v87
	s_nop 1
	v_cndmask_b32_e64 v92, 0, 32, vcc
	v_ldexp_f32 v87, v87, v92
	v_log_f32_e32 v87, v87
	v_cndmask_b32_e32 v92, 0, v216, vcc
	v_mul_f32_e32 v93, 0x3f317217, v87
	v_fma_f32 v93, v87, s5, -v93
	v_fmac_f32_e32 v93, 0x3377d1cf, v87
	v_fmac_f32_e32 v93, 0x3f317217, v87
	v_cmp_lt_f32_e64 vcc, |v87|, s18
	s_nop 1
	v_cndmask_b32_e32 v87, v87, v93, vcc
	v_sub_f32_e32 v87, v87, v92
	v_cmp_gt_f32_e32 vcc, s4, v67
	s_nop 1
	v_cndmask_b32_e64 v67, v87, -v67, vcc
	v_sub_f32_e32 v67, -0.5, v67
	v_mul_f32_e32 v67, 0x3fb8aa3b, v67
	v_exp_f32_e32 v87, v67
	v_ashrrev_i32_e32 v67, 31, v66
	v_lshlrev_b64 v[66:67], 12, v[66:67]
	v_lshl_add_u64 v[66:67], s[6:7], 0, v[66:67]
	v_mul_f32_e32 v87, 0xbfb8aa3b, v87
	v_exp_f32_e32 v87, v87
	v_lshl_add_u64 v[66:67], v[66:67], 0, v[88:89]
	global_store_dword v[66:67], v87, off
	v_mov_b32_e32 v87, v171
	v_add_f32_e32 v87, v0, v87
	v_mul_f32_e32 v88, 0xbfb8aa3b, v87
	v_exp_f32_e32 v88, v88
	s_nop 0
	v_add_f32_e32 v88, 1.0, v88
	v_cmp_gt_f32_e32 vcc, s69, v88
	s_nop 1
	v_cndmask_b32_e64 v89, 0, 32, vcc
	v_ldexp_f32 v88, v88, v89
	v_log_f32_e32 v88, v88
	v_cndmask_b32_e32 v89, 0, v216, vcc
	v_mul_f32_e32 v90, 0x3f317217, v88
	v_fma_f32 v90, v88, s5, -v90
	v_fmac_f32_e32 v90, 0x3377d1cf, v88
	v_fmac_f32_e32 v90, 0x3f317217, v88
	v_cmp_lt_f32_e64 vcc, |v88|, s18
	s_nop 1
	v_cndmask_b32_e32 v88, v88, v90, vcc
	v_sub_f32_e32 v88, v88, v89
	v_cmp_gt_f32_e32 vcc, s4, v87
	s_nop 1
	v_cndmask_b32_e64 v87, v88, -v87, vcc
	v_sub_f32_e32 v87, -0.5, v87
	v_mul_f32_e32 v87, 0x3fb8aa3b, v87
	v_exp_f32_e32 v87, v87
	s_nop 0
	v_mul_f32_e32 v87, 0xbfb8aa3b, v87
	v_exp_f32_e32 v87, v87
	global_store_dword v[66:67], v87, off offset:128
; #define PW(T, off) ((T*)(lndp(p.ws) + (off)))
; DEVI float bf2f(bf16 h) { return __uint_as_float(((unsigned)h) << 16); }
; DEVI float sigmf(float x) { return __builtin_amdgcn_rcpf(1.f + __expf(-x)); }
; DEVI float softplusf(float x) { return x > 20.f ? x : __logf(1.f + __expf(x)); }
; DEVI float tanhfast(float x) { return 1.f - 2.f / (__expf(2.f * x) + 1.f); }
; DEVI int accrow(int r, int lane) { return (r & 3) + 8 * (r >> 2) + 4 * (lane >> 5); }
; template <int EPI>
; DEVI void gemm_epi(const Params& p, const GJob& jb, f32x16 (&acc)[2][2], int rbase, int cbase, int lane) {
;     ...
;   for (int i = 0; i < 2; ++i) {
; #pragma unroll
;     for (int r = 0; r < 16; ++r) {
;       const int row = rbase + i * 32 + accrow(r, lane);
;       if (row < M) {
; #pragma unroll
;         for (int j = 0; j < 2; ++j) {
;           const int col = cbase + j * 32 + (lane & 31);
;           const float v = acc[i][j][r];
;           if (EPI == EPI_SSD_IN) {
;             if (col < 2048) ((bf16*)(ar + S_ZB))[(size_t)row * 2048 + col] = f2bf(v);
;             else if (col < 6144) ((bf16*)(ar + S_XBC))[(size_t)row * 4096 + col - 2048] = f2bf(v);
;             else if (col < 6176) ((float*)(ar + S_DTRAW))[(size_t)row * 32 + col - 6144] = v;
;           } else if (EPI == EPI_RESID) {
;             PW(bf16, W_Z)[(size_t)row * 1024 + col] = f2bf(ALPHA * bf2f(PW(bf16, W_Xb)[(size_t)row * 1024 + col]) + v);
;           } else if (EPI == EPI_GU) {
;             ((bf16*)(ar + F_GU))[(size_t)row * 5632 + col] = f2bf(v);
;           } else if (EPI == EPI_BF16) {
;             ((bf16*)jb.of)[(size_t)row * 1024 + col] = f2bf(v);
;           } else if (EPI == EPI_F32) {
;             jb.of[(size_t)row * 1024 + col] = v;
;           } else if (EPI == EPI_RK_W1) {
;             if (col < 64) ((bf16*)(ar + R_HW))[(size_t)row * 64 + col] = f2bf(tanhfast(v));
;           } else if (EPI == EPI_RK_A1) {
;             if (col < 64) ((bf16*)(ar + R_HA))[(size_t)row * 64 + col] = f2bf(v);
;           } else if (EPI == EPI_RK_G1) {
;             if (col < 192) ((bf16*)(ar + R_HG))[(size_t)row * 192 + col] = f2bf(col < 160 ? sigmf(v) : 0.f);
;           } else if (EPI == EPI_RK_W2) {
;             const float z = i_rk_w0[col] + v;
;             const float wl = -softplusf(-z) - 0.5f;
;             ((float*)(ar + R_W))[(size_t)row * 1024 + col] = __expf(-__expf(wl));
.LBB0_546:
	s_or_b64 exec, exec, s[2:3]
	v_or_b32_e32 v66, v86, v71
	v_cmp_gt_i32_e32 vcc, s90, v66
	s_and_saveexec_b64 s[2:3], vcc
	s_cbranch_execz .LBB0_548
	s_waitcnt vmcnt(1)
	v_lshlrev_b64 v[88:89], 2, v[64:65]
	v_lshl_add_u64 v[90:91], s[8:9], 0, v[88:89]
	v_mov_b32_e32 v67, v170
	s_mov_b32 s5, 0x3f317217
	s_mov_b32 s18, 0x7f800000
	s_mov_b32 s4, 0xc1a00000
	v_add_f32_e32 v67, v17, v67
	v_mul_f32_e32 v71, 0xbfb8aa3b, v67
	v_exp_f32_e32 v71, v71
	s_nop 0
	v_add_f32_e32 v71, 1.0, v71
	v_cmp_gt_f32_e32 vcc, s69, v71
	s_nop 1
	v_cndmask_b32_e64 v87, 0, 32, vcc
	v_ldexp_f32 v71, v71, v87
	v_log_f32_e32 v71, v71
	v_cndmask_b32_e32 v87, 0, v216, vcc
	v_mul_f32_e32 v92, 0x3f317217, v71
	v_fma_f32 v92, v71, s5, -v92
	v_fmac_f32_e32 v92, 0x3377d1cf, v71
	v_fmac_f32_e32 v92, 0x3f317217, v71
	v_cmp_lt_f32_e64 vcc, |v71|, s18
	s_nop 1
	v_cndmask_b32_e32 v71, v71, v92, vcc
	v_sub_f32_e32 v71, v71, v87
	v_cmp_gt_f32_e32 vcc, s4, v67
	s_nop 1
	v_cndmask_b32_e64 v67, v71, -v67, vcc
	v_sub_f32_e32 v67, -0.5, v67
	v_mul_f32_e32 v67, 0x3fb8aa3b, v67
	v_exp_f32_e32 v71, v67
	v_ashrrev_i32_e32 v67, 31, v66
	v_lshlrev_b64 v[66:67], 12, v[66:67]
	v_lshl_add_u64 v[66:67], s[6:7], 0, v[66:67]
	v_mul_f32_e32 v71, 0xbfb8aa3b, v71
	v_exp_f32_e32 v71, v71
	v_lshl_add_u64 v[66:67], v[66:67], 0, v[88:89]
	global_store_dword v[66:67], v71, off
	v_mov_b32_e32 v71, v171
	v_add_f32_e32 v71, v1, v71
	v_mul_f32_e32 v87, 0xbfb8aa3b, v71
	v_exp_f32_e32 v87, v87
	s_nop 0
	v_add_f32_e32 v87, 1.0, v87
	v_cmp_gt_f32_e32 vcc, s69, v87
	s_nop 1
	v_cndmask_b32_e64 v88, 0, 32, vcc
	v_ldexp_f32 v87, v87, v88
	v_log_f32_e32 v87, v87
	v_cndmask_b32_e32 v88, 0, v216, vcc
	v_mul_f32_e32 v89, 0x3f317217, v87
	v_fma_f32 v89, v87, s5, -v89
	v_fmac_f32_e32 v89, 0x3377d1cf, v87
	v_fmac_f32_e32 v89, 0x3f317217, v87
	v_cmp_lt_f32_e64 vcc, |v87|, s18
	s_nop 1
	v_cndmask_b32_e32 v87, v87, v89, vcc
	v_sub_f32_e32 v87, v87, v88
	v_cmp_gt_f32_e32 vcc, s4, v71
	s_nop 1
	v_cndmask_b32_e64 v71, v87, -v71, vcc
	v_sub_f32_e32 v71, -0.5, v71
	v_mul_f32_e32 v71, 0x3fb8aa3b, v71
	v_exp_f32_e32 v71, v71
	s_nop 0
	v_mul_f32_e32 v71, 0xbfb8aa3b, v71
	v_exp_f32_e32 v71, v71
	global_store_dword v[66:67], v71, off offset:128
.LBB0_548:
	s_or_b64 exec, exec, s[2:3]
	v_or_b32_e32 v66, v86, v72
	v_cmp_gt_i32_e32 vcc, s90, v66
	s_and_saveexec_b64 s[2:3], vcc
	s_cbranch_execz .LBB0_550
	s_waitcnt vmcnt(1)
	v_lshlrev_b64 v[88:89], 2, v[64:65]
	v_lshl_add_u64 v[90:91], s[8:9], 0, v[88:89]
	v_mov_b32_e32 v67, v170
	s_mov_b32 s5, 0x3f317217
	s_mov_b32 s18, 0x7f800000
	s_mov_b32 s4, 0xc1a00000
	v_add_f32_e32 v67, v18, v67
	v_mul_f32_e32 v71, 0xbfb8aa3b, v67
	v_exp_f32_e32 v71, v71
	s_nop 0
	v_add_f32_e32 v71, 1.0, v71
	v_cmp_gt_f32_e32 vcc, s69, v71
	s_nop 1
	v_cndmask_b32_e64 v72, 0, 32, vcc
	v_ldexp_f32 v71, v71, v72
	v_log_f32_e32 v71, v71
	v_cndmask_b32_e32 v72, 0, v216, vcc
	v_mul_f32_e32 v87, 0x3f317217, v71
	v_fma_f32 v87, v71, s5, -v87
	v_fmac_f32_e32 v87, 0x3377d1cf, v71
	v_fmac_f32_e32 v87, 0x3f317217, v71
	v_cmp_lt_f32_e64 vcc, |v71|, s18
	s_nop 1
	v_cndmask_b32_e32 v71, v71, v87, vcc
	v_sub_f32_e32 v71, v71, v72
	v_cmp_gt_f32_e32 vcc, s4, v67
	s_nop 1
	v_cndmask_b32_e64 v67, v71, -v67, vcc
	v_sub_f32_e32 v67, -0.5, v67
	v_mul_f32_e32 v67, 0x3fb8aa3b, v67
	v_exp_f32_e32 v71, v67
	v_ashrrev_i32_e32 v67, 31, v66
	v_lshlrev_b64 v[66:67], 12, v[66:67]
	v_lshl_add_u64 v[66:67], s[6:7], 0, v[66:67]
	v_mul_f32_e32 v71, 0xbfb8aa3b, v71
	v_exp_f32_e32 v71, v71
	v_lshl_add_u64 v[66:67], v[66:67], 0, v[88:89]
	global_store_dword v[66:67], v71, off
	v_mov_b32_e32 v71, v171
	v_add_f32_e32 v71, v2, v71
	v_mul_f32_e32 v72, 0xbfb8aa3b, v71
	v_exp_f32_e32 v72, v72
	s_nop 0
	v_add_f32_e32 v72, 1.0, v72
	v_cmp_gt_f32_e32 vcc, s69, v72
	s_nop 1
	v_cndmask_b32_e64 v87, 0, 32, vcc
	v_ldexp_f32 v72, v72, v87
	v_log_f32_e32 v72, v72
	v_cndmask_b32_e32 v87, 0, v216, vcc
	v_mul_f32_e32 v88, 0x3f317217, v72
	v_fma_f32 v88, v72, s5, -v88
	v_fmac_f32_e32 v88, 0x3377d1cf, v72
	v_fmac_f32_e32 v88, 0x3f317217, v72
	v_cmp_lt_f32_e64 vcc, |v72|, s18
	s_nop 1
	v_cndmask_b32_e32 v72, v72, v88, vcc
	v_sub_f32_e32 v72, v72, v87
	v_cmp_gt_f32_e32 vcc, s4, v71
	s_nop 1
	v_cndmask_b32_e64 v71, v72, -v71, vcc
	v_sub_f32_e32 v71, -0.5, v71
	v_mul_f32_e32 v71, 0x3fb8aa3b, v71
	v_exp_f32_e32 v71, v71
	s_nop 0
	v_mul_f32_e32 v71, 0xbfb8aa3b, v71
	v_exp_f32_e32 v71, v71
	global_store_dword v[66:67], v71, off offset:128
.LBB0_550:
	s_or_b64 exec, exec, s[2:3]
	v_or_b32_e32 v66, v86, v73
	v_cmp_gt_i32_e32 vcc, s90, v66
	s_and_saveexec_b64 s[2:3], vcc
	s_cbranch_execz .LBB0_552
	v_lshlrev_b64 v[72:73], 2, v[64:65]
	s_waitcnt vmcnt(1)
	v_lshl_add_u64 v[88:89], s[8:9], 0, v[72:73]
	v_mov_b32_e32 v67, v170
	s_mov_b32 s5, 0x3f317217
	s_mov_b32 s18, 0x7f800000
	s_mov_b32 s4, 0xc1a00000
	v_add_f32_e32 v67, v19, v67
	v_mul_f32_e32 v71, 0xbfb8aa3b, v67
	v_exp_f32_e32 v71, v71
	s_nop 0
	v_add_f32_e32 v71, 1.0, v71
	v_cmp_gt_f32_e32 vcc, s69, v71
	s_nop 1
	v_cndmask_b32_e64 v87, 0, 32, vcc
	v_ldexp_f32 v71, v71, v87
	v_log_f32_e32 v71, v71
	v_cndmask_b32_e32 v87, 0, v216, vcc
	v_mul_f32_e32 v90, 0x3f317217, v71
	v_fma_f32 v90, v71, s5, -v90
	v_fmac_f32_e32 v90, 0x3377d1cf, v71
	v_fmac_f32_e32 v90, 0x3f317217, v71
	v_cmp_lt_f32_e64 vcc, |v71|, s18
	s_nop 1
	v_cndmask_b32_e32 v71, v71, v90, vcc
	v_sub_f32_e32 v71, v71, v87
	v_cmp_gt_f32_e32 vcc, s4, v67
	s_nop 1
	v_cndmask_b32_e64 v67, v71, -v67, vcc
	v_sub_f32_e32 v67, -0.5, v67
	v_mul_f32_e32 v67, 0x3fb8aa3b, v67
	v_exp_f32_e32 v71, v67
	v_ashrrev_i32_e32 v67, 31, v66
	v_lshlrev_b64 v[66:67], 12, v[66:67]
	v_lshl_add_u64 v[66:67], s[6:7], 0, v[66:67]
	v_mul_f32_e32 v71, 0xbfb8aa3b, v71
	v_exp_f32_e32 v71, v71
	v_lshl_add_u64 v[66:67], v[66:67], 0, v[72:73]
	global_store_dword v[66:67], v71, off
	v_mov_b32_e32 v71, v171
	v_add_f32_e32 v71, v3, v71
	v_mul_f32_e32 v72, 0xbfb8aa3b, v71
	v_exp_f32_e32 v72, v72
	s_nop 0
	v_add_f32_e32 v72, 1.0, v72
	v_cmp_gt_f32_e32 vcc, s69, v72
	s_nop 1
	v_cndmask_b32_e64 v73, 0, 32, vcc
	v_ldexp_f32 v72, v72, v73
	v_log_f32_e32 v72, v72
	v_cndmask_b32_e32 v73, 0, v216, vcc
	v_mul_f32_e32 v87, 0x3f317217, v72
	v_fma_f32 v87, v72, s5, -v87
	v_fmac_f32_e32 v87, 0x3377d1cf, v72
	v_fmac_f32_e32 v87, 0x3f317217, v72
	v_cmp_lt_f32_e64 vcc, |v72|, s18
	s_nop 1
	v_cndmask_b32_e32 v72, v72, v87, vcc
	v_sub_f32_e32 v72, v72, v73
	v_cmp_gt_f32_e32 vcc, s4, v71
	s_nop 1
	v_cndmask_b32_e64 v71, v72, -v71, vcc
	v_sub_f32_e32 v71, -0.5, v71
	v_mul_f32_e32 v71, 0x3fb8aa3b, v71
	v_exp_f32_e32 v71, v71
	s_nop 0
	v_mul_f32_e32 v71, 0xbfb8aa3b, v71
	v_exp_f32_e32 v71, v71
	global_store_dword v[66:67], v71, off offset:128
; #define PW(T, off) ((T*)(lndp(p.ws) + (off)))
; DEVI float bf2f(bf16 h) { return __uint_as_float(((unsigned)h) << 16); }
; DEVI float sigmf(float x) { return __builtin_amdgcn_rcpf(1.f + __expf(-x)); }
; DEVI float softplusf(float x) { return x > 20.f ? x : __logf(1.f + __expf(x)); }
; DEVI float tanhfast(float x) { return 1.f - 2.f / (__expf(2.f * x) + 1.f); }
; DEVI int accrow(int r, int lane) { return (r & 3) + 8 * (r >> 2) + 4 * (lane >> 5); }
; template <int EPI>
; DEVI void gemm_epi(const Params& p, const GJob& jb, f32x16 (&acc)[2][2], int rbase, int cbase, int lane) {
;     ...
;   for (int i = 0; i < 2; ++i) {
; #pragma unroll
;     for (int r = 0; r < 16; ++r) {
;       const int row = rbase + i * 32 + accrow(r, lane);
;       if (row < M) {
; #pragma unroll
;         for (int j = 0; j < 2; ++j) {
;           const int col = cbase + j * 32 + (lane & 31);
;           const float v = acc[i][j][r];
;           if (EPI == EPI_SSD_IN) {
;             if (col < 2048) ((bf16*)(ar + S_ZB))[(size_t)row * 2048 + col] = f2bf(v);
;             else if (col < 6144) ((bf16*)(ar + S_XBC))[(size_t)row * 4096 + col - 2048] = f2bf(v);
;             else if (col < 6176) ((float*)(ar + S_DTRAW))[(size_t)row * 32 + col - 6144] = v;
;           } else if (EPI == EPI_RESID) {
;             PW(bf16, W_Z)[(size_t)row * 1024 + col] = f2bf(ALPHA * bf2f(PW(bf16, W_Xb)[(size_t)row * 1024 + col]) + v);
;           } else if (EPI == EPI_GU) {
;             ((bf16*)(ar + F_GU))[(size_t)row * 5632 + col] = f2bf(v);
;           } else if (EPI == EPI_BF16) {
;             ((bf16*)jb.of)[(size_t)row * 1024 + col] = f2bf(v);
;           } else if (EPI == EPI_F32) {
;             jb.of[(size_t)row * 1024 + col] = v;
;           } else if (EPI == EPI_RK_W1) {
;             if (col < 64) ((bf16*)(ar + R_HW))[(size_t)row * 64 + col] = f2bf(tanhfast(v));
;           } else if (EPI == EPI_RK_A1) {
;             if (col < 64) ((bf16*)(ar + R_HA))[(size_t)row * 64 + col] = f2bf(v);
;           } else if (EPI == EPI_RK_G1) {
;             if (col < 192) ((bf16*)(ar + R_HG))[(size_t)row * 192 + col] = f2bf(col < 160 ? sigmf(v) : 0.f);
;           } else if (EPI == EPI_RK_W2) {
;             const float z = i_rk_w0[col] + v;
;             const float wl = -softplusf(-z) - 0.5f;
;             ((float*)(ar + R_W))[(size_t)row * 1024 + col] = __expf(-__expf(wl));
.LBB0_552:
	s_or_b64 exec, exec, s[2:3]
	v_or_b32_e32 v66, v86, v74
	v_cmp_gt_i32_e32 vcc, s90, v66
	s_and_saveexec_b64 s[2:3], vcc
	s_cbranch_execz .LBB0_554
	v_lshlrev_b64 v[72:73], 2, v[64:65]
	s_waitcnt vmcnt(1)
	v_lshl_add_u64 v[88:89], s[8:9], 0, v[72:73]
	v_mov_b32_e32 v67, v170
	s_mov_b32 s5, 0x3f317217
	s_mov_b32 s18, 0x7f800000
	s_mov_b32 s4, 0xc1a00000
	v_add_f32_e32 v67, v20, v67
	v_mul_f32_e32 v71, 0xbfb8aa3b, v67
	v_exp_f32_e32 v71, v71
	s_nop 0
	v_add_f32_e32 v71, 1.0, v71
	v_cmp_gt_f32_e32 vcc, s69, v71
	s_nop 1
	v_cndmask_b32_e64 v74, 0, 32, vcc
	v_ldexp_f32 v71, v71, v74
	v_log_f32_e32 v71, v71
	v_cndmask_b32_e32 v74, 0, v216, vcc
	v_mul_f32_e32 v87, 0x3f317217, v71
	v_fma_f32 v87, v71, s5, -v87
	v_fmac_f32_e32 v87, 0x3377d1cf, v71
	v_fmac_f32_e32 v87, 0x3f317217, v71
	v_cmp_lt_f32_e64 vcc, |v71|, s18
	s_nop 1
	v_cndmask_b32_e32 v71, v71, v87, vcc
	v_sub_f32_e32 v71, v71, v74
	v_cmp_gt_f32_e32 vcc, s4, v67
	s_nop 1
	v_cndmask_b32_e64 v67, v71, -v67, vcc
	v_sub_f32_e32 v67, -0.5, v67
	v_mul_f32_e32 v67, 0x3fb8aa3b, v67
	v_exp_f32_e32 v71, v67
	v_ashrrev_i32_e32 v67, 31, v66
	v_lshlrev_b64 v[66:67], 12, v[66:67]
	v_lshl_add_u64 v[66:67], s[6:7], 0, v[66:67]
	v_mul_f32_e32 v71, 0xbfb8aa3b, v71
	v_exp_f32_e32 v71, v71
	v_lshl_add_u64 v[66:67], v[66:67], 0, v[72:73]
	global_store_dword v[66:67], v71, off
	v_mov_b32_e32 v71, v171
	v_add_f32_e32 v71, v4, v71
	v_mul_f32_e32 v72, 0xbfb8aa3b, v71
	v_exp_f32_e32 v72, v72
	s_nop 0
	v_add_f32_e32 v72, 1.0, v72
	v_cmp_gt_f32_e32 vcc, s69, v72
	s_nop 1
	v_cndmask_b32_e64 v73, 0, 32, vcc
	v_ldexp_f32 v72, v72, v73
	v_log_f32_e32 v72, v72
	v_cndmask_b32_e32 v73, 0, v216, vcc
	v_mul_f32_e32 v74, 0x3f317217, v72
	v_fma_f32 v74, v72, s5, -v74
	v_fmac_f32_e32 v74, 0x3377d1cf, v72
	v_fmac_f32_e32 v74, 0x3f317217, v72
	v_cmp_lt_f32_e64 vcc, |v72|, s18
	s_nop 1
	v_cndmask_b32_e32 v72, v72, v74, vcc
	v_sub_f32_e32 v72, v72, v73
	v_cmp_gt_f32_e32 vcc, s4, v71
	s_nop 1
	v_cndmask_b32_e64 v71, v72, -v71, vcc
	v_sub_f32_e32 v71, -0.5, v71
	v_mul_f32_e32 v71, 0x3fb8aa3b, v71
	v_exp_f32_e32 v71, v71
	s_nop 0
	v_mul_f32_e32 v71, 0xbfb8aa3b, v71
	v_exp_f32_e32 v71, v71
	global_store_dword v[66:67], v71, off offset:128
.LBB0_554:
	s_or_b64 exec, exec, s[2:3]
	v_or_b32_e32 v66, v86, v75
	v_cmp_gt_i32_e32 vcc, s90, v66
	s_and_saveexec_b64 s[2:3], vcc
	s_cbranch_execz .LBB0_556
	v_lshlrev_b64 v[72:73], 2, v[64:65]
	v_lshl_add_u64 v[74:75], s[8:9], 0, v[72:73]
	v_mov_b32_e32 v67, v170
	s_mov_b32 s5, 0x3f317217
	s_mov_b32 s18, 0x7f800000
	s_mov_b32 s4, 0xc1a00000
	v_add_f32_e32 v67, v21, v67
	v_mul_f32_e32 v71, 0xbfb8aa3b, v67
	v_exp_f32_e32 v71, v71
	s_nop 0
	v_add_f32_e32 v71, 1.0, v71
	v_cmp_gt_f32_e32 vcc, s69, v71
	s_nop 1
	v_cndmask_b32_e64 v87, 0, 32, vcc
	v_ldexp_f32 v71, v71, v87
	v_log_f32_e32 v71, v71
	v_cndmask_b32_e32 v87, 0, v216, vcc
	v_mul_f32_e32 v88, 0x3f317217, v71
	v_fma_f32 v88, v71, s5, -v88
	v_fmac_f32_e32 v88, 0x3377d1cf, v71
	v_fmac_f32_e32 v88, 0x3f317217, v71
	v_cmp_lt_f32_e64 vcc, |v71|, s18
	s_nop 1
	v_cndmask_b32_e32 v71, v71, v88, vcc
	v_sub_f32_e32 v71, v71, v87
	v_cmp_gt_f32_e32 vcc, s4, v67
	s_nop 1
	v_cndmask_b32_e64 v67, v71, -v67, vcc
	v_sub_f32_e32 v67, -0.5, v67
	v_mul_f32_e32 v67, 0x3fb8aa3b, v67
	v_exp_f32_e32 v71, v67
	v_ashrrev_i32_e32 v67, 31, v66
	v_lshlrev_b64 v[66:67], 12, v[66:67]
	v_lshl_add_u64 v[66:67], s[6:7], 0, v[66:67]
	v_mul_f32_e32 v71, 0xbfb8aa3b, v71
	v_exp_f32_e32 v71, v71
	v_lshl_add_u64 v[66:67], v[66:67], 0, v[72:73]
	global_store_dword v[66:67], v71, off
	v_mov_b32_e32 v71, v171
	v_add_f32_e32 v71, v5, v71
	v_mul_f32_e32 v72, 0xbfb8aa3b, v71
	v_exp_f32_e32 v72, v72
	s_nop 0
	v_add_f32_e32 v72, 1.0, v72
	v_cmp_gt_f32_e32 vcc, s69, v72
	s_nop 1
	v_cndmask_b32_e64 v73, 0, 32, vcc
	v_ldexp_f32 v72, v72, v73
	v_log_f32_e32 v72, v72
	v_cndmask_b32_e32 v73, 0, v216, vcc
	v_mul_f32_e32 v74, 0x3f317217, v72
	v_fma_f32 v74, v72, s5, -v74
	v_fmac_f32_e32 v74, 0x3377d1cf, v72
	v_fmac_f32_e32 v74, 0x3f317217, v72
	v_cmp_lt_f32_e64 vcc, |v72|, s18
	s_nop 1
	v_cndmask_b32_e32 v72, v72, v74, vcc
	v_sub_f32_e32 v72, v72, v73
	v_cmp_gt_f32_e32 vcc, s4, v71
	s_nop 1
	v_cndmask_b32_e64 v71, v72, -v71, vcc
	v_sub_f32_e32 v71, -0.5, v71
	v_mul_f32_e32 v71, 0x3fb8aa3b, v71
	v_exp_f32_e32 v71, v71
	s_nop 0
	v_mul_f32_e32 v71, 0xbfb8aa3b, v71
	v_exp_f32_e32 v71, v71
	global_store_dword v[66:67], v71, off offset:128
.LBB0_556:
	s_or_b64 exec, exec, s[2:3]
	v_or_b32_e32 v66, v86, v76
	v_cmp_gt_i32_e32 vcc, s90, v66
	s_and_saveexec_b64 s[2:3], vcc
	s_cbranch_execz .LBB0_558
	v_lshlrev_b64 v[72:73], 2, v[64:65]
	v_lshl_add_u64 v[74:75], s[8:9], 0, v[72:73]
	v_mov_b32_e32 v67, v170
	s_mov_b32 s5, 0x3f317217
	s_mov_b32 s18, 0x7f800000
	s_mov_b32 s4, 0xc1a00000
	v_add_f32_e32 v67, v22, v67
	v_mul_f32_e32 v71, 0xbfb8aa3b, v67
	v_exp_f32_e32 v71, v71
	s_nop 0
	v_add_f32_e32 v71, 1.0, v71
	v_cmp_gt_f32_e32 vcc, s69, v71
	s_nop 1
	v_cndmask_b32_e64 v76, 0, 32, vcc
	v_ldexp_f32 v71, v71, v76
	v_log_f32_e32 v71, v71
	v_cndmask_b32_e32 v76, 0, v216, vcc
	v_mul_f32_e32 v87, 0x3f317217, v71
	v_fma_f32 v87, v71, s5, -v87
	v_fmac_f32_e32 v87, 0x3377d1cf, v71
	v_fmac_f32_e32 v87, 0x3f317217, v71
	v_cmp_lt_f32_e64 vcc, |v71|, s18
	s_nop 1
	v_cndmask_b32_e32 v71, v71, v87, vcc
	v_sub_f32_e32 v71, v71, v76
	v_cmp_gt_f32_e32 vcc, s4, v67
	s_nop 1
	v_cndmask_b32_e64 v67, v71, -v67, vcc
	v_sub_f32_e32 v67, -0.5, v67
	v_mul_f32_e32 v67, 0x3fb8aa3b, v67
	v_exp_f32_e32 v71, v67
	v_ashrrev_i32_e32 v67, 31, v66
	v_lshlrev_b64 v[66:67], 12, v[66:67]
	v_lshl_add_u64 v[66:67], s[6:7], 0, v[66:67]
	v_mul_f32_e32 v71, 0xbfb8aa3b, v71
	v_exp_f32_e32 v71, v71
	v_lshl_add_u64 v[66:67], v[66:67], 0, v[72:73]
	global_store_dword v[66:67], v71, off
	v_mov_b32_e32 v71, v171
	v_add_f32_e32 v71, v6, v71
	v_mul_f32_e32 v72, 0xbfb8aa3b, v71
	v_exp_f32_e32 v72, v72
	s_nop 0
	v_add_f32_e32 v72, 1.0, v72
	v_cmp_gt_f32_e32 vcc, s69, v72
	s_nop 1
	v_cndmask_b32_e64 v73, 0, 32, vcc
	v_ldexp_f32 v72, v72, v73
	v_log_f32_e32 v72, v72
	v_cndmask_b32_e32 v73, 0, v216, vcc
	v_mul_f32_e32 v74, 0x3f317217, v72
	v_fma_f32 v74, v72, s5, -v74
	v_fmac_f32_e32 v74, 0x3377d1cf, v72
	v_fmac_f32_e32 v74, 0x3f317217, v72
	v_cmp_lt_f32_e64 vcc, |v72|, s18
	s_nop 1
	v_cndmask_b32_e32 v72, v72, v74, vcc
	v_sub_f32_e32 v72, v72, v73
	v_cmp_gt_f32_e32 vcc, s4, v71
	s_nop 1
	v_cndmask_b32_e64 v71, v72, -v71, vcc
	v_sub_f32_e32 v71, -0.5, v71
	v_mul_f32_e32 v71, 0x3fb8aa3b, v71
	v_exp_f32_e32 v71, v71
	s_nop 0
	v_mul_f32_e32 v71, 0xbfb8aa3b, v71
	v_exp_f32_e32 v71, v71
	global_store_dword v[66:67], v71, off offset:128
; #define PW(T, off) ((T*)(lndp(p.ws) + (off)))
; DEVI float bf2f(bf16 h) { return __uint_as_float(((unsigned)h) << 16); }
; DEVI float sigmf(float x) { return __builtin_amdgcn_rcpf(1.f + __expf(-x)); }
; DEVI float softplusf(float x) { return x > 20.f ? x : __logf(1.f + __expf(x)); }
; DEVI float tanhfast(float x) { return 1.f - 2.f / (__expf(2.f * x) + 1.f); }
; DEVI int accrow(int r, int lane) { return (r & 3) + 8 * (r >> 2) + 4 * (lane >> 5); }
; template <int EPI>
; DEVI void gemm_epi(const Params& p, const GJob& jb, f32x16 (&acc)[2][2], int rbase, int cbase, int lane) {
;     ...
;       const int row = rbase + i * 32 + accrow(r, lane);
;       if (row < M) {
; #pragma unroll
;         for (int j = 0; j < 2; ++j) {
;           const int col = cbase + j * 32 + (lane & 31);
;           const float v = acc[i][j][r];
;           if (EPI == EPI_SSD_IN) {
;             if (col < 2048) ((bf16*)(ar + S_ZB))[(size_t)row * 2048 + col] = f2bf(v);
;             else if (col < 6144) ((bf16*)(ar + S_XBC))[(size_t)row * 4096 + col - 2048] = f2bf(v);
;             else if (col < 6176) ((float*)(ar + S_DTRAW))[(size_t)row * 32 + col - 6144] = v;
;           } else if (EPI == EPI_RESID) {
;             PW(bf16, W_Z)[(size_t)row * 1024 + col] = f2bf(ALPHA * bf2f(PW(bf16, W_Xb)[(size_t)row * 1024 + col]) + v);
;           } else if (EPI == EPI_GU) {
;             ((bf16*)(ar + F_GU))[(size_t)row * 5632 + col] = f2bf(v);
;           } else if (EPI == EPI_BF16) {
;             ((bf16*)jb.of)[(size_t)row * 1024 + col] = f2bf(v);
;           } else if (EPI == EPI_F32) {
;             jb.of[(size_t)row * 1024 + col] = v;
;           } else if (EPI == EPI_RK_W1) {
;             if (col < 64) ((bf16*)(ar + R_HW))[(size_t)row * 64 + col] = f2bf(tanhfast(v));
;           } else if (EPI == EPI_RK_A1) {
;             if (col < 64) ((bf16*)(ar + R_HA))[(size_t)row * 64 + col] = f2bf(v);
;           } else if (EPI == EPI_RK_G1) {
;             if (col < 192) ((bf16*)(ar + R_HG))[(size_t)row * 192 + col] = f2bf(col < 160 ? sigmf(v) : 0.f);
;           } else if (EPI == EPI_RK_W2) {
;             const float z = i_rk_w0[col] + v;
;             const float wl = -softplusf(-z) - 0.5f;
;             ((float*)(ar + R_W))[(size_t)row * 1024 + col] = __expf(-__expf(wl));
.LBB0_558:
	s_or_b64 exec, exec, s[2:3]
	v_or_b32_e32 v66, v86, v77
	v_cmp_gt_i32_e32 vcc, s90, v66
	s_and_saveexec_b64 s[2:3], vcc
	s_cbranch_execz .LBB0_560
	v_lshlrev_b64 v[72:73], 2, v[64:65]
	v_lshl_add_u64 v[74:75], s[8:9], 0, v[72:73]
	v_mov_b32_e32 v67, v170
	s_mov_b32 s5, 0x3f317217
	s_mov_b32 s18, 0x7f800000
	s_mov_b32 s4, 0xc1a00000
	v_add_f32_e32 v67, v23, v67
	v_mul_f32_e32 v71, 0xbfb8aa3b, v67
	v_exp_f32_e32 v71, v71
	s_nop 0
	v_add_f32_e32 v71, 1.0, v71
	v_cmp_gt_f32_e32 vcc, s69, v71
	s_nop 1
	v_cndmask_b32_e64 v76, 0, 32, vcc
	v_ldexp_f32 v71, v71, v76
	v_log_f32_e32 v71, v71
	v_cndmask_b32_e32 v76, 0, v216, vcc
	v_mul_f32_e32 v77, 0x3f317217, v71
	v_fma_f32 v77, v71, s5, -v77
	v_fmac_f32_e32 v77, 0x3377d1cf, v71
	v_fmac_f32_e32 v77, 0x3f317217, v71
	v_cmp_lt_f32_e64 vcc, |v71|, s18
	s_nop 1
	v_cndmask_b32_e32 v71, v71, v77, vcc
	v_sub_f32_e32 v71, v71, v76
	v_cmp_gt_f32_e32 vcc, s4, v67
	s_nop 1
	v_cndmask_b32_e64 v67, v71, -v67, vcc
	v_sub_f32_e32 v67, -0.5, v67
	v_mul_f32_e32 v67, 0x3fb8aa3b, v67
	v_exp_f32_e32 v71, v67
	v_ashrrev_i32_e32 v67, 31, v66
	v_lshlrev_b64 v[66:67], 12, v[66:67]
	v_lshl_add_u64 v[66:67], s[6:7], 0, v[66:67]
	v_mul_f32_e32 v71, 0xbfb8aa3b, v71
	v_exp_f32_e32 v71, v71
	v_lshl_add_u64 v[66:67], v[66:67], 0, v[72:73]
	global_store_dword v[66:67], v71, off
	v_mov_b32_e32 v71, v171
	v_add_f32_e32 v71, v7, v71
	v_mul_f32_e32 v72, 0xbfb8aa3b, v71
	v_exp_f32_e32 v72, v72
	s_nop 0
	v_add_f32_e32 v72, 1.0, v72
	v_cmp_gt_f32_e32 vcc, s69, v72
	s_nop 1
	v_cndmask_b32_e64 v73, 0, 32, vcc
	v_ldexp_f32 v72, v72, v73
	v_log_f32_e32 v72, v72
	v_cndmask_b32_e32 v73, 0, v216, vcc
	v_mul_f32_e32 v74, 0x3f317217, v72
	v_fma_f32 v74, v72, s5, -v74
	v_fmac_f32_e32 v74, 0x3377d1cf, v72
	v_fmac_f32_e32 v74, 0x3f317217, v72
	v_cmp_lt_f32_e64 vcc, |v72|, s18
	s_nop 1
	v_cndmask_b32_e32 v72, v72, v74, vcc
	v_sub_f32_e32 v72, v72, v73
	v_cmp_gt_f32_e32 vcc, s4, v71
	s_nop 1
	v_cndmask_b32_e64 v71, v72, -v71, vcc
	v_sub_f32_e32 v71, -0.5, v71
	v_mul_f32_e32 v71, 0x3fb8aa3b, v71
	v_exp_f32_e32 v71, v71
	s_nop 0
	v_mul_f32_e32 v71, 0xbfb8aa3b, v71
	v_exp_f32_e32 v71, v71
	global_store_dword v[66:67], v71, off offset:128
.LBB0_560:
	s_or_b64 exec, exec, s[2:3]
	v_or_b32_e32 v66, v86, v78
	v_cmp_gt_i32_e32 vcc, s90, v66
	s_and_saveexec_b64 s[2:3], vcc
	s_cbranch_execz .LBB0_562
	v_lshlrev_b64 v[72:73], 2, v[64:65]
	v_lshl_add_u64 v[74:75], s[8:9], 0, v[72:73]
	v_mov_b32_e32 v67, v170
	s_mov_b32 s5, 0x3f317217
	s_mov_b32 s18, 0x7f800000
	s_mov_b32 s4, 0xc1a00000
	v_add_f32_e32 v67, v24, v67
	v_mul_f32_e32 v71, 0xbfb8aa3b, v67
	v_exp_f32_e32 v71, v71
	s_nop 0
	v_add_f32_e32 v71, 1.0, v71
	v_cmp_gt_f32_e32 vcc, s69, v71
	s_nop 1
	v_cndmask_b32_e64 v76, 0, 32, vcc
	v_ldexp_f32 v71, v71, v76
	v_log_f32_e32 v71, v71
	v_cndmask_b32_e32 v76, 0, v216, vcc
	v_mul_f32_e32 v77, 0x3f317217, v71
	v_fma_f32 v77, v71, s5, -v77
	v_fmac_f32_e32 v77, 0x3377d1cf, v71
	v_fmac_f32_e32 v77, 0x3f317217, v71
	v_cmp_lt_f32_e64 vcc, |v71|, s18
	s_nop 1
	v_cndmask_b32_e32 v71, v71, v77, vcc
	v_sub_f32_e32 v71, v71, v76
	v_cmp_gt_f32_e32 vcc, s4, v67
	s_nop 1
	v_cndmask_b32_e64 v67, v71, -v67, vcc
	v_sub_f32_e32 v67, -0.5, v67
	v_mul_f32_e32 v67, 0x3fb8aa3b, v67
	v_exp_f32_e32 v71, v67
	v_ashrrev_i32_e32 v67, 31, v66
	v_lshlrev_b64 v[66:67], 12, v[66:67]
	v_lshl_add_u64 v[66:67], s[6:7], 0, v[66:67]
	v_mul_f32_e32 v71, 0xbfb8aa3b, v71
	v_exp_f32_e32 v71, v71
	v_lshl_add_u64 v[66:67], v[66:67], 0, v[72:73]
	global_store_dword v[66:67], v71, off
	v_mov_b32_e32 v71, v171
	v_add_f32_e32 v71, v8, v71
	v_mul_f32_e32 v72, 0xbfb8aa3b, v71
	v_exp_f32_e32 v72, v72
	s_nop 0
	v_add_f32_e32 v72, 1.0, v72
	v_cmp_gt_f32_e32 vcc, s69, v72
	s_nop 1
	v_cndmask_b32_e64 v73, 0, 32, vcc
	v_ldexp_f32 v72, v72, v73
	v_log_f32_e32 v72, v72
	v_cndmask_b32_e32 v73, 0, v216, vcc
	v_mul_f32_e32 v74, 0x3f317217, v72
	v_fma_f32 v74, v72, s5, -v74
	v_fmac_f32_e32 v74, 0x3377d1cf, v72
	v_fmac_f32_e32 v74, 0x3f317217, v72
	v_cmp_lt_f32_e64 vcc, |v72|, s18
	s_nop 1
	v_cndmask_b32_e32 v72, v72, v74, vcc
	v_sub_f32_e32 v72, v72, v73
	v_cmp_gt_f32_e32 vcc, s4, v71
	s_nop 1
	v_cndmask_b32_e64 v71, v72, -v71, vcc
	v_sub_f32_e32 v71, -0.5, v71
	v_mul_f32_e32 v71, 0x3fb8aa3b, v71
	v_exp_f32_e32 v71, v71
	s_nop 0
	v_mul_f32_e32 v71, 0xbfb8aa3b, v71
	v_exp_f32_e32 v71, v71
	global_store_dword v[66:67], v71, off offset:128
.LBB0_562:
	s_or_b64 exec, exec, s[2:3]
	v_or_b32_e32 v66, v86, v79
	v_cmp_gt_i32_e32 vcc, s90, v66
	s_and_saveexec_b64 s[2:3], vcc
	s_cbranch_execz .LBB0_564
	v_lshlrev_b64 v[72:73], 2, v[64:65]
	v_lshl_add_u64 v[74:75], s[8:9], 0, v[72:73]
	v_mov_b32_e32 v67, v170
	s_mov_b32 s5, 0x3f317217
	s_mov_b32 s18, 0x7f800000
	s_mov_b32 s4, 0xc1a00000
	v_add_f32_e32 v67, v25, v67
	v_mul_f32_e32 v71, 0xbfb8aa3b, v67
	v_exp_f32_e32 v71, v71
	s_nop 0
	v_add_f32_e32 v71, 1.0, v71
	v_cmp_gt_f32_e32 vcc, s69, v71
	s_nop 1
	v_cndmask_b32_e64 v76, 0, 32, vcc
	v_ldexp_f32 v71, v71, v76
	v_log_f32_e32 v71, v71
	v_cndmask_b32_e32 v76, 0, v216, vcc
	v_mul_f32_e32 v77, 0x3f317217, v71
	v_fma_f32 v77, v71, s5, -v77
	v_fmac_f32_e32 v77, 0x3377d1cf, v71
	v_fmac_f32_e32 v77, 0x3f317217, v71
	v_cmp_lt_f32_e64 vcc, |v71|, s18
	s_nop 1
	v_cndmask_b32_e32 v71, v71, v77, vcc
	v_sub_f32_e32 v71, v71, v76
	v_cmp_gt_f32_e32 vcc, s4, v67
	s_nop 1
	v_cndmask_b32_e64 v67, v71, -v67, vcc
	v_sub_f32_e32 v67, -0.5, v67
	v_mul_f32_e32 v67, 0x3fb8aa3b, v67
	v_exp_f32_e32 v71, v67
	v_ashrrev_i32_e32 v67, 31, v66
	v_lshlrev_b64 v[66:67], 12, v[66:67]
	v_lshl_add_u64 v[66:67], s[6:7], 0, v[66:67]
	v_mul_f32_e32 v71, 0xbfb8aa3b, v71
	v_exp_f32_e32 v71, v71
	v_lshl_add_u64 v[66:67], v[66:67], 0, v[72:73]
	global_store_dword v[66:67], v71, off
	v_mov_b32_e32 v71, v171
	v_add_f32_e32 v71, v9, v71
	v_mul_f32_e32 v72, 0xbfb8aa3b, v71
	v_exp_f32_e32 v72, v72
	s_nop 0
	v_add_f32_e32 v72, 1.0, v72
	v_cmp_gt_f32_e32 vcc, s69, v72
	s_nop 1
	v_cndmask_b32_e64 v73, 0, 32, vcc
	v_ldexp_f32 v72, v72, v73
	v_log_f32_e32 v72, v72
	v_cndmask_b32_e32 v73, 0, v216, vcc
	v_mul_f32_e32 v74, 0x3f317217, v72
	v_fma_f32 v74, v72, s5, -v74
	v_fmac_f32_e32 v74, 0x3377d1cf, v72
	v_fmac_f32_e32 v74, 0x3f317217, v72
	v_cmp_lt_f32_e64 vcc, |v72|, s18
	s_nop 1
	v_cndmask_b32_e32 v72, v72, v74, vcc
	v_sub_f32_e32 v72, v72, v73
	v_cmp_gt_f32_e32 vcc, s4, v71
	s_nop 1
	v_cndmask_b32_e64 v71, v72, -v71, vcc
	v_sub_f32_e32 v71, -0.5, v71
	v_mul_f32_e32 v71, 0x3fb8aa3b, v71
	v_exp_f32_e32 v71, v71
	s_nop 0
	v_mul_f32_e32 v71, 0xbfb8aa3b, v71
	v_exp_f32_e32 v71, v71
	global_store_dword v[66:67], v71, off offset:128
; #define PW(T, off) ((T*)(lndp(p.ws) + (off)))
; DEVI float bf2f(bf16 h) { return __uint_as_float(((unsigned)h) << 16); }
; DEVI float sigmf(float x) { return __builtin_amdgcn_rcpf(1.f + __expf(-x)); }
; DEVI float softplusf(float x) { return x > 20.f ? x : __logf(1.f + __expf(x)); }
; DEVI float tanhfast(float x) { return 1.f - 2.f / (__expf(2.f * x) + 1.f); }
; DEVI int accrow(int r, int lane) { return (r & 3) + 8 * (r >> 2) + 4 * (lane >> 5); }
; template <int EPI>
; DEVI void gemm_epi(const Params& p, const GJob& jb, f32x16 (&acc)[2][2], int rbase, int cbase, int lane) {
;     ...
;       const int row = rbase + i * 32 + accrow(r, lane);
;       if (row < M) {
; #pragma unroll
;         for (int j = 0; j < 2; ++j) {
;           const int col = cbase + j * 32 + (lane & 31);
;           const float v = acc[i][j][r];
;           if (EPI == EPI_SSD_IN) {
;             if (col < 2048) ((bf16*)(ar + S_ZB))[(size_t)row * 2048 + col] = f2bf(v);
;             else if (col < 6144) ((bf16*)(ar + S_XBC))[(size_t)row * 4096 + col - 2048] = f2bf(v);
;             else if (col < 6176) ((float*)(ar + S_DTRAW))[(size_t)row * 32 + col - 6144] = v;
;           } else if (EPI == EPI_RESID) {
;             PW(bf16, W_Z)[(size_t)row * 1024 + col] = f2bf(ALPHA * bf2f(PW(bf16, W_Xb)[(size_t)row * 1024 + col]) + v);
;           } else if (EPI == EPI_GU) {
;             ((bf16*)(ar + F_GU))[(size_t)row * 5632 + col] = f2bf(v);
;           } else if (EPI == EPI_BF16) {
;             ((bf16*)jb.of)[(size_t)row * 1024 + col] = f2bf(v);
;           } else if (EPI == EPI_F32) {
;             jb.of[(size_t)row * 1024 + col] = v;
;           } else if (EPI == EPI_RK_W1) {
;             if (col < 64) ((bf16*)(ar + R_HW))[(size_t)row * 64 + col] = f2bf(tanhfast(v));
;           } else if (EPI == EPI_RK_A1) {
;             if (col < 64) ((bf16*)(ar + R_HA))[(size_t)row * 64 + col] = f2bf(v);
;           } else if (EPI == EPI_RK_G1) {
;             if (col < 192) ((bf16*)(ar + R_HG))[(size_t)row * 192 + col] = f2bf(col < 160 ? sigmf(v) : 0.f);
;           } else if (EPI == EPI_RK_W2) {
;             const float z = i_rk_w0[col] + v;
;             const float wl = -softplusf(-z) - 0.5f;
;             ((float*)(ar + R_W))[(size_t)row * 1024 + col] = __expf(-__expf(wl));
.LBB0_564:
	s_or_b64 exec, exec, s[2:3]
	v_or_b32_e32 v66, v86, v80
	v_cmp_gt_i32_e32 vcc, s90, v66
	s_and_saveexec_b64 s[2:3], vcc
	s_cbranch_execz .LBB0_566
	v_lshlrev_b64 v[72:73], 2, v[64:65]
	v_lshl_add_u64 v[74:75], s[8:9], 0, v[72:73]
	v_mov_b32_e32 v67, v170
	s_mov_b32 s5, 0x3f317217
	s_mov_b32 s18, 0x7f800000
	s_mov_b32 s4, 0xc1a00000
	v_add_f32_e32 v67, v26, v67
	v_mul_f32_e32 v71, 0xbfb8aa3b, v67
	v_exp_f32_e32 v71, v71
	s_nop 0
	v_add_f32_e32 v71, 1.0, v71
	v_cmp_gt_f32_e32 vcc, s69, v71
	s_nop 1
	v_cndmask_b32_e64 v76, 0, 32, vcc
	v_ldexp_f32 v71, v71, v76
	v_log_f32_e32 v71, v71
	v_cndmask_b32_e32 v76, 0, v216, vcc
	v_mul_f32_e32 v77, 0x3f317217, v71
	v_fma_f32 v77, v71, s5, -v77
	v_fmac_f32_e32 v77, 0x3377d1cf, v71
	v_fmac_f32_e32 v77, 0x3f317217, v71
	v_cmp_lt_f32_e64 vcc, |v71|, s18
	s_nop 1
	v_cndmask_b32_e32 v71, v71, v77, vcc
	v_sub_f32_e32 v71, v71, v76
	v_cmp_gt_f32_e32 vcc, s4, v67
	s_nop 1
	v_cndmask_b32_e64 v67, v71, -v67, vcc
	v_sub_f32_e32 v67, -0.5, v67
	v_mul_f32_e32 v67, 0x3fb8aa3b, v67
	v_exp_f32_e32 v71, v67
	v_ashrrev_i32_e32 v67, 31, v66
	v_lshlrev_b64 v[66:67], 12, v[66:67]
	v_lshl_add_u64 v[66:67], s[6:7], 0, v[66:67]
	v_mul_f32_e32 v71, 0xbfb8aa3b, v71
	v_exp_f32_e32 v71, v71
	v_lshl_add_u64 v[66:67], v[66:67], 0, v[72:73]
	global_store_dword v[66:67], v71, off
	v_mov_b32_e32 v71, v171
	v_add_f32_e32 v71, v10, v71
	v_mul_f32_e32 v72, 0xbfb8aa3b, v71
	v_exp_f32_e32 v72, v72
	s_nop 0
	v_add_f32_e32 v72, 1.0, v72
	v_cmp_gt_f32_e32 vcc, s69, v72
	s_nop 1
	v_cndmask_b32_e64 v73, 0, 32, vcc
	v_ldexp_f32 v72, v72, v73
	v_log_f32_e32 v72, v72
	v_cndmask_b32_e32 v73, 0, v216, vcc
	v_mul_f32_e32 v74, 0x3f317217, v72
	v_fma_f32 v74, v72, s5, -v74
	v_fmac_f32_e32 v74, 0x3377d1cf, v72
	v_fmac_f32_e32 v74, 0x3f317217, v72
	v_cmp_lt_f32_e64 vcc, |v72|, s18
	s_nop 1
	v_cndmask_b32_e32 v72, v72, v74, vcc
	v_sub_f32_e32 v72, v72, v73
	v_cmp_gt_f32_e32 vcc, s4, v71
	s_nop 1
	v_cndmask_b32_e64 v71, v72, -v71, vcc
	v_sub_f32_e32 v71, -0.5, v71
	v_mul_f32_e32 v71, 0x3fb8aa3b, v71
	v_exp_f32_e32 v71, v71
	s_nop 0
	v_mul_f32_e32 v71, 0xbfb8aa3b, v71
	v_exp_f32_e32 v71, v71
	global_store_dword v[66:67], v71, off offset:128
.LBB0_566:
	s_or_b64 exec, exec, s[2:3]
	v_or_b32_e32 v66, v86, v81
	v_cmp_gt_i32_e32 vcc, s90, v66
	s_and_saveexec_b64 s[2:3], vcc
	s_cbranch_execz .LBB0_568
	v_lshlrev_b64 v[72:73], 2, v[64:65]
	v_lshl_add_u64 v[74:75], s[8:9], 0, v[72:73]
	v_mov_b32_e32 v67, v170
	s_mov_b32 s5, 0x3f317217
	s_mov_b32 s18, 0x7f800000
	s_mov_b32 s4, 0xc1a00000
	v_add_f32_e32 v67, v27, v67
	v_mul_f32_e32 v71, 0xbfb8aa3b, v67
	v_exp_f32_e32 v71, v71
	s_nop 0
	v_add_f32_e32 v71, 1.0, v71
	v_cmp_gt_f32_e32 vcc, s69, v71
	s_nop 1
	v_cndmask_b32_e64 v76, 0, 32, vcc
	v_ldexp_f32 v71, v71, v76
	v_log_f32_e32 v71, v71
	v_cndmask_b32_e32 v76, 0, v216, vcc
	v_mul_f32_e32 v77, 0x3f317217, v71
	v_fma_f32 v77, v71, s5, -v77
	v_fmac_f32_e32 v77, 0x3377d1cf, v71
	v_fmac_f32_e32 v77, 0x3f317217, v71
	v_cmp_lt_f32_e64 vcc, |v71|, s18
	s_nop 1
	v_cndmask_b32_e32 v71, v71, v77, vcc
	v_sub_f32_e32 v71, v71, v76
	v_cmp_gt_f32_e32 vcc, s4, v67
	s_nop 1
	v_cndmask_b32_e64 v67, v71, -v67, vcc
	v_sub_f32_e32 v67, -0.5, v67
	v_mul_f32_e32 v67, 0x3fb8aa3b, v67
	v_exp_f32_e32 v71, v67
	v_ashrrev_i32_e32 v67, 31, v66
	v_lshlrev_b64 v[66:67], 12, v[66:67]
	v_lshl_add_u64 v[66:67], s[6:7], 0, v[66:67]
	v_mul_f32_e32 v71, 0xbfb8aa3b, v71
	v_exp_f32_e32 v71, v71
	v_lshl_add_u64 v[66:67], v[66:67], 0, v[72:73]
	global_store_dword v[66:67], v71, off
	v_mov_b32_e32 v71, v171
	v_add_f32_e32 v71, v11, v71
	v_mul_f32_e32 v72, 0xbfb8aa3b, v71
	v_exp_f32_e32 v72, v72
	s_nop 0
	v_add_f32_e32 v72, 1.0, v72
	v_cmp_gt_f32_e32 vcc, s69, v72
	s_nop 1
	v_cndmask_b32_e64 v73, 0, 32, vcc
	v_ldexp_f32 v72, v72, v73
	v_log_f32_e32 v72, v72
	v_cndmask_b32_e32 v73, 0, v216, vcc
	v_mul_f32_e32 v74, 0x3f317217, v72
	v_fma_f32 v74, v72, s5, -v74
	v_fmac_f32_e32 v74, 0x3377d1cf, v72
	v_fmac_f32_e32 v74, 0x3f317217, v72
	v_cmp_lt_f32_e64 vcc, |v72|, s18
	s_nop 1
	v_cndmask_b32_e32 v72, v72, v74, vcc
	v_sub_f32_e32 v72, v72, v73
	v_cmp_gt_f32_e32 vcc, s4, v71
	s_nop 1
	v_cndmask_b32_e64 v71, v72, -v71, vcc
	v_sub_f32_e32 v71, -0.5, v71
	v_mul_f32_e32 v71, 0x3fb8aa3b, v71
	v_exp_f32_e32 v71, v71
	s_nop 0
	v_mul_f32_e32 v71, 0xbfb8aa3b, v71
	v_exp_f32_e32 v71, v71
	global_store_dword v[66:67], v71, off offset:128
.LBB0_568:
	s_or_b64 exec, exec, s[2:3]
	v_or_b32_e32 v66, v86, v82
	v_cmp_gt_i32_e32 vcc, s90, v66
	s_and_saveexec_b64 s[2:3], vcc
	s_cbranch_execz .LBB0_570
	v_lshlrev_b64 v[72:73], 2, v[64:65]
	v_lshl_add_u64 v[74:75], s[8:9], 0, v[72:73]
	v_mov_b32_e32 v67, v170
	s_mov_b32 s5, 0x3f317217
	s_mov_b32 s18, 0x7f800000
	s_mov_b32 s4, 0xc1a00000
	v_add_f32_e32 v67, v28, v67
	v_mul_f32_e32 v71, 0xbfb8aa3b, v67
	v_exp_f32_e32 v71, v71
	s_nop 0
	v_add_f32_e32 v71, 1.0, v71
	v_cmp_gt_f32_e32 vcc, s69, v71
	s_nop 1
	v_cndmask_b32_e64 v76, 0, 32, vcc
	v_ldexp_f32 v71, v71, v76
	v_log_f32_e32 v71, v71
	v_cndmask_b32_e32 v76, 0, v216, vcc
	v_mul_f32_e32 v77, 0x3f317217, v71
	v_fma_f32 v77, v71, s5, -v77
	v_fmac_f32_e32 v77, 0x3377d1cf, v71
	v_fmac_f32_e32 v77, 0x3f317217, v71
	v_cmp_lt_f32_e64 vcc, |v71|, s18
	s_nop 1
	v_cndmask_b32_e32 v71, v71, v77, vcc
	v_sub_f32_e32 v71, v71, v76
	v_cmp_gt_f32_e32 vcc, s4, v67
	s_nop 1
	v_cndmask_b32_e64 v67, v71, -v67, vcc
	v_sub_f32_e32 v67, -0.5, v67
	v_mul_f32_e32 v67, 0x3fb8aa3b, v67
	v_exp_f32_e32 v71, v67
	v_ashrrev_i32_e32 v67, 31, v66
	v_lshlrev_b64 v[66:67], 12, v[66:67]
	v_lshl_add_u64 v[66:67], s[6:7], 0, v[66:67]
	v_mul_f32_e32 v71, 0xbfb8aa3b, v71
	v_exp_f32_e32 v71, v71
	v_lshl_add_u64 v[66:67], v[66:67], 0, v[72:73]
	global_store_dword v[66:67], v71, off
	v_mov_b32_e32 v71, v171
	v_add_f32_e32 v71, v12, v71
	v_mul_f32_e32 v72, 0xbfb8aa3b, v71
	v_exp_f32_e32 v72, v72
	s_nop 0
	v_add_f32_e32 v72, 1.0, v72
	v_cmp_gt_f32_e32 vcc, s69, v72
	s_nop 1
	v_cndmask_b32_e64 v73, 0, 32, vcc
	v_ldexp_f32 v72, v72, v73
	v_log_f32_e32 v72, v72
	v_cndmask_b32_e32 v73, 0, v216, vcc
	v_mul_f32_e32 v74, 0x3f317217, v72
	v_fma_f32 v74, v72, s5, -v74
	v_fmac_f32_e32 v74, 0x3377d1cf, v72
	v_fmac_f32_e32 v74, 0x3f317217, v72
	v_cmp_lt_f32_e64 vcc, |v72|, s18
	s_nop 1
	v_cndmask_b32_e32 v72, v72, v74, vcc
	v_sub_f32_e32 v72, v72, v73
	v_cmp_gt_f32_e32 vcc, s4, v71
	s_nop 1
	v_cndmask_b32_e64 v71, v72, -v71, vcc
	v_sub_f32_e32 v71, -0.5, v71
	v_mul_f32_e32 v71, 0x3fb8aa3b, v71
	v_exp_f32_e32 v71, v71
	s_nop 0
	v_mul_f32_e32 v71, 0xbfb8aa3b, v71
	v_exp_f32_e32 v71, v71
	global_store_dword v[66:67], v71, off offset:128
; #define PW(T, off) ((T*)(lndp(p.ws) + (off)))
; DEVI float bf2f(bf16 h) { return __uint_as_float(((unsigned)h) << 16); }
; DEVI float sigmf(float x) { return __builtin_amdgcn_rcpf(1.f + __expf(-x)); }
; DEVI float softplusf(float x) { return x > 20.f ? x : __logf(1.f + __expf(x)); }
; DEVI float tanhfast(float x) { return 1.f - 2.f / (__expf(2.f * x) + 1.f); }
; DEVI int accrow(int r, int lane) { return (r & 3) + 8 * (r >> 2) + 4 * (lane >> 5); }
; template <int EPI>
; DEVI void gemm_epi(const Params& p, const GJob& jb, f32x16 (&acc)[2][2], int rbase, int cbase, int lane) {
;     ...
;       const int row = rbase + i * 32 + accrow(r, lane);
;       if (row < M) {
; #pragma unroll
;         for (int j = 0; j < 2; ++j) {
;           const int col = cbase + j * 32 + (lane & 31);
;           const float v = acc[i][j][r];
;           if (EPI == EPI_SSD_IN) {
;             if (col < 2048) ((bf16*)(ar + S_ZB))[(size_t)row * 2048 + col] = f2bf(v);
;             else if (col < 6144) ((bf16*)(ar + S_XBC))[(size_t)row * 4096 + col - 2048] = f2bf(v);
;             else if (col < 6176) ((float*)(ar + S_DTRAW))[(size_t)row * 32 + col - 6144] = v;
;           } else if (EPI == EPI_RESID) {
;             PW(bf16, W_Z)[(size_t)row * 1024 + col] = f2bf(ALPHA * bf2f(PW(bf16, W_Xb)[(size_t)row * 1024 + col]) + v);
;           } else if (EPI == EPI_GU) {
;             ((bf16*)(ar + F_GU))[(size_t)row * 5632 + col] = f2bf(v);
;           } else if (EPI == EPI_BF16) {
;             ((bf16*)jb.of)[(size_t)row * 1024 + col] = f2bf(v);
;           } else if (EPI == EPI_F32) {
;             jb.of[(size_t)row * 1024 + col] = v;
;           } else if (EPI == EPI_RK_W1) {
;             if (col < 64) ((bf16*)(ar + R_HW))[(size_t)row * 64 + col] = f2bf(tanhfast(v));
;           } else if (EPI == EPI_RK_A1) {
;             if (col < 64) ((bf16*)(ar + R_HA))[(size_t)row * 64 + col] = f2bf(v);
;           } else if (EPI == EPI_RK_G1) {
;             if (col < 192) ((bf16*)(ar + R_HG))[(size_t)row * 192 + col] = f2bf(col < 160 ? sigmf(v) : 0.f);
;           } else if (EPI == EPI_RK_W2) {
;             const float z = i_rk_w0[col] + v;
;             const float wl = -softplusf(-z) - 0.5f;
;             ((float*)(ar + R_W))[(size_t)row * 1024 + col] = __expf(-__expf(wl));
.LBB0_570:
	s_or_b64 exec, exec, s[2:3]
	v_or_b32_e32 v66, v86, v83
	v_cmp_gt_i32_e32 vcc, s90, v66
	s_and_saveexec_b64 s[2:3], vcc
	s_cbranch_execz .LBB0_572
	v_lshlrev_b64 v[72:73], 2, v[64:65]
	v_lshl_add_u64 v[74:75], s[8:9], 0, v[72:73]
	v_mov_b32_e32 v67, v170
	s_mov_b32 s5, 0x3f317217
	s_mov_b32 s18, 0x7f800000
	s_mov_b32 s4, 0xc1a00000
	v_add_f32_e32 v67, v29, v67
	v_mul_f32_e32 v71, 0xbfb8aa3b, v67
	v_exp_f32_e32 v71, v71
	s_nop 0
	v_add_f32_e32 v71, 1.0, v71
	v_cmp_gt_f32_e32 vcc, s69, v71
	s_nop 1
	v_cndmask_b32_e64 v76, 0, 32, vcc
	v_ldexp_f32 v71, v71, v76
	v_log_f32_e32 v71, v71
	v_cndmask_b32_e32 v76, 0, v216, vcc
	v_mul_f32_e32 v77, 0x3f317217, v71
	v_fma_f32 v77, v71, s5, -v77
	v_fmac_f32_e32 v77, 0x3377d1cf, v71
	v_fmac_f32_e32 v77, 0x3f317217, v71
	v_cmp_lt_f32_e64 vcc, |v71|, s18
	s_nop 1
	v_cndmask_b32_e32 v71, v71, v77, vcc
	v_sub_f32_e32 v71, v71, v76
	v_cmp_gt_f32_e32 vcc, s4, v67
	s_nop 1
	v_cndmask_b32_e64 v67, v71, -v67, vcc
	v_sub_f32_e32 v67, -0.5, v67
	v_mul_f32_e32 v67, 0x3fb8aa3b, v67
	v_exp_f32_e32 v71, v67
	v_ashrrev_i32_e32 v67, 31, v66
	v_lshlrev_b64 v[66:67], 12, v[66:67]
	v_lshl_add_u64 v[66:67], s[6:7], 0, v[66:67]
	v_mul_f32_e32 v71, 0xbfb8aa3b, v71
	v_exp_f32_e32 v71, v71
	v_lshl_add_u64 v[66:67], v[66:67], 0, v[72:73]
	global_store_dword v[66:67], v71, off
	v_mov_b32_e32 v71, v171
	v_add_f32_e32 v71, v13, v71
	v_mul_f32_e32 v72, 0xbfb8aa3b, v71
	v_exp_f32_e32 v72, v72
	s_nop 0
	v_add_f32_e32 v72, 1.0, v72
	v_cmp_gt_f32_e32 vcc, s69, v72
	s_nop 1
	v_cndmask_b32_e64 v73, 0, 32, vcc
	v_ldexp_f32 v72, v72, v73
	v_log_f32_e32 v72, v72
	v_cndmask_b32_e32 v73, 0, v216, vcc
	v_mul_f32_e32 v74, 0x3f317217, v72
	v_fma_f32 v74, v72, s5, -v74
	v_fmac_f32_e32 v74, 0x3377d1cf, v72
	v_fmac_f32_e32 v74, 0x3f317217, v72
	v_cmp_lt_f32_e64 vcc, |v72|, s18
	s_nop 1
	v_cndmask_b32_e32 v72, v72, v74, vcc
	v_sub_f32_e32 v72, v72, v73
	v_cmp_gt_f32_e32 vcc, s4, v71
	s_nop 1
	v_cndmask_b32_e64 v71, v72, -v71, vcc
	v_sub_f32_e32 v71, -0.5, v71
	v_mul_f32_e32 v71, 0x3fb8aa3b, v71
	v_exp_f32_e32 v71, v71
	s_nop 0
	v_mul_f32_e32 v71, 0xbfb8aa3b, v71
	v_exp_f32_e32 v71, v71
	global_store_dword v[66:67], v71, off offset:128
.LBB0_572:
	s_or_b64 exec, exec, s[2:3]
	v_or_b32_e32 v66, v86, v84
	v_cmp_gt_i32_e32 vcc, s90, v66
	s_and_saveexec_b64 s[2:3], vcc
	s_cbranch_execz .LBB0_574
	v_lshlrev_b64 v[72:73], 2, v[64:65]
	v_lshl_add_u64 v[74:75], s[8:9], 0, v[72:73]
	v_mov_b32_e32 v67, v170
	s_mov_b32 s5, 0x3f317217
	s_mov_b32 s18, 0x7f800000
	s_mov_b32 s4, 0xc1a00000
	v_add_f32_e32 v67, v30, v67
	v_mul_f32_e32 v71, 0xbfb8aa3b, v67
	v_exp_f32_e32 v71, v71
	s_nop 0
	v_add_f32_e32 v71, 1.0, v71
	v_cmp_gt_f32_e32 vcc, s69, v71
	s_nop 1
	v_cndmask_b32_e64 v76, 0, 32, vcc
	v_ldexp_f32 v71, v71, v76
	v_log_f32_e32 v71, v71
	v_cndmask_b32_e32 v76, 0, v216, vcc
	v_mul_f32_e32 v77, 0x3f317217, v71
	v_fma_f32 v77, v71, s5, -v77
	v_fmac_f32_e32 v77, 0x3377d1cf, v71
	v_fmac_f32_e32 v77, 0x3f317217, v71
	v_cmp_lt_f32_e64 vcc, |v71|, s18
	s_nop 1
	v_cndmask_b32_e32 v71, v71, v77, vcc
	v_sub_f32_e32 v71, v71, v76
	v_cmp_gt_f32_e32 vcc, s4, v67
	s_nop 1
	v_cndmask_b32_e64 v67, v71, -v67, vcc
	v_sub_f32_e32 v67, -0.5, v67
	v_mul_f32_e32 v67, 0x3fb8aa3b, v67
	v_exp_f32_e32 v71, v67
	v_ashrrev_i32_e32 v67, 31, v66
	v_lshlrev_b64 v[66:67], 12, v[66:67]
	v_lshl_add_u64 v[66:67], s[6:7], 0, v[66:67]
	v_mul_f32_e32 v71, 0xbfb8aa3b, v71
	v_exp_f32_e32 v71, v71
	v_lshl_add_u64 v[66:67], v[66:67], 0, v[72:73]
	global_store_dword v[66:67], v71, off
	v_mov_b32_e32 v71, v171
	v_add_f32_e32 v71, v14, v71
	v_mul_f32_e32 v72, 0xbfb8aa3b, v71
	v_exp_f32_e32 v72, v72
	s_nop 0
	v_add_f32_e32 v72, 1.0, v72
	v_cmp_gt_f32_e32 vcc, s69, v72
	s_nop 1
	v_cndmask_b32_e64 v73, 0, 32, vcc
	v_ldexp_f32 v72, v72, v73
	v_log_f32_e32 v72, v72
	v_cndmask_b32_e32 v73, 0, v216, vcc
	v_mul_f32_e32 v74, 0x3f317217, v72
	v_fma_f32 v74, v72, s5, -v74
	v_fmac_f32_e32 v74, 0x3377d1cf, v72
	v_fmac_f32_e32 v74, 0x3f317217, v72
	v_cmp_lt_f32_e64 vcc, |v72|, s18
	s_nop 1
	v_cndmask_b32_e32 v72, v72, v74, vcc
	v_sub_f32_e32 v72, v72, v73
	v_cmp_gt_f32_e32 vcc, s4, v71
	s_nop 1
	v_cndmask_b32_e64 v71, v72, -v71, vcc
	v_sub_f32_e32 v71, -0.5, v71
	v_mul_f32_e32 v71, 0x3fb8aa3b, v71
	v_exp_f32_e32 v71, v71
	s_nop 0
	v_mul_f32_e32 v71, 0xbfb8aa3b, v71
	v_exp_f32_e32 v71, v71
	global_store_dword v[66:67], v71, off offset:128
.LBB0_574:
	s_or_b64 exec, exec, s[2:3]
	v_or_b32_e32 v66, v86, v85
	v_cmp_gt_i32_e32 vcc, s90, v66
	s_and_saveexec_b64 s[2:3], vcc
	s_cbranch_execz .LBB0_576
	v_lshlrev_b64 v[72:73], 2, v[64:65]
	v_lshl_add_u64 v[74:75], s[8:9], 0, v[72:73]
	v_mov_b32_e32 v67, v170
	s_mov_b32 s5, 0x3f317217
	s_mov_b32 s8, 0x7f800000
	s_mov_b32 s4, 0xc1a00000
	v_add_f32_e32 v67, v31, v67
	v_mul_f32_e32 v71, 0xbfb8aa3b, v67
	v_exp_f32_e32 v71, v71
	s_nop 0
	v_add_f32_e32 v71, 1.0, v71
	v_cmp_gt_f32_e32 vcc, s69, v71
	s_nop 1
	v_cndmask_b32_e64 v76, 0, 32, vcc
	v_ldexp_f32 v71, v71, v76
	v_log_f32_e32 v71, v71
	v_cndmask_b32_e32 v76, 0, v216, vcc
	v_mul_f32_e32 v77, 0x3f317217, v71
	v_fma_f32 v77, v71, s5, -v77
	v_fmac_f32_e32 v77, 0x3377d1cf, v71
	v_fmac_f32_e32 v77, 0x3f317217, v71
	v_cmp_lt_f32_e64 vcc, |v71|, s8
	s_nop 1
	v_cndmask_b32_e32 v71, v71, v77, vcc
	v_sub_f32_e32 v71, v71, v76
	v_cmp_gt_f32_e32 vcc, s4, v67
	s_nop 1
	v_cndmask_b32_e64 v67, v71, -v67, vcc
	v_sub_f32_e32 v67, -0.5, v67
	v_mul_f32_e32 v67, 0x3fb8aa3b, v67
	v_exp_f32_e32 v71, v67
	v_ashrrev_i32_e32 v67, 31, v66
	v_lshlrev_b64 v[66:67], 12, v[66:67]
	v_lshl_add_u64 v[66:67], s[6:7], 0, v[66:67]
	v_mul_f32_e32 v71, 0xbfb8aa3b, v71
	v_exp_f32_e32 v71, v71
	v_lshl_add_u64 v[66:67], v[66:67], 0, v[72:73]
	global_store_dword v[66:67], v71, off
	v_mov_b32_e32 v71, v171
	v_add_f32_e32 v71, v15, v71
	v_mul_f32_e32 v72, 0xbfb8aa3b, v71
	v_exp_f32_e32 v72, v72
	s_nop 0
	v_add_f32_e32 v72, 1.0, v72
	v_cmp_gt_f32_e32 vcc, s69, v72
	s_nop 1
	v_cndmask_b32_e64 v73, 0, 32, vcc
	v_ldexp_f32 v72, v72, v73
	v_log_f32_e32 v72, v72
	v_cndmask_b32_e32 v73, 0, v216, vcc
	v_mul_f32_e32 v74, 0x3f317217, v72
	v_fma_f32 v74, v72, s5, -v74
	v_fmac_f32_e32 v74, 0x3377d1cf, v72
	v_fmac_f32_e32 v74, 0x3f317217, v72
	v_cmp_lt_f32_e64 vcc, |v72|, s8
	s_nop 1
	v_cndmask_b32_e32 v72, v72, v74, vcc
	v_sub_f32_e32 v72, v72, v73
	v_cmp_gt_f32_e32 vcc, s4, v71
	s_nop 1
	v_cndmask_b32_e64 v71, v72, -v71, vcc
	v_sub_f32_e32 v71, -0.5, v71
	v_mul_f32_e32 v71, 0x3fb8aa3b, v71
	v_exp_f32_e32 v71, v71
	s_nop 0
	v_mul_f32_e32 v71, 0xbfb8aa3b, v71
	v_exp_f32_e32 v71, v71
	global_store_dword v[66:67], v71, off offset:128

; #define PIN(i) (gl_in(p.in[lnd(i)]))
; #define PW(T, off) ((T*)(lndp(p.ws) + (off)))
; template <int EPI>
; DEVI void gemm_epi(const Params& p, const GJob& jb, f32x16 (&acc)[2][2], int rbase, int cbase, int lane) {
;   const float* i_rk_w0 = PIN(23);
;   const float* i_rk_a0 = PIN(26);
;   char* ar = PW(char, W_arena);
; #pragma unroll
;   for (int i = 0; i < 2; ++i) {
; #pragma unroll
;     for (int r = 0; r < 16; ++r) {
;       const int row = rbase + i * 32 + accrow(r, lane);
;       if (row < M) {
; #pragma unroll
;         for (int j = 0; j < 2; ++j) {
;           const int col = cbase + j * 32 + (lane & 31);
;           const float v = acc[i][j][r];
;           if (EPI == EPI_SSD_IN) {
;             if (col < 2048) ((bf16*)(ar + S_ZB))[(size_t)row * 2048 + col] = f2bf(v);
;             else if (col < 6144) ((bf16*)(ar + S_XBC))[(size_t)row * 4096 + col - 2048] = f2bf(v);
;             else if (col < 6176) ((float*)(ar + S_DTRAW))[(size_t)row * 32 + col - 6144] = v;
;           } else if (EPI == EPI_RESID) {
;             PW(bf16, W_Z)[(size_t)row * 1024 + col] = f2bf(ALPHA * bf2f(PW(bf16, W_Xb)[(size_t)row * 1024 + col]) + v);
;           } else if (EPI == EPI_GU) {
;             ((bf16*)(ar + F_GU))[(size_t)row * 5632 + col] = f2bf(v);
;           } else if (EPI == EPI_BF16) {
;             ((bf16*)jb.of)[(size_t)row * 1024 + col] = f2bf(v);
;           } else if (EPI == EPI_F32) {
;             jb.of[(size_t)row * 1024 + col] = v;
;           } else if (EPI == EPI_RK_W1) {
;             if (col < 64) ((bf16*)(ar + R_HW))[(size_t)row * 64 + col] = f2bf(tanhfast(v));
;           } else if (EPI == EPI_RK_A1) {
;             if (col < 64) ((bf16*)(ar + R_HA))[(size_t)row * 64 + col] = f2bf(v);
;           } else if (EPI == EPI_RK_G1) {
;             if (col < 192) ((bf16*)(ar + R_HG))[(size_t)row * 192 + col] = f2bf(col < 160 ? sigmf(v) : 0.f);
;           } else if (EPI == EPI_RK_W2) {
;             const float z = i_rk_w0[col] + v;
;             const float wl = -softplusf(-z) - 0.5f;
;             ((float*)(ar + R_W))[(size_t)row * 1024 + col] = __expf(-__expf(wl));
;           } else if (EPI == EPI_RESID_TAIL) {
;             atomicAdd(PW(float, W_ZT) + (size_t)(row - 16384) * 1024 + col, v);
;           } else if (EPI == EPI_RK_A2) {
;             ((bf16*)(ar + R_A))[(size_t)row * 1024 + col] = f2bf(sigmf(i_rk_a0[col] + v));
.LBB0_577:
	s_and_b64 vcc, exec, s[2:3]
	s_cbranch_vccz .LBB0_356
	s_mov_b32 s2, 23
	s_ashr_i32 s3, s2, 31
	s_lshl_b64 s[2:3], s[2:3], 3
	s_add_u32 s2, s0, s2
	s_addc_u32 s3, s1, s3
	s_load_dwordx2 s[2:3], s[2:3], 0x0
	s_mov_b32 s4, 26
	s_waitcnt lgkmcnt(0)
	s_ashr_i32 s5, s4, 31
	s_lshl_b64 s[2:3], s[4:5], 3
	s_add_u32 s2, s0, s2
	s_addc_u32 s3, s1, s3
	s_load_dwordx2 s[2:3], s[2:3], 0x0
	s_mov_b64 s[4:5], s[74:75]
	v_or_b32_e32 v66, v68, v69
	s_waitcnt lgkmcnt(0)
	s_add_u32 s6, s4, 0x15efc000
	s_addc_u32 s7, s5, 0
	v_cmp_gt_i32_e32 vcc, s90, v66
	v_lshlrev_b64 v[176:177], 2, v[64:65]
	v_lshl_add_u64 v[176:177], v[176:177], 0, s[2:3]
	global_load_dword v174, v[176:177], off
	global_load_dword v175, v[176:177], off offset:128
	s_waitcnt vmcnt(0)
	s_and_saveexec_b64 s[4:5], vcc
	s_cbranch_execz .LBB0_580
	s_waitcnt vmcnt(4)
	v_lshl_add_u64 v[72:73], v[64:65], 2, s[2:3]
	v_mov_b32_e32 v67, v174
	v_mov_b32_e32 v71, v175
	v_add_f32_e32 v32, v32, v67
	v_add_f32_e32 v48, v48, v71
	v_mul_f32_e32 v32, 0xbfb8aa3b, v32
	v_mul_f32_e32 v48, 0xbfb8aa3b, v48
	v_exp_f32_e32 v32, v32
	v_exp_f32_e32 v48, v48
	v_ashrrev_i32_e32 v67, 31, v66
	v_lshlrev_b64 v[66:67], 11, v[66:67]
	v_add_f32_e32 v32, 1.0, v32
	v_add_f32_e32 v48, 1.0, v48
	v_rcp_f32_e32 v32, v32
	v_rcp_f32_e32 v48, v48
	v_lshl_add_u64 v[66:67], s[6:7], 0, v[66:67]
	v_lshl_add_u64 v[66:67], v[64:65], 1, v[66:67]
	v_cvt_pk_bf16_f32 v32, v32, s0
	v_cvt_pk_bf16_f32 v48, v48, s0
	global_store_short v[66:67], v32, off
	global_store_short v[66:67], v48, off offset:64
.LBB0_580:
	s_or_b64 exec, exec, s[4:5]
	v_or_b32_e32 v48, 1, v69
	v_or_b32_e32 v32, v48, v68
	v_cmp_gt_i32_e32 vcc, s90, v32
	s_and_saveexec_b64 s[4:5], vcc
	s_cbranch_execz .LBB0_582
	v_lshl_add_u64 v[66:67], v[64:65], 2, s[2:3]
	v_mov_b32_e32 v71, v174
	s_nop 0
	v_mov_b32_e32 v66, v175
	v_add_f32_e32 v33, v33, v71
	v_add_f32_e32 v49, v49, v66
	v_mul_f32_e32 v33, 0xbfb8aa3b, v33
	v_mul_f32_e32 v49, 0xbfb8aa3b, v49
	v_exp_f32_e32 v66, v33
	v_exp_f32_e32 v49, v49
	v_ashrrev_i32_e32 v33, 31, v32
	v_lshlrev_b64 v[32:33], 11, v[32:33]
	v_add_f32_e32 v66, 1.0, v66
	v_add_f32_e32 v49, 1.0, v49
	v_rcp_f32_e32 v66, v66
	v_rcp_f32_e32 v49, v49
	v_lshl_add_u64 v[32:33], s[6:7], 0, v[32:33]
	v_lshl_add_u64 v[32:33], v[64:65], 1, v[32:33]
	v_cvt_pk_bf16_f32 v66, v66, s0
	v_cvt_pk_bf16_f32 v49, v49, s0
	global_store_short v[32:33], v66, off
	global_store_short v[32:33], v49, off offset:64
.LBB0_582:
	s_or_b64 exec, exec, s[4:5]
	v_or_b32_e32 v49, 2, v69
	v_or_b32_e32 v32, v49, v68
	v_cmp_gt_i32_e32 vcc, s90, v32
	s_and_saveexec_b64 s[4:5], vcc
	s_cbranch_execz .LBB0_584
	v_lshl_add_u64 v[66:67], v[64:65], 2, s[2:3]
	v_mov_b32_e32 v33, v174
	s_nop 0
	v_mov_b32_e32 v66, v175
	v_add_f32_e32 v33, v34, v33
	v_add_f32_e32 v34, v50, v66
	v_mul_f32_e32 v33, 0xbfb8aa3b, v33
	v_mul_f32_e32 v34, 0xbfb8aa3b, v34
	v_exp_f32_e32 v50, v33
	v_exp_f32_e32 v34, v34
	v_ashrrev_i32_e32 v33, 31, v32
	v_lshlrev_b64 v[32:33], 11, v[32:33]
	v_add_f32_e32 v50, 1.0, v50
	v_add_f32_e32 v34, 1.0, v34
	v_rcp_f32_e32 v50, v50
	v_rcp_f32_e32 v34, v34
	v_lshl_add_u64 v[32:33], s[6:7], 0, v[32:33]
	v_lshl_add_u64 v[32:33], v[64:65], 1, v[32:33]
	v_cvt_pk_bf16_f32 v50, v50, s0
	v_cvt_pk_bf16_f32 v34, v34, s0
	global_store_short v[32:33], v50, off
	global_store_short v[32:33], v34, off offset:64
.LBB0_584:
	s_or_b64 exec, exec, s[4:5]
	v_or_b32_e32 v34, 3, v70
	v_or_b32_e32 v32, v68, v34
	v_cmp_gt_i32_e32 vcc, s90, v32
	s_and_saveexec_b64 s[4:5], vcc
	s_cbranch_execz .LBB0_586
	v_lshl_add_u64 v[66:67], v[64:65], 2, s[2:3]
	v_mov_b32_e32 v33, v174
	v_mov_b32_e32 v50, v175
	v_add_f32_e32 v33, v35, v33
	v_add_f32_e32 v35, v51, v50
	v_mul_f32_e32 v33, 0xbfb8aa3b, v33
	v_mul_f32_e32 v35, 0xbfb8aa3b, v35
	v_exp_f32_e32 v50, v33
	v_exp_f32_e32 v35, v35
	v_ashrrev_i32_e32 v33, 31, v32
	v_lshlrev_b64 v[32:33], 11, v[32:33]
	v_add_f32_e32 v50, 1.0, v50
	v_add_f32_e32 v35, 1.0, v35
	v_rcp_f32_e32 v50, v50
	v_rcp_f32_e32 v35, v35
	v_lshl_add_u64 v[32:33], s[6:7], 0, v[32:33]
	v_lshl_add_u64 v[32:33], v[64:65], 1, v[32:33]
	v_cvt_pk_bf16_f32 v50, v50, s0
	v_cvt_pk_bf16_f32 v35, v35, s0
	global_store_short v[32:33], v50, off
	global_store_short v[32:33], v35, off offset:64
.LBB0_586:
	s_or_b64 exec, exec, s[4:5]
	v_or_b32_e32 v35, 8, v69
	v_or_b32_e32 v32, v35, v68
	v_cmp_gt_i32_e32 vcc, s90, v32
	s_and_saveexec_b64 s[4:5], vcc
	s_cbranch_execz .LBB0_588
	v_lshl_add_u64 v[50:51], v[64:65], 2, s[2:3]
	v_mov_b32_e32 v33, v174
	s_nop 0
	v_mov_b32_e32 v50, v175
	v_add_f32_e32 v33, v36, v33
	v_add_f32_e32 v36, v52, v50
	v_mul_f32_e32 v33, 0xbfb8aa3b, v33
	v_mul_f32_e32 v36, 0xbfb8aa3b, v36
	v_exp_f32_e32 v50, v33
	v_exp_f32_e32 v36, v36
	v_ashrrev_i32_e32 v33, 31, v32
	v_lshlrev_b64 v[32:33], 11, v[32:33]
	v_add_f32_e32 v50, 1.0, v50
	v_add_f32_e32 v36, 1.0, v36
	v_rcp_f32_e32 v50, v50
	v_rcp_f32_e32 v36, v36
	v_lshl_add_u64 v[32:33], s[6:7], 0, v[32:33]
	v_lshl_add_u64 v[32:33], v[64:65], 1, v[32:33]
	v_cvt_pk_bf16_f32 v50, v50, s0
	v_cvt_pk_bf16_f32 v36, v36, s0
	global_store_short v[32:33], v50, off
	global_store_short v[32:33], v36, off offset:64
.LBB0_588:
	s_or_b64 exec, exec, s[4:5]
	v_or_b32_e32 v36, 9, v69
	v_or_b32_e32 v32, v36, v68
	v_cmp_gt_i32_e32 vcc, s90, v32
	s_and_saveexec_b64 s[4:5], vcc
	s_cbranch_execz .LBB0_590
	v_lshl_add_u64 v[50:51], v[64:65], 2, s[2:3]
	v_mov_b32_e32 v33, v174
	s_nop 0
	v_mov_b32_e32 v50, v175
	v_add_f32_e32 v33, v37, v33
	v_add_f32_e32 v37, v53, v50
	v_mul_f32_e32 v33, 0xbfb8aa3b, v33
	v_mul_f32_e32 v37, 0xbfb8aa3b, v37
	v_exp_f32_e32 v50, v33
	v_exp_f32_e32 v37, v37
	v_ashrrev_i32_e32 v33, 31, v32
	v_lshlrev_b64 v[32:33], 11, v[32:33]
	v_add_f32_e32 v50, 1.0, v50
	v_add_f32_e32 v37, 1.0, v37
	v_rcp_f32_e32 v50, v50
	v_rcp_f32_e32 v37, v37
	v_lshl_add_u64 v[32:33], s[6:7], 0, v[32:33]
	v_lshl_add_u64 v[32:33], v[64:65], 1, v[32:33]
	v_cvt_pk_bf16_f32 v50, v50, s0
	v_cvt_pk_bf16_f32 v37, v37, s0
	global_store_short v[32:33], v50, off
	global_store_short v[32:33], v37, off offset:64
; #define PW(T, off) ((T*)(lndp(p.ws) + (off)))
; DEVI float bf2f(bf16 h) { return __uint_as_float(((unsigned)h) << 16); }
; DEVI float sigmf(float x) { return __builtin_amdgcn_rcpf(1.f + __expf(-x)); }
; DEVI float softplusf(float x) { return x > 20.f ? x : __logf(1.f + __expf(x)); }
; template <int EPI>
; DEVI void gemm_epi(const Params& p, const GJob& jb, f32x16 (&acc)[2][2], int rbase, int cbase, int lane) {
;     ...
;       const int row = rbase + i * 32 + accrow(r, lane);
;       if (row < M) {
; #pragma unroll
;         for (int j = 0; j < 2; ++j) {
;           const int col = cbase + j * 32 + (lane & 31);
;           const float v = acc[i][j][r];
;           if (EPI == EPI_SSD_IN) {
;             if (col < 2048) ((bf16*)(ar + S_ZB))[(size_t)row * 2048 + col] = f2bf(v);
;             else if (col < 6144) ((bf16*)(ar + S_XBC))[(size_t)row * 4096 + col - 2048] = f2bf(v);
;             else if (col < 6176) ((float*)(ar + S_DTRAW))[(size_t)row * 32 + col - 6144] = v;
;           } else if (EPI == EPI_RESID) {
;             PW(bf16, W_Z)[(size_t)row * 1024 + col] = f2bf(ALPHA * bf2f(PW(bf16, W_Xb)[(size_t)row * 1024 + col]) + v);
;           } else if (EPI == EPI_GU) {
;             ((bf16*)(ar + F_GU))[(size_t)row * 5632 + col] = f2bf(v);
;           } else if (EPI == EPI_BF16) {
;             ((bf16*)jb.of)[(size_t)row * 1024 + col] = f2bf(v);
;           } else if (EPI == EPI_F32) {
;             jb.of[(size_t)row * 1024 + col] = v;
;           } else if (EPI == EPI_RK_W1) {
;             if (col < 64) ((bf16*)(ar + R_HW))[(size_t)row * 64 + col] = f2bf(tanhfast(v));
;           } else if (EPI == EPI_RK_A1) {
;             if (col < 64) ((bf16*)(ar + R_HA))[(size_t)row * 64 + col] = f2bf(v);
;           } else if (EPI == EPI_RK_G1) {
;             if (col < 192) ((bf16*)(ar + R_HG))[(size_t)row * 192 + col] = f2bf(col < 160 ? sigmf(v) : 0.f);
;           } else if (EPI == EPI_RK_W2) {
;             const float z = i_rk_w0[col] + v;
;             const float wl = -softplusf(-z) - 0.5f;
;             ((float*)(ar + R_W))[(size_t)row * 1024 + col] = __expf(-__expf(wl));
;           } else if (EPI == EPI_RESID_TAIL) {
;             atomicAdd(PW(float, W_ZT) + (size_t)(row - 16384) * 1024 + col, v);
;           } else if (EPI == EPI_RK_A2) {
;             ((bf16*)(ar + R_A))[(size_t)row * 1024 + col] = f2bf(sigmf(i_rk_a0[col] + v));
.LBB0_590:
	s_or_b64 exec, exec, s[4:5]
	v_or_b32_e32 v37, 10, v69
	v_or_b32_e32 v32, v37, v68
	v_cmp_gt_i32_e32 vcc, s90, v32
	s_and_saveexec_b64 s[4:5], vcc
	s_cbranch_execz .LBB0_592
	v_lshl_add_u64 v[50:51], v[64:65], 2, s[2:3]
	v_mov_b32_e32 v33, v174
	s_nop 0
	v_mov_b32_e32 v50, v175
	v_add_f32_e32 v33, v38, v33
	v_add_f32_e32 v38, v54, v50
	v_mul_f32_e32 v33, 0xbfb8aa3b, v33
	v_mul_f32_e32 v38, 0xbfb8aa3b, v38
	v_exp_f32_e32 v50, v33
	v_exp_f32_e32 v38, v38
	v_ashrrev_i32_e32 v33, 31, v32
	v_lshlrev_b64 v[32:33], 11, v[32:33]
	v_add_f32_e32 v50, 1.0, v50
	v_add_f32_e32 v38, 1.0, v38
	v_rcp_f32_e32 v50, v50
	v_rcp_f32_e32 v38, v38
	v_lshl_add_u64 v[32:33], s[6:7], 0, v[32:33]
	v_lshl_add_u64 v[32:33], v[64:65], 1, v[32:33]
	v_cvt_pk_bf16_f32 v50, v50, s0
	v_cvt_pk_bf16_f32 v38, v38, s0
	global_store_short v[32:33], v50, off
	global_store_short v[32:33], v38, off offset:64
.LBB0_592:
	s_or_b64 exec, exec, s[4:5]
	v_or_b32_e32 v38, 11, v70
	v_or_b32_e32 v32, v68, v38
	v_cmp_gt_i32_e32 vcc, s90, v32
	s_and_saveexec_b64 s[4:5], vcc
	s_cbranch_execz .LBB0_594
	v_lshl_add_u64 v[50:51], v[64:65], 2, s[2:3]
	v_mov_b32_e32 v33, v174
	s_nop 0
	v_mov_b32_e32 v50, v175
	v_add_f32_e32 v33, v39, v33
	v_add_f32_e32 v39, v55, v50
	v_mul_f32_e32 v33, 0xbfb8aa3b, v33
	v_mul_f32_e32 v39, 0xbfb8aa3b, v39
	v_exp_f32_e32 v50, v33
	v_exp_f32_e32 v39, v39
	v_ashrrev_i32_e32 v33, 31, v32
	v_lshlrev_b64 v[32:33], 11, v[32:33]
	v_add_f32_e32 v50, 1.0, v50
	v_add_f32_e32 v39, 1.0, v39
	v_rcp_f32_e32 v50, v50
	v_rcp_f32_e32 v39, v39
	v_lshl_add_u64 v[32:33], s[6:7], 0, v[32:33]
	v_lshl_add_u64 v[32:33], v[64:65], 1, v[32:33]
	v_cvt_pk_bf16_f32 v50, v50, s0
	v_cvt_pk_bf16_f32 v39, v39, s0
	global_store_short v[32:33], v50, off
	global_store_short v[32:33], v39, off offset:64
.LBB0_594:
	s_or_b64 exec, exec, s[4:5]
	v_or_b32_e32 v39, 16, v69
	v_or_b32_e32 v32, v39, v68
	v_cmp_gt_i32_e32 vcc, s90, v32
	s_and_saveexec_b64 s[4:5], vcc
	s_cbranch_execz .LBB0_596
	v_lshl_add_u64 v[50:51], v[64:65], 2, s[2:3]
	v_mov_b32_e32 v33, v174
	s_nop 0
	v_mov_b32_e32 v50, v175
	v_add_f32_e32 v33, v40, v33
	v_add_f32_e32 v40, v56, v50
	v_mul_f32_e32 v33, 0xbfb8aa3b, v33
	v_mul_f32_e32 v40, 0xbfb8aa3b, v40
	v_exp_f32_e32 v50, v33
	v_exp_f32_e32 v40, v40
	v_ashrrev_i32_e32 v33, 31, v32
	v_lshlrev_b64 v[32:33], 11, v[32:33]
	v_add_f32_e32 v50, 1.0, v50
	v_add_f32_e32 v40, 1.0, v40
	v_rcp_f32_e32 v50, v50
	v_rcp_f32_e32 v40, v40
	v_lshl_add_u64 v[32:33], s[6:7], 0, v[32:33]
	v_lshl_add_u64 v[32:33], v[64:65], 1, v[32:33]
	v_cvt_pk_bf16_f32 v50, v50, s0
	v_cvt_pk_bf16_f32 v40, v40, s0
	global_store_short v[32:33], v50, off
	global_store_short v[32:33], v40, off offset:64
.LBB0_596:
	s_or_b64 exec, exec, s[4:5]
	v_or_b32_e32 v40, 17, v69
	v_or_b32_e32 v32, v40, v68
	v_cmp_gt_i32_e32 vcc, s90, v32
	s_and_saveexec_b64 s[4:5], vcc
	s_cbranch_execz .LBB0_598
	v_lshl_add_u64 v[50:51], v[64:65], 2, s[2:3]
	v_mov_b32_e32 v33, v174
	s_nop 0
	v_mov_b32_e32 v50, v175
	v_add_f32_e32 v33, v41, v33
	v_add_f32_e32 v41, v57, v50
	v_mul_f32_e32 v33, 0xbfb8aa3b, v33
	v_mul_f32_e32 v41, 0xbfb8aa3b, v41
	v_exp_f32_e32 v50, v33
	v_exp_f32_e32 v41, v41
	v_ashrrev_i32_e32 v33, 31, v32
	v_lshlrev_b64 v[32:33], 11, v[32:33]
	v_add_f32_e32 v50, 1.0, v50
	v_add_f32_e32 v41, 1.0, v41
	v_rcp_f32_e32 v50, v50
	v_rcp_f32_e32 v41, v41
	v_lshl_add_u64 v[32:33], s[6:7], 0, v[32:33]
	v_lshl_add_u64 v[32:33], v[64:65], 1, v[32:33]
	v_cvt_pk_bf16_f32 v50, v50, s0
	v_cvt_pk_bf16_f32 v41, v41, s0
	global_store_short v[32:33], v50, off
	global_store_short v[32:33], v41, off offset:64
.LBB0_598:
	s_or_b64 exec, exec, s[4:5]
	v_or_b32_e32 v41, 18, v69
	v_or_b32_e32 v32, v41, v68
	v_cmp_gt_i32_e32 vcc, s90, v32
	s_and_saveexec_b64 s[4:5], vcc
	s_cbranch_execz .LBB0_600
	v_lshl_add_u64 v[50:51], v[64:65], 2, s[2:3]
	v_mov_b32_e32 v33, v174
	s_nop 0
	v_mov_b32_e32 v50, v175
	v_add_f32_e32 v33, v42, v33
	v_add_f32_e32 v42, v58, v50
	v_mul_f32_e32 v33, 0xbfb8aa3b, v33
	v_mul_f32_e32 v42, 0xbfb8aa3b, v42
	v_exp_f32_e32 v50, v33
	v_exp_f32_e32 v42, v42
	v_ashrrev_i32_e32 v33, 31, v32
	v_lshlrev_b64 v[32:33], 11, v[32:33]
	v_add_f32_e32 v50, 1.0, v50
	v_add_f32_e32 v42, 1.0, v42
	v_rcp_f32_e32 v50, v50
	v_rcp_f32_e32 v42, v42
	v_lshl_add_u64 v[32:33], s[6:7], 0, v[32:33]
	v_lshl_add_u64 v[32:33], v[64:65], 1, v[32:33]
	v_cvt_pk_bf16_f32 v50, v50, s0
	v_cvt_pk_bf16_f32 v42, v42, s0
	global_store_short v[32:33], v50, off
	global_store_short v[32:33], v42, off offset:64
.LBB0_600:
	s_or_b64 exec, exec, s[4:5]
	v_or_b32_e32 v42, 19, v70
	v_or_b32_e32 v32, v68, v42
	v_cmp_gt_i32_e32 vcc, s90, v32
	s_and_saveexec_b64 s[4:5], vcc
	s_cbranch_execz .LBB0_602
	v_lshl_add_u64 v[50:51], v[64:65], 2, s[2:3]
	v_mov_b32_e32 v33, v174
	s_nop 0
	v_mov_b32_e32 v50, v175
	v_add_f32_e32 v33, v43, v33
	v_add_f32_e32 v43, v59, v50
	v_mul_f32_e32 v33, 0xbfb8aa3b, v33
	v_mul_f32_e32 v43, 0xbfb8aa3b, v43
	v_exp_f32_e32 v50, v33
	v_exp_f32_e32 v43, v43
	v_ashrrev_i32_e32 v33, 31, v32
	v_lshlrev_b64 v[32:33], 11, v[32:33]
	v_add_f32_e32 v50, 1.0, v50
	v_add_f32_e32 v43, 1.0, v43
	v_rcp_f32_e32 v50, v50
	v_rcp_f32_e32 v43, v43
	v_lshl_add_u64 v[32:33], s[6:7], 0, v[32:33]
	v_lshl_add_u64 v[32:33], v[64:65], 1, v[32:33]
	v_cvt_pk_bf16_f32 v50, v50, s0
	v_cvt_pk_bf16_f32 v43, v43, s0
	global_store_short v[32:33], v50, off
	global_store_short v[32:33], v43, off offset:64
; #define PW(T, off) ((T*)(lndp(p.ws) + (off)))
; DEVI float bf2f(bf16 h) { return __uint_as_float(((unsigned)h) << 16); }
; DEVI float sigmf(float x) { return __builtin_amdgcn_rcpf(1.f + __expf(-x)); }
; DEVI float softplusf(float x) { return x > 20.f ? x : __logf(1.f + __expf(x)); }
; template <int EPI>
; DEVI void gemm_epi(const Params& p, const GJob& jb, f32x16 (&acc)[2][2], int rbase, int cbase, int lane) {
;     ...
;       const int row = rbase + i * 32 + accrow(r, lane);
;       if (row < M) {
; #pragma unroll
;         for (int j = 0; j < 2; ++j) {
;           const int col = cbase + j * 32 + (lane & 31);
;           const float v = acc[i][j][r];
;           if (EPI == EPI_SSD_IN) {
;             if (col < 2048) ((bf16*)(ar + S_ZB))[(size_t)row * 2048 + col] = f2bf(v);
;             else if (col < 6144) ((bf16*)(ar + S_XBC))[(size_t)row * 4096 + col - 2048] = f2bf(v);
;             else if (col < 6176) ((float*)(ar + S_DTRAW))[(size_t)row * 32 + col - 6144] = v;
;           } else if (EPI == EPI_RESID) {
;             PW(bf16, W_Z)[(size_t)row * 1024 + col] = f2bf(ALPHA * bf2f(PW(bf16, W_Xb)[(size_t)row * 1024 + col]) + v);
;           } else if (EPI == EPI_GU) {
;             ((bf16*)(ar + F_GU))[(size_t)row * 5632 + col] = f2bf(v);
;           } else if (EPI == EPI_BF16) {
;             ((bf16*)jb.of)[(size_t)row * 1024 + col] = f2bf(v);
;           } else if (EPI == EPI_F32) {
;             jb.of[(size_t)row * 1024 + col] = v;
;           } else if (EPI == EPI_RK_W1) {
;             if (col < 64) ((bf16*)(ar + R_HW))[(size_t)row * 64 + col] = f2bf(tanhfast(v));
;           } else if (EPI == EPI_RK_A1) {
;             if (col < 64) ((bf16*)(ar + R_HA))[(size_t)row * 64 + col] = f2bf(v);
;           } else if (EPI == EPI_RK_G1) {
;             if (col < 192) ((bf16*)(ar + R_HG))[(size_t)row * 192 + col] = f2bf(col < 160 ? sigmf(v) : 0.f);
;           } else if (EPI == EPI_RK_W2) {
;             const float z = i_rk_w0[col] + v;
;             const float wl = -softplusf(-z) - 0.5f;
;             ((float*)(ar + R_W))[(size_t)row * 1024 + col] = __expf(-__expf(wl));
;           } else if (EPI == EPI_RESID_TAIL) {
;             atomicAdd(PW(float, W_ZT) + (size_t)(row - 16384) * 1024 + col, v);
;           } else if (EPI == EPI_RK_A2) {
;             ((bf16*)(ar + R_A))[(size_t)row * 1024 + col] = f2bf(sigmf(i_rk_a0[col] + v));
.LBB0_602:
	s_or_b64 exec, exec, s[4:5]
	v_or_b32_e32 v43, 24, v69
	v_or_b32_e32 v32, v43, v68
	v_cmp_gt_i32_e32 vcc, s90, v32
	s_and_saveexec_b64 s[4:5], vcc
	s_cbranch_execz .LBB0_604
	v_lshl_add_u64 v[50:51], v[64:65], 2, s[2:3]
	v_mov_b32_e32 v33, v174
	s_nop 0
	v_mov_b32_e32 v50, v175
	v_add_f32_e32 v33, v44, v33
	v_add_f32_e32 v44, v60, v50
	v_mul_f32_e32 v33, 0xbfb8aa3b, v33
	v_mul_f32_e32 v44, 0xbfb8aa3b, v44
	v_exp_f32_e32 v50, v33
	v_exp_f32_e32 v44, v44
	v_ashrrev_i32_e32 v33, 31, v32
	v_lshlrev_b64 v[32:33], 11, v[32:33]
	v_add_f32_e32 v50, 1.0, v50
	v_add_f32_e32 v44, 1.0, v44
	v_rcp_f32_e32 v50, v50
	v_rcp_f32_e32 v44, v44
	v_lshl_add_u64 v[32:33], s[6:7], 0, v[32:33]
	v_lshl_add_u64 v[32:33], v[64:65], 1, v[32:33]
	v_cvt_pk_bf16_f32 v50, v50, s0
	v_cvt_pk_bf16_f32 v44, v44, s0
	global_store_short v[32:33], v50, off
	global_store_short v[32:33], v44, off offset:64
.LBB0_604:
	s_or_b64 exec, exec, s[4:5]
	v_or_b32_e32 v44, 25, v69
	v_or_b32_e32 v32, v44, v68
	v_cmp_gt_i32_e32 vcc, s90, v32
	s_and_saveexec_b64 s[4:5], vcc
	s_cbranch_execz .LBB0_606
	v_lshl_add_u64 v[50:51], v[64:65], 2, s[2:3]
	v_mov_b32_e32 v33, v174
	s_nop 0
	v_mov_b32_e32 v50, v175
	v_add_f32_e32 v33, v45, v33
	v_add_f32_e32 v45, v61, v50
	v_mul_f32_e32 v33, 0xbfb8aa3b, v33
	v_mul_f32_e32 v45, 0xbfb8aa3b, v45
	v_exp_f32_e32 v50, v33
	v_exp_f32_e32 v45, v45
	v_ashrrev_i32_e32 v33, 31, v32
	v_lshlrev_b64 v[32:33], 11, v[32:33]
	v_add_f32_e32 v50, 1.0, v50
	v_add_f32_e32 v45, 1.0, v45
	v_rcp_f32_e32 v50, v50
	v_rcp_f32_e32 v45, v45
	v_lshl_add_u64 v[32:33], s[6:7], 0, v[32:33]
	v_lshl_add_u64 v[32:33], v[64:65], 1, v[32:33]
	v_cvt_pk_bf16_f32 v50, v50, s0
	v_cvt_pk_bf16_f32 v45, v45, s0
	global_store_short v[32:33], v50, off
	global_store_short v[32:33], v45, off offset:64
.LBB0_606:
	s_or_b64 exec, exec, s[4:5]
	v_or_b32_e32 v45, 26, v69
	v_or_b32_e32 v32, v45, v68
	v_cmp_gt_i32_e32 vcc, s90, v32
	s_and_saveexec_b64 s[4:5], vcc
	s_cbranch_execz .LBB0_608
	v_lshl_add_u64 v[50:51], v[64:65], 2, s[2:3]
	v_mov_b32_e32 v33, v174
	s_nop 0
	v_mov_b32_e32 v50, v175
	v_add_f32_e32 v33, v46, v33
	v_add_f32_e32 v46, v62, v50
	v_mul_f32_e32 v33, 0xbfb8aa3b, v33
	v_mul_f32_e32 v46, 0xbfb8aa3b, v46
	v_exp_f32_e32 v50, v33
	v_exp_f32_e32 v46, v46
	v_ashrrev_i32_e32 v33, 31, v32
	v_lshlrev_b64 v[32:33], 11, v[32:33]
	v_add_f32_e32 v50, 1.0, v50
	v_add_f32_e32 v46, 1.0, v46
	v_rcp_f32_e32 v50, v50
	v_rcp_f32_e32 v46, v46
	v_lshl_add_u64 v[32:33], s[6:7], 0, v[32:33]
	v_lshl_add_u64 v[32:33], v[64:65], 1, v[32:33]
	v_cvt_pk_bf16_f32 v50, v50, s0
	v_cvt_pk_bf16_f32 v46, v46, s0
	global_store_short v[32:33], v50, off
	global_store_short v[32:33], v46, off offset:64
.LBB0_608:
	s_or_b64 exec, exec, s[4:5]
	v_or_b32_e32 v46, 27, v70
	v_or_b32_e32 v32, v68, v46
	v_cmp_gt_i32_e32 vcc, s90, v32
	s_and_saveexec_b64 s[4:5], vcc
	s_cbranch_execz .LBB0_610
	v_lshl_add_u64 v[50:51], v[64:65], 2, s[2:3]
	v_mov_b32_e32 v33, v174
	s_nop 0
	v_mov_b32_e32 v50, v175
	v_add_f32_e32 v33, v47, v33
	v_add_f32_e32 v47, v63, v50
	v_mul_f32_e32 v33, 0xbfb8aa3b, v33
	v_mul_f32_e32 v47, 0xbfb8aa3b, v47
	v_exp_f32_e32 v50, v33
	v_exp_f32_e32 v47, v47
	v_ashrrev_i32_e32 v33, 31, v32
	v_lshlrev_b64 v[32:33], 11, v[32:33]
	v_add_f32_e32 v50, 1.0, v50
	v_add_f32_e32 v47, 1.0, v47
	v_rcp_f32_e32 v50, v50
	v_rcp_f32_e32 v47, v47
	v_lshl_add_u64 v[32:33], s[6:7], 0, v[32:33]
	v_lshl_add_u64 v[32:33], v[64:65], 1, v[32:33]
	v_cvt_pk_bf16_f32 v50, v50, s0
	v_cvt_pk_bf16_f32 v47, v47, s0
	global_store_short v[32:33], v50, off
	global_store_short v[32:33], v47, off offset:64
.LBB0_610:
	s_or_b64 exec, exec, s[4:5]
	v_or_b32_e32 v47, 32, v68
	v_or_b32_e32 v32, v47, v69
	v_cmp_gt_i32_e32 vcc, s90, v32
	s_and_saveexec_b64 s[4:5], vcc
	s_cbranch_execz .LBB0_612
	v_lshl_add_u64 v[50:51], v[64:65], 2, s[2:3]
	v_mov_b32_e32 v33, v174
	s_nop 0
	v_mov_b32_e32 v50, v175
	v_add_f32_e32 v16, v16, v33
	v_add_f32_e32 v0, v0, v50
	v_mul_f32_e32 v16, 0xbfb8aa3b, v16
	v_mul_f32_e32 v0, 0xbfb8aa3b, v0
	v_exp_f32_e32 v16, v16
	v_exp_f32_e32 v0, v0
	v_ashrrev_i32_e32 v33, 31, v32
	v_lshlrev_b64 v[32:33], 11, v[32:33]
	v_add_f32_e32 v16, 1.0, v16
	v_add_f32_e32 v0, 1.0, v0
	v_rcp_f32_e32 v16, v16
	v_rcp_f32_e32 v0, v0
	v_lshl_add_u64 v[32:33], s[6:7], 0, v[32:33]
	v_lshl_add_u64 v[32:33], v[64:65], 1, v[32:33]
	v_cvt_pk_bf16_f32 v16, v16, s0
	v_cvt_pk_bf16_f32 v0, v0, s0
	global_store_short v[32:33], v16, off
	global_store_short v[32:33], v0, off offset:64
.LBB0_612:
	s_or_b64 exec, exec, s[4:5]
	v_or_b32_e32 v0, v47, v48
	v_cmp_gt_i32_e32 vcc, s90, v0
	s_and_saveexec_b64 s[4:5], vcc
	s_cbranch_execz .LBB0_614
	v_lshl_add_u64 v[32:33], v[64:65], 2, s[2:3]
	v_mov_b32_e32 v16, v174
	s_nop 0
	v_mov_b32_e32 v32, v175
	v_add_f32_e32 v16, v17, v16
	v_add_f32_e32 v1, v1, v32
	v_mul_f32_e32 v16, 0xbfb8aa3b, v16
	v_mul_f32_e32 v1, 0xbfb8aa3b, v1
	v_exp_f32_e32 v16, v16
	v_exp_f32_e32 v17, v1
	v_ashrrev_i32_e32 v1, 31, v0
	v_lshlrev_b64 v[0:1], 11, v[0:1]
	v_add_f32_e32 v16, 1.0, v16
	v_add_f32_e32 v17, 1.0, v17
	v_rcp_f32_e32 v16, v16
	v_rcp_f32_e32 v17, v17
	v_lshl_add_u64 v[0:1], s[6:7], 0, v[0:1]
	v_lshl_add_u64 v[0:1], v[64:65], 1, v[0:1]
	v_cvt_pk_bf16_f32 v16, v16, s0
	v_cvt_pk_bf16_f32 v17, v17, s0
	global_store_short v[0:1], v16, off
	global_store_short v[0:1], v17, off offset:64
; #define PW(T, off) ((T*)(lndp(p.ws) + (off)))
; DEVI float bf2f(bf16 h) { return __uint_as_float(((unsigned)h) << 16); }
; DEVI float sigmf(float x) { return __builtin_amdgcn_rcpf(1.f + __expf(-x)); }
; DEVI float softplusf(float x) { return x > 20.f ? x : __logf(1.f + __expf(x)); }
; template <int EPI>
; DEVI void gemm_epi(const Params& p, const GJob& jb, f32x16 (&acc)[2][2], int rbase, int cbase, int lane) {
;     ...
;       const int row = rbase + i * 32 + accrow(r, lane);
;       if (row < M) {
; #pragma unroll
;         for (int j = 0; j < 2; ++j) {
;           const int col = cbase + j * 32 + (lane & 31);
;           const float v = acc[i][j][r];
;           if (EPI == EPI_SSD_IN) {
;             if (col < 2048) ((bf16*)(ar + S_ZB))[(size_t)row * 2048 + col] = f2bf(v);
;             else if (col < 6144) ((bf16*)(ar + S_XBC))[(size_t)row * 4096 + col - 2048] = f2bf(v);
;             else if (col < 6176) ((float*)(ar + S_DTRAW))[(size_t)row * 32 + col - 6144] = v;
;           } else if (EPI == EPI_RESID) {
;             PW(bf16, W_Z)[(size_t)row * 1024 + col] = f2bf(ALPHA * bf2f(PW(bf16, W_Xb)[(size_t)row * 1024 + col]) + v);
;           } else if (EPI == EPI_GU) {
;             ((bf16*)(ar + F_GU))[(size_t)row * 5632 + col] = f2bf(v);
;           } else if (EPI == EPI_BF16) {
;             ((bf16*)jb.of)[(size_t)row * 1024 + col] = f2bf(v);
;           } else if (EPI == EPI_F32) {
;             jb.of[(size_t)row * 1024 + col] = v;
;           } else if (EPI == EPI_RK_W1) {
;             if (col < 64) ((bf16*)(ar + R_HW))[(size_t)row * 64 + col] = f2bf(tanhfast(v));
;           } else if (EPI == EPI_RK_A1) {
;             if (col < 64) ((bf16*)(ar + R_HA))[(size_t)row * 64 + col] = f2bf(v);
;           } else if (EPI == EPI_RK_G1) {
;             if (col < 192) ((bf16*)(ar + R_HG))[(size_t)row * 192 + col] = f2bf(col < 160 ? sigmf(v) : 0.f);
;           } else if (EPI == EPI_RK_W2) {
;             const float z = i_rk_w0[col] + v;
;             const float wl = -softplusf(-z) - 0.5f;
;             ((float*)(ar + R_W))[(size_t)row * 1024 + col] = __expf(-__expf(wl));
;           } else if (EPI == EPI_RESID_TAIL) {
;             atomicAdd(PW(float, W_ZT) + (size_t)(row - 16384) * 1024 + col, v);
;           } else if (EPI == EPI_RK_A2) {
;             ((bf16*)(ar + R_A))[(size_t)row * 1024 + col] = f2bf(sigmf(i_rk_a0[col] + v));
.LBB0_614:
	s_or_b64 exec, exec, s[4:5]
	v_or_b32_e32 v0, v47, v49
	v_cmp_gt_i32_e32 vcc, s90, v0
	s_and_saveexec_b64 s[4:5], vcc
	s_cbranch_execz .LBB0_616
	v_lshl_add_u64 v[16:17], v[64:65], 2, s[2:3]
	v_mov_b32_e32 v1, v174
	s_nop 0
	v_mov_b32_e32 v16, v175
	v_add_f32_e32 v1, v18, v1
	v_add_f32_e32 v2, v2, v16
	v_mul_f32_e32 v1, 0xbfb8aa3b, v1
	v_mul_f32_e32 v2, 0xbfb8aa3b, v2
	v_exp_f32_e32 v16, v1
	v_exp_f32_e32 v2, v2
	v_ashrrev_i32_e32 v1, 31, v0
	v_lshlrev_b64 v[0:1], 11, v[0:1]
	v_add_f32_e32 v16, 1.0, v16
	v_add_f32_e32 v2, 1.0, v2
	v_rcp_f32_e32 v16, v16
	v_rcp_f32_e32 v2, v2
	v_lshl_add_u64 v[0:1], s[6:7], 0, v[0:1]
	v_lshl_add_u64 v[0:1], v[64:65], 1, v[0:1]
	v_cvt_pk_bf16_f32 v16, v16, s0
	v_cvt_pk_bf16_f32 v2, v2, s0
	global_store_short v[0:1], v16, off
	global_store_short v[0:1], v2, off offset:64
.LBB0_616:
	s_or_b64 exec, exec, s[4:5]
	v_or_b32_e32 v0, v47, v34
	v_cmp_gt_i32_e32 vcc, s90, v0
	s_and_saveexec_b64 s[4:5], vcc
	s_cbranch_execz .LBB0_618
	v_lshl_add_u64 v[16:17], v[64:65], 2, s[2:3]
	v_mov_b32_e32 v1, v174
	v_mov_b32_e32 v2, v175
	v_add_f32_e32 v1, v19, v1
	v_add_f32_e32 v2, v3, v2
	v_mul_f32_e32 v1, 0xbfb8aa3b, v1
	v_mul_f32_e32 v2, 0xbfb8aa3b, v2
	v_exp_f32_e32 v3, v1
	v_exp_f32_e32 v2, v2
	v_ashrrev_i32_e32 v1, 31, v0
	v_lshlrev_b64 v[0:1], 11, v[0:1]
	v_add_f32_e32 v3, 1.0, v3
	v_add_f32_e32 v2, 1.0, v2
	v_rcp_f32_e32 v3, v3
	v_rcp_f32_e32 v2, v2
	v_lshl_add_u64 v[0:1], s[6:7], 0, v[0:1]
	v_lshl_add_u64 v[0:1], v[64:65], 1, v[0:1]
	v_cvt_pk_bf16_f32 v3, v3, s0
	v_cvt_pk_bf16_f32 v2, v2, s0
	global_store_short v[0:1], v3, off
	global_store_short v[0:1], v2, off offset:64
.LBB0_618:
	s_or_b64 exec, exec, s[4:5]
	v_or_b32_e32 v0, v47, v35
	v_cmp_gt_i32_e32 vcc, s90, v0
	s_and_saveexec_b64 s[4:5], vcc
	s_cbranch_execz .LBB0_620
	v_lshl_add_u64 v[2:3], v[64:65], 2, s[2:3]
	v_mov_b32_e32 v1, v174
	s_nop 0
	v_mov_b32_e32 v2, v175
	v_add_f32_e32 v1, v20, v1
	v_add_f32_e32 v2, v4, v2
	v_mul_f32_e32 v1, 0xbfb8aa3b, v1
	v_mul_f32_e32 v2, 0xbfb8aa3b, v2
	v_exp_f32_e32 v3, v1
	v_exp_f32_e32 v2, v2
	v_ashrrev_i32_e32 v1, 31, v0
	v_lshlrev_b64 v[0:1], 11, v[0:1]
	v_add_f32_e32 v3, 1.0, v3
	v_add_f32_e32 v2, 1.0, v2
	v_rcp_f32_e32 v3, v3
	v_rcp_f32_e32 v2, v2
	v_lshl_add_u64 v[0:1], s[6:7], 0, v[0:1]
	v_lshl_add_u64 v[0:1], v[64:65], 1, v[0:1]
	v_cvt_pk_bf16_f32 v3, v3, s0
	v_cvt_pk_bf16_f32 v2, v2, s0
	global_store_short v[0:1], v3, off
	global_store_short v[0:1], v2, off offset:64
.LBB0_620:
	s_or_b64 exec, exec, s[4:5]
	v_or_b32_e32 v0, v47, v36
	v_cmp_gt_i32_e32 vcc, s90, v0
	s_and_saveexec_b64 s[4:5], vcc
	s_cbranch_execz .LBB0_622
	v_lshl_add_u64 v[2:3], v[64:65], 2, s[2:3]
	v_mov_b32_e32 v1, v174
	s_nop 0
	v_mov_b32_e32 v2, v175
	v_add_f32_e32 v1, v21, v1
	v_add_f32_e32 v2, v5, v2
	v_mul_f32_e32 v1, 0xbfb8aa3b, v1
	v_mul_f32_e32 v2, 0xbfb8aa3b, v2
	v_exp_f32_e32 v3, v1
	v_exp_f32_e32 v2, v2
	v_ashrrev_i32_e32 v1, 31, v0
	v_lshlrev_b64 v[0:1], 11, v[0:1]
	v_add_f32_e32 v3, 1.0, v3
	v_add_f32_e32 v2, 1.0, v2
	v_rcp_f32_e32 v3, v3
	v_rcp_f32_e32 v2, v2
	v_lshl_add_u64 v[0:1], s[6:7], 0, v[0:1]
	v_lshl_add_u64 v[0:1], v[64:65], 1, v[0:1]
	v_cvt_pk_bf16_f32 v3, v3, s0
	v_cvt_pk_bf16_f32 v2, v2, s0
	global_store_short v[0:1], v3, off
	global_store_short v[0:1], v2, off offset:64
.LBB0_622:
	s_or_b64 exec, exec, s[4:5]
	v_or_b32_e32 v0, v47, v37
	v_cmp_gt_i32_e32 vcc, s90, v0
	s_and_saveexec_b64 s[4:5], vcc
	s_cbranch_execz .LBB0_624
	v_lshl_add_u64 v[2:3], v[64:65], 2, s[2:3]
	v_mov_b32_e32 v1, v174
	s_nop 0
	v_mov_b32_e32 v2, v175
	v_add_f32_e32 v1, v22, v1
	v_add_f32_e32 v2, v6, v2
	v_mul_f32_e32 v1, 0xbfb8aa3b, v1
	v_mul_f32_e32 v2, 0xbfb8aa3b, v2
	v_exp_f32_e32 v3, v1
	v_exp_f32_e32 v2, v2
	v_ashrrev_i32_e32 v1, 31, v0
	v_lshlrev_b64 v[0:1], 11, v[0:1]
	v_add_f32_e32 v3, 1.0, v3
	v_add_f32_e32 v2, 1.0, v2
	v_rcp_f32_e32 v3, v3
	v_rcp_f32_e32 v2, v2
	v_lshl_add_u64 v[0:1], s[6:7], 0, v[0:1]
	v_lshl_add_u64 v[0:1], v[64:65], 1, v[0:1]
	v_cvt_pk_bf16_f32 v3, v3, s0
	v_cvt_pk_bf16_f32 v2, v2, s0
	global_store_short v[0:1], v3, off
	global_store_short v[0:1], v2, off offset:64
.LBB0_624:
	s_or_b64 exec, exec, s[4:5]
	v_or_b32_e32 v0, v47, v38
	v_cmp_gt_i32_e32 vcc, s90, v0
	s_and_saveexec_b64 s[4:5], vcc
	s_cbranch_execz .LBB0_626
	v_lshl_add_u64 v[2:3], v[64:65], 2, s[2:3]
	v_mov_b32_e32 v1, v174
	s_nop 0
	v_mov_b32_e32 v2, v175
	v_add_f32_e32 v1, v23, v1
	v_add_f32_e32 v2, v7, v2
	v_mul_f32_e32 v1, 0xbfb8aa3b, v1
	v_mul_f32_e32 v2, 0xbfb8aa3b, v2
	v_exp_f32_e32 v3, v1
	v_exp_f32_e32 v2, v2
	v_ashrrev_i32_e32 v1, 31, v0
	v_lshlrev_b64 v[0:1], 11, v[0:1]
	v_add_f32_e32 v3, 1.0, v3
	v_add_f32_e32 v2, 1.0, v2
	v_rcp_f32_e32 v3, v3
	v_rcp_f32_e32 v2, v2
	v_lshl_add_u64 v[0:1], s[6:7], 0, v[0:1]
	v_lshl_add_u64 v[0:1], v[64:65], 1, v[0:1]
	v_cvt_pk_bf16_f32 v3, v3, s0
	v_cvt_pk_bf16_f32 v2, v2, s0
	global_store_short v[0:1], v3, off
	global_store_short v[0:1], v2, off offset:64
.LBB0_626:
	s_or_b64 exec, exec, s[4:5]
	v_or_b32_e32 v0, v47, v39
	v_cmp_gt_i32_e32 vcc, s90, v0
	s_and_saveexec_b64 s[4:5], vcc
	s_cbranch_execz .LBB0_628
	v_lshl_add_u64 v[2:3], v[64:65], 2, s[2:3]
	v_mov_b32_e32 v1, v174
	s_nop 0
	v_mov_b32_e32 v2, v175
	v_add_f32_e32 v1, v24, v1
	v_add_f32_e32 v2, v8, v2
	v_mul_f32_e32 v1, 0xbfb8aa3b, v1
	v_mul_f32_e32 v2, 0xbfb8aa3b, v2
	v_exp_f32_e32 v3, v1
	v_exp_f32_e32 v2, v2
	v_ashrrev_i32_e32 v1, 31, v0
	v_lshlrev_b64 v[0:1], 11, v[0:1]
	v_add_f32_e32 v3, 1.0, v3
	v_add_f32_e32 v2, 1.0, v2
	v_rcp_f32_e32 v3, v3
	v_rcp_f32_e32 v2, v2
	v_lshl_add_u64 v[0:1], s[6:7], 0, v[0:1]
	v_lshl_add_u64 v[0:1], v[64:65], 1, v[0:1]
	v_cvt_pk_bf16_f32 v3, v3, s0
	v_cvt_pk_bf16_f32 v2, v2, s0
	global_store_short v[0:1], v3, off
	global_store_short v[0:1], v2, off offset:64
; #define PW(T, off) ((T*)(lndp(p.ws) + (off)))
; DEVI float bf2f(bf16 h) { return __uint_as_float(((unsigned)h) << 16); }
; DEVI float sigmf(float x) { return __builtin_amdgcn_rcpf(1.f + __expf(-x)); }
; DEVI float softplusf(float x) { return x > 20.f ? x : __logf(1.f + __expf(x)); }
; template <int EPI>
; DEVI void gemm_epi(const Params& p, const GJob& jb, f32x16 (&acc)[2][2], int rbase, int cbase, int lane) {
;     ...
;       const int row = rbase + i * 32 + accrow(r, lane);
;       if (row < M) {
; #pragma unroll
;         for (int j = 0; j < 2; ++j) {
;           const int col = cbase + j * 32 + (lane & 31);
;           const float v = acc[i][j][r];
;           if (EPI == EPI_SSD_IN) {
;             if (col < 2048) ((bf16*)(ar + S_ZB))[(size_t)row * 2048 + col] = f2bf(v);
;             else if (col < 6144) ((bf16*)(ar + S_XBC))[(size_t)row * 4096 + col - 2048] = f2bf(v);
;             else if (col < 6176) ((float*)(ar + S_DTRAW))[(size_t)row * 32 + col - 6144] = v;
;           } else if (EPI == EPI_RESID) {
;             PW(bf16, W_Z)[(size_t)row * 1024 + col] = f2bf(ALPHA * bf2f(PW(bf16, W_Xb)[(size_t)row * 1024 + col]) + v);
;           } else if (EPI == EPI_GU) {
;             ((bf16*)(ar + F_GU))[(size_t)row * 5632 + col] = f2bf(v);
;           } else if (EPI == EPI_BF16) {
;             ((bf16*)jb.of)[(size_t)row * 1024 + col] = f2bf(v);
;           } else if (EPI == EPI_F32) {
;             jb.of[(size_t)row * 1024 + col] = v;
;           } else if (EPI == EPI_RK_W1) {
;             if (col < 64) ((bf16*)(ar + R_HW))[(size_t)row * 64 + col] = f2bf(tanhfast(v));
;           } else if (EPI == EPI_RK_A1) {
;             if (col < 64) ((bf16*)(ar + R_HA))[(size_t)row * 64 + col] = f2bf(v);
;           } else if (EPI == EPI_RK_G1) {
;             if (col < 192) ((bf16*)(ar + R_HG))[(size_t)row * 192 + col] = f2bf(col < 160 ? sigmf(v) : 0.f);
;           } else if (EPI == EPI_RK_W2) {
;             const float z = i_rk_w0[col] + v;
;             const float wl = -softplusf(-z) - 0.5f;
;             ((float*)(ar + R_W))[(size_t)row * 1024 + col] = __expf(-__expf(wl));
;           } else if (EPI == EPI_RESID_TAIL) {
;             atomicAdd(PW(float, W_ZT) + (size_t)(row - 16384) * 1024 + col, v);
;           } else if (EPI == EPI_RK_A2) {
;             ((bf16*)(ar + R_A))[(size_t)row * 1024 + col] = f2bf(sigmf(i_rk_a0[col] + v));
.LBB0_628:
	s_or_b64 exec, exec, s[4:5]
	v_or_b32_e32 v0, v47, v40
	v_cmp_gt_i32_e32 vcc, s90, v0
	s_and_saveexec_b64 s[4:5], vcc
	s_cbranch_execz .LBB0_630
	v_lshl_add_u64 v[2:3], v[64:65], 2, s[2:3]
	v_mov_b32_e32 v1, v174
	s_nop 0
	v_mov_b32_e32 v2, v175
	v_add_f32_e32 v1, v25, v1
	v_add_f32_e32 v2, v9, v2
	v_mul_f32_e32 v1, 0xbfb8aa3b, v1
	v_mul_f32_e32 v2, 0xbfb8aa3b, v2
	v_exp_f32_e32 v3, v1
	v_exp_f32_e32 v2, v2
	v_ashrrev_i32_e32 v1, 31, v0
	v_lshlrev_b64 v[0:1], 11, v[0:1]
	v_add_f32_e32 v3, 1.0, v3
	v_add_f32_e32 v2, 1.0, v2
	v_rcp_f32_e32 v3, v3
	v_rcp_f32_e32 v2, v2
	v_lshl_add_u64 v[0:1], s[6:7], 0, v[0:1]
	v_lshl_add_u64 v[0:1], v[64:65], 1, v[0:1]
	v_cvt_pk_bf16_f32 v3, v3, s0
	v_cvt_pk_bf16_f32 v2, v2, s0
	global_store_short v[0:1], v3, off
	global_store_short v[0:1], v2, off offset:64
.LBB0_630:
	s_or_b64 exec, exec, s[4:5]
	v_or_b32_e32 v0, v47, v41
	v_cmp_gt_i32_e32 vcc, s90, v0
	s_and_saveexec_b64 s[4:5], vcc
	s_cbranch_execz .LBB0_632
	v_lshl_add_u64 v[2:3], v[64:65], 2, s[2:3]
	v_mov_b32_e32 v1, v174
	s_nop 0
	v_mov_b32_e32 v2, v175
	v_add_f32_e32 v1, v26, v1
	v_add_f32_e32 v2, v10, v2
	v_mul_f32_e32 v1, 0xbfb8aa3b, v1
	v_mul_f32_e32 v2, 0xbfb8aa3b, v2
	v_exp_f32_e32 v3, v1
	v_exp_f32_e32 v2, v2
	v_ashrrev_i32_e32 v1, 31, v0
	v_lshlrev_b64 v[0:1], 11, v[0:1]
	v_add_f32_e32 v3, 1.0, v3
	v_add_f32_e32 v2, 1.0, v2
	v_rcp_f32_e32 v3, v3
	v_rcp_f32_e32 v2, v2
	v_lshl_add_u64 v[0:1], s[6:7], 0, v[0:1]
	v_lshl_add_u64 v[0:1], v[64:65], 1, v[0:1]
	v_cvt_pk_bf16_f32 v3, v3, s0
	v_cvt_pk_bf16_f32 v2, v2, s0
	global_store_short v[0:1], v3, off
	global_store_short v[0:1], v2, off offset:64
.LBB0_632:
	s_or_b64 exec, exec, s[4:5]
	v_or_b32_e32 v0, v47, v42
	v_cmp_gt_i32_e32 vcc, s90, v0
	s_and_saveexec_b64 s[4:5], vcc
	s_cbranch_execz .LBB0_634
	v_lshl_add_u64 v[2:3], v[64:65], 2, s[2:3]
	v_mov_b32_e32 v1, v174
	s_nop 0
	v_mov_b32_e32 v2, v175
	v_add_f32_e32 v1, v27, v1
	v_add_f32_e32 v2, v11, v2
	v_mul_f32_e32 v1, 0xbfb8aa3b, v1
	v_mul_f32_e32 v2, 0xbfb8aa3b, v2
	v_exp_f32_e32 v3, v1
	v_exp_f32_e32 v2, v2
	v_ashrrev_i32_e32 v1, 31, v0
	v_lshlrev_b64 v[0:1], 11, v[0:1]
	v_add_f32_e32 v3, 1.0, v3
	v_add_f32_e32 v2, 1.0, v2
	v_rcp_f32_e32 v3, v3
	v_rcp_f32_e32 v2, v2
	v_lshl_add_u64 v[0:1], s[6:7], 0, v[0:1]
	v_lshl_add_u64 v[0:1], v[64:65], 1, v[0:1]
	v_cvt_pk_bf16_f32 v3, v3, s0
	v_cvt_pk_bf16_f32 v2, v2, s0
	global_store_short v[0:1], v3, off
	global_store_short v[0:1], v2, off offset:64
.LBB0_634:
	s_or_b64 exec, exec, s[4:5]
	v_or_b32_e32 v0, v47, v43
	v_cmp_gt_i32_e32 vcc, s90, v0
	s_and_saveexec_b64 s[4:5], vcc
	s_cbranch_execz .LBB0_636
	v_lshl_add_u64 v[2:3], v[64:65], 2, s[2:3]
	v_mov_b32_e32 v1, v174
	s_nop 0
	v_mov_b32_e32 v2, v175
	v_add_f32_e32 v1, v28, v1
	v_add_f32_e32 v2, v12, v2
	v_mul_f32_e32 v1, 0xbfb8aa3b, v1
	v_mul_f32_e32 v2, 0xbfb8aa3b, v2
	v_exp_f32_e32 v3, v1
	v_exp_f32_e32 v2, v2
	v_ashrrev_i32_e32 v1, 31, v0
	v_lshlrev_b64 v[0:1], 11, v[0:1]
	v_add_f32_e32 v3, 1.0, v3
	v_add_f32_e32 v2, 1.0, v2
	v_rcp_f32_e32 v3, v3
	v_rcp_f32_e32 v2, v2
	v_lshl_add_u64 v[0:1], s[6:7], 0, v[0:1]
	v_lshl_add_u64 v[0:1], v[64:65], 1, v[0:1]
	v_cvt_pk_bf16_f32 v3, v3, s0
	v_cvt_pk_bf16_f32 v2, v2, s0
	global_store_short v[0:1], v3, off
	global_store_short v[0:1], v2, off offset:64
.LBB0_636:
	s_or_b64 exec, exec, s[4:5]
	v_or_b32_e32 v0, v47, v44
	v_cmp_gt_i32_e32 vcc, s90, v0
	s_and_saveexec_b64 s[4:5], vcc
	s_cbranch_execz .LBB0_638
	v_lshl_add_u64 v[2:3], v[64:65], 2, s[2:3]
	v_mov_b32_e32 v1, v174
	s_nop 0
	v_mov_b32_e32 v2, v175
	v_add_f32_e32 v1, v29, v1
	v_add_f32_e32 v2, v13, v2
	v_mul_f32_e32 v1, 0xbfb8aa3b, v1
	v_mul_f32_e32 v2, 0xbfb8aa3b, v2
	v_exp_f32_e32 v3, v1
	v_exp_f32_e32 v2, v2
	v_ashrrev_i32_e32 v1, 31, v0
	v_lshlrev_b64 v[0:1], 11, v[0:1]
	v_add_f32_e32 v3, 1.0, v3
	v_add_f32_e32 v2, 1.0, v2
	v_rcp_f32_e32 v3, v3
	v_rcp_f32_e32 v2, v2
	v_lshl_add_u64 v[0:1], s[6:7], 0, v[0:1]
	v_lshl_add_u64 v[0:1], v[64:65], 1, v[0:1]
	v_cvt_pk_bf16_f32 v3, v3, s0
	v_cvt_pk_bf16_f32 v2, v2, s0
	global_store_short v[0:1], v3, off
	global_store_short v[0:1], v2, off offset:64
.LBB0_638:
	s_or_b64 exec, exec, s[4:5]
	v_or_b32_e32 v0, v47, v45
	v_cmp_gt_i32_e32 vcc, s90, v0
	s_and_saveexec_b64 s[4:5], vcc
	s_cbranch_execz .LBB0_640
	v_lshl_add_u64 v[2:3], v[64:65], 2, s[2:3]
	v_mov_b32_e32 v1, v174
	s_nop 0
	v_mov_b32_e32 v2, v175
	v_add_f32_e32 v1, v30, v1
	v_add_f32_e32 v2, v14, v2
	v_mul_f32_e32 v1, 0xbfb8aa3b, v1
	v_mul_f32_e32 v2, 0xbfb8aa3b, v2
	v_exp_f32_e32 v3, v1
	v_exp_f32_e32 v2, v2
	v_ashrrev_i32_e32 v1, 31, v0
	v_lshlrev_b64 v[0:1], 11, v[0:1]
	v_add_f32_e32 v3, 1.0, v3
	v_add_f32_e32 v2, 1.0, v2
	v_rcp_f32_e32 v3, v3
	v_rcp_f32_e32 v2, v2
	v_lshl_add_u64 v[0:1], s[6:7], 0, v[0:1]
	v_lshl_add_u64 v[0:1], v[64:65], 1, v[0:1]
	v_cvt_pk_bf16_f32 v3, v3, s0
	v_cvt_pk_bf16_f32 v2, v2, s0
	global_store_short v[0:1], v3, off
	global_store_short v[0:1], v2, off offset:64
.LBB0_640:
	s_or_b64 exec, exec, s[4:5]
	v_or_b32_e32 v0, v47, v46
	v_cmp_gt_i32_e32 vcc, s90, v0
	s_and_saveexec_b64 s[4:5], vcc
	s_cbranch_execz .LBB0_355
	v_lshl_add_u64 v[2:3], v[64:65], 2, s[2:3]
	v_mov_b32_e32 v4, v174
	v_ashrrev_i32_e32 v1, 31, v0
	v_mov_b32_e32 v2, v175
	v_lshlrev_b64 v[0:1], 11, v[0:1]
	v_lshl_add_u64 v[0:1], s[6:7], 0, v[0:1]
	v_lshl_add_u64 v[0:1], v[64:65], 1, v[0:1]
	v_add_f32_e32 v4, v31, v4
	v_mul_f32_e32 v4, 0xbfb8aa3b, v4
	v_add_f32_e32 v2, v15, v2
	v_mul_f32_e32 v2, 0xbfb8aa3b, v2
	v_exp_f32_e32 v4, v4
	v_exp_f32_e32 v2, v2
	v_add_f32_e32 v4, 1.0, v4
	v_add_f32_e32 v2, 1.0, v2
	v_rcp_f32_e32 v4, v4
	v_rcp_f32_e32 v2, v2
	v_cvt_pk_bf16_f32 v4, v4, s0
	v_cvt_pk_bf16_f32 v2, v2, s0
	global_store_short v[0:1], v4, off
	global_store_short v[0:1], v2, off offset:64
	s_branch .LBB0_355
